# all 9 GEMM K-loops: 8-phase (16 MFMA per barrier pair) merged to 4-phase (32 MFMA per barrier pair), lgkmcnt(0)+vmcnt(8) before each barrier
# speedup vs baseline: 1.0142x; 1.0103x over previous
.LBB0_274:
	ds_read_b128 v[128:131], v211
	ds_read_b128 v[132:135], v211 offset:1024
	ds_read_b128 v[136:139], v211 offset:2048
	ds_read_b128 v[140:143], v211 offset:3072
	s_add_u32 s4, s2, 0xfffc0080
	s_addc_u32 s5, s3, -1
	s_cmp_eq_u32 s69, 12
	s_cselect_b32 s7, s11, s5
	s_cselect_b32 s6, s15, s4
	s_cselect_b32 s5, s36, s39
	s_cselect_b32 s4, s37, s38
	v_lshl_add_u64 v[200:201], s[2:3], 0, v[162:163]
	s_add_i32 m0, s44, 0xc000
	ds_read_b128 v[168:171], v212
	ds_read_b128 v[172:175], v212 offset:1024
	ds_read_b128 v[176:179], v212 offset:2048
	ds_read_b128 v[180:183], v212 offset:3072
	ds_read_b128 v[184:187], v212 offset:4096
	ds_read_b128 v[188:191], v212 offset:5120
	ds_read_b128 v[192:195], v212 offset:6144
	ds_read_b128 v[196:199], v212 offset:7168
	global_load_lds_dwordx4 v[200:201], off
	v_lshl_add_u64 v[200:201], s[2:3], 0, v[164:165]
	s_add_i32 m0, s44, 0xe000
	s_nop 0
	global_load_lds_dwordx4 v[200:201], off
	ds_read_b128 v[222:225], v213
	ds_read_b128 v[226:229], v213 offset:1024
	ds_read_b128 v[230:233], v213 offset:2048
	ds_read_b128 v[234:237], v213 offset:3072
	s_waitcnt lgkmcnt(0)
	s_waitcnt vmcnt(8)
	s_barrier
	s_setprio 1
	v_mfma_f32_16x16x32_bf16 v[124:127], v[128:131], v[168:171], v[124:127]
	v_mfma_f32_16x16x32_bf16 v[120:123], v[136:139], v[168:171], v[120:123]
	v_mfma_f32_16x16x32_bf16 v[108:111], v[128:131], v[176:179], v[108:111]
	v_mfma_f32_16x16x32_bf16 v[104:107], v[136:139], v[176:179], v[104:107]
	v_mfma_f32_16x16x32_bf16 v[92:95], v[128:131], v[184:187], v[92:95]
	v_mfma_f32_16x16x32_bf16 v[88:91], v[136:139], v[184:187], v[88:91]
	v_mfma_f32_16x16x32_bf16 v[76:79], v[128:131], v[192:195], v[76:79]
	v_mfma_f32_16x16x32_bf16 v[72:75], v[136:139], v[192:195], v[72:75]
	v_mfma_f32_16x16x32_bf16 v[124:127], v[132:135], v[172:175], v[124:127]
	v_mfma_f32_16x16x32_bf16 v[120:123], v[140:143], v[172:175], v[120:123]
	v_mfma_f32_16x16x32_bf16 v[108:111], v[132:135], v[180:183], v[108:111]
	v_mfma_f32_16x16x32_bf16 v[104:107], v[140:143], v[180:183], v[104:107]
	v_mfma_f32_16x16x32_bf16 v[92:95], v[132:135], v[188:191], v[92:95]
	v_mfma_f32_16x16x32_bf16 v[88:91], v[140:143], v[188:191], v[88:91]
	v_mfma_f32_16x16x32_bf16 v[76:79], v[132:135], v[196:199], v[76:79]
	v_mfma_f32_16x16x32_bf16 v[72:75], v[140:143], v[196:199], v[72:75]
	v_mfma_f32_16x16x32_bf16 v[116:119], v[222:225], v[168:171], v[116:119]
	v_mfma_f32_16x16x32_bf16 v[112:115], v[230:233], v[168:171], v[112:115]
	v_mfma_f32_16x16x32_bf16 v[100:103], v[222:225], v[176:179], v[100:103]
	v_mfma_f32_16x16x32_bf16 v[96:99], v[230:233], v[176:179], v[96:99]
	v_mfma_f32_16x16x32_bf16 v[84:87], v[222:225], v[184:187], v[84:87]
	v_mfma_f32_16x16x32_bf16 v[80:83], v[230:233], v[184:187], v[80:83]
	v_mfma_f32_16x16x32_bf16 v[68:71], v[222:225], v[192:195], v[68:71]
	v_mfma_f32_16x16x32_bf16 v[64:67], v[230:233], v[192:195], v[64:67]
	v_mfma_f32_16x16x32_bf16 v[116:119], v[226:229], v[172:175], v[116:119]
	v_mfma_f32_16x16x32_bf16 v[112:115], v[234:237], v[172:175], v[112:115]
	v_mfma_f32_16x16x32_bf16 v[100:103], v[226:229], v[180:183], v[100:103]
	v_mfma_f32_16x16x32_bf16 v[96:99], v[234:237], v[180:183], v[96:99]
	v_mfma_f32_16x16x32_bf16 v[84:87], v[226:229], v[188:191], v[84:87]
	v_mfma_f32_16x16x32_bf16 v[80:83], v[234:237], v[188:191], v[80:83]
	v_mfma_f32_16x16x32_bf16 v[68:71], v[226:229], v[196:199], v[68:71]
	v_mfma_f32_16x16x32_bf16 v[64:67], v[234:237], v[196:199], v[64:67]
	s_setprio 0
	s_barrier
	ds_read_b128 v[168:171], v212 offset:16384
	ds_read_b128 v[172:175], v212 offset:17408
	ds_read_b128 v[176:179], v212 offset:18432
	ds_read_b128 v[180:183], v212 offset:19456
	ds_read_b128 v[184:187], v212 offset:20480
	ds_read_b128 v[188:191], v212 offset:21504
	ds_read_b128 v[192:195], v212 offset:22528
	ds_read_b128 v[196:199], v212 offset:23552
	s_mov_b32 m0, s42
	v_lshl_add_u64 v[200:201], s[4:5], 0, v[144:145]
	global_load_lds_dwordx4 v[200:201], off
	v_lshl_add_u64 v[238:239], s[4:5], 0, v[146:147]
	s_mov_b32 m0, s43
	s_nop 0
	global_load_lds_dwordx4 v[238:239], off
	s_mov_b32 m0, s44
	v_lshl_add_u64 v[240:241], s[6:7], 0, v[144:145]
	global_load_lds_dwordx4 v[240:241], off
	v_lshl_add_u64 v[242:243], s[6:7], 0, v[146:147]
	s_mov_b32 m0, s45
	s_nop 0
	global_load_lds_dwordx4 v[242:243], off
	s_add_u32 s70, s4, 0x40000
	s_addc_u32 s71, s5, 0
	s_mov_b32 m0, s46
	v_lshl_add_u64 v[248:249], s[70:71], 0, v[144:145]
	global_load_lds_dwordx4 v[248:249], off
	v_lshl_add_u64 v[248:249], s[70:71], 0, v[146:147]
	s_mov_b32 m0, s47
	s_nop 0
	global_load_lds_dwordx4 v[248:249], off
	s_waitcnt lgkmcnt(0)
	s_waitcnt vmcnt(8)
	s_barrier
	s_setprio 1
	v_mfma_f32_16x16x32_bf16 v[60:63], v[128:131], v[168:171], v[60:63]
	v_mfma_f32_16x16x32_bf16 v[56:59], v[136:139], v[168:171], v[56:59]
	v_mfma_f32_16x16x32_bf16 v[44:47], v[128:131], v[176:179], v[44:47]
	v_mfma_f32_16x16x32_bf16 v[40:43], v[136:139], v[176:179], v[40:43]
	v_mfma_f32_16x16x32_bf16 v[28:31], v[128:131], v[184:187], v[28:31]
	v_mfma_f32_16x16x32_bf16 v[24:27], v[136:139], v[184:187], v[24:27]
	v_mfma_f32_16x16x32_bf16 v[12:15], v[128:131], v[192:195], v[12:15]
	v_mfma_f32_16x16x32_bf16 v[8:11], v[136:139], v[192:195], v[8:11]
	v_mfma_f32_16x16x32_bf16 v[60:63], v[132:135], v[172:175], v[60:63]
	v_mfma_f32_16x16x32_bf16 v[56:59], v[140:143], v[172:175], v[56:59]
	v_mfma_f32_16x16x32_bf16 v[44:47], v[132:135], v[180:183], v[44:47]
	v_mfma_f32_16x16x32_bf16 v[40:43], v[140:143], v[180:183], v[40:43]
	v_mfma_f32_16x16x32_bf16 v[28:31], v[132:135], v[188:191], v[28:31]
	v_mfma_f32_16x16x32_bf16 v[24:27], v[140:143], v[188:191], v[24:27]
	v_mfma_f32_16x16x32_bf16 v[12:15], v[132:135], v[196:199], v[12:15]
	v_mfma_f32_16x16x32_bf16 v[8:11], v[140:143], v[196:199], v[8:11]
	v_mfma_f32_16x16x32_bf16 v[52:55], v[222:225], v[168:171], v[52:55]
	v_mfma_f32_16x16x32_bf16 v[48:51], v[230:233], v[168:171], v[48:51]
	v_mfma_f32_16x16x32_bf16 v[36:39], v[222:225], v[176:179], v[36:39]
	v_mfma_f32_16x16x32_bf16 v[32:35], v[230:233], v[176:179], v[32:35]
	v_mfma_f32_16x16x32_bf16 v[20:23], v[222:225], v[184:187], v[20:23]
	v_mfma_f32_16x16x32_bf16 v[16:19], v[230:233], v[184:187], v[16:19]
	v_mfma_f32_16x16x32_bf16 v[4:7], v[222:225], v[192:195], v[4:7]
	v_mfma_f32_16x16x32_bf16 v[0:3], v[230:233], v[192:195], v[0:3]
	v_mfma_f32_16x16x32_bf16 v[52:55], v[226:229], v[172:175], v[52:55]
	v_mfma_f32_16x16x32_bf16 v[48:51], v[234:237], v[172:175], v[48:51]
	v_mfma_f32_16x16x32_bf16 v[36:39], v[226:229], v[180:183], v[36:39]
	v_mfma_f32_16x16x32_bf16 v[32:35], v[234:237], v[180:183], v[32:35]
	v_mfma_f32_16x16x32_bf16 v[20:23], v[226:229], v[188:191], v[20:23]
	v_mfma_f32_16x16x32_bf16 v[16:19], v[234:237], v[188:191], v[16:19]
	v_mfma_f32_16x16x32_bf16 v[4:7], v[226:229], v[196:199], v[4:7]
	v_mfma_f32_16x16x32_bf16 v[0:3], v[234:237], v[196:199], v[0:3]
	s_setprio 0
	s_barrier
	ds_read_b128 v[128:131], v214
	ds_read_b128 v[132:135], v214 offset:1024
	ds_read_b128 v[136:139], v214 offset:2048
	ds_read_b128 v[140:143], v214 offset:3072
	s_add_u32 s6, s6, 0x40000
	s_addc_u32 s7, s7, 0
	s_mov_b32 m0, s48
	v_lshl_add_u64 v[222:223], s[6:7], 0, v[144:145]
	ds_read_b128 v[168:171], v212 offset:32768
	ds_read_b128 v[172:175], v212 offset:33792
	ds_read_b128 v[176:179], v212 offset:34816
	ds_read_b128 v[180:183], v212 offset:35840
	ds_read_b128 v[184:187], v212 offset:36864
	ds_read_b128 v[188:191], v212 offset:37888
	ds_read_b128 v[192:195], v212 offset:38912
	ds_read_b128 v[196:199], v212 offset:39936
	global_load_lds_dwordx4 v[222:223], off
	v_lshl_add_u64 v[222:223], s[6:7], 0, v[146:147]
	s_mov_b32 m0, s49
	s_nop 0
	global_load_lds_dwordx4 v[222:223], off
	ds_read_b128 v[222:225], v215
	ds_read_b128 v[226:229], v215 offset:1024
	ds_read_b128 v[230:233], v215 offset:2048
	ds_read_b128 v[234:237], v215 offset:3072
	s_waitcnt lgkmcnt(0)
	s_waitcnt vmcnt(8)
	s_barrier
	s_setprio 1
	v_mfma_f32_16x16x32_bf16 v[124:127], v[128:131], v[168:171], v[124:127]
	v_mfma_f32_16x16x32_bf16 v[120:123], v[136:139], v[168:171], v[120:123]
	v_mfma_f32_16x16x32_bf16 v[108:111], v[128:131], v[176:179], v[108:111]
	v_mfma_f32_16x16x32_bf16 v[104:107], v[136:139], v[176:179], v[104:107]
	v_mfma_f32_16x16x32_bf16 v[92:95], v[128:131], v[184:187], v[92:95]
	v_mfma_f32_16x16x32_bf16 v[88:91], v[136:139], v[184:187], v[88:91]
	v_mfma_f32_16x16x32_bf16 v[76:79], v[128:131], v[192:195], v[76:79]
	v_mfma_f32_16x16x32_bf16 v[72:75], v[136:139], v[192:195], v[72:75]
	v_mfma_f32_16x16x32_bf16 v[124:127], v[132:135], v[172:175], v[124:127]
	v_mfma_f32_16x16x32_bf16 v[120:123], v[140:143], v[172:175], v[120:123]
	v_mfma_f32_16x16x32_bf16 v[108:111], v[132:135], v[180:183], v[108:111]
	v_mfma_f32_16x16x32_bf16 v[104:107], v[140:143], v[180:183], v[104:107]
	v_mfma_f32_16x16x32_bf16 v[92:95], v[132:135], v[188:191], v[92:95]
	v_mfma_f32_16x16x32_bf16 v[88:91], v[140:143], v[188:191], v[88:91]
	v_mfma_f32_16x16x32_bf16 v[76:79], v[132:135], v[196:199], v[76:79]
	v_mfma_f32_16x16x32_bf16 v[72:75], v[140:143], v[196:199], v[72:75]
	v_mfma_f32_16x16x32_bf16 v[116:119], v[222:225], v[168:171], v[116:119]
	v_mfma_f32_16x16x32_bf16 v[112:115], v[230:233], v[168:171], v[112:115]
	v_mfma_f32_16x16x32_bf16 v[100:103], v[222:225], v[176:179], v[100:103]
	v_mfma_f32_16x16x32_bf16 v[96:99], v[230:233], v[176:179], v[96:99]
	v_mfma_f32_16x16x32_bf16 v[84:87], v[222:225], v[184:187], v[84:87]
	v_mfma_f32_16x16x32_bf16 v[80:83], v[230:233], v[184:187], v[80:83]
	v_mfma_f32_16x16x32_bf16 v[68:71], v[222:225], v[192:195], v[68:71]
	v_mfma_f32_16x16x32_bf16 v[64:67], v[230:233], v[192:195], v[64:67]
	v_mfma_f32_16x16x32_bf16 v[116:119], v[226:229], v[172:175], v[116:119]
	v_mfma_f32_16x16x32_bf16 v[112:115], v[234:237], v[172:175], v[112:115]
	v_mfma_f32_16x16x32_bf16 v[100:103], v[226:229], v[180:183], v[100:103]
	v_mfma_f32_16x16x32_bf16 v[96:99], v[234:237], v[180:183], v[96:99]
	v_mfma_f32_16x16x32_bf16 v[84:87], v[226:229], v[188:191], v[84:87]
	v_mfma_f32_16x16x32_bf16 v[80:83], v[234:237], v[188:191], v[80:83]
	v_mfma_f32_16x16x32_bf16 v[68:71], v[226:229], v[196:199], v[68:71]
	v_mfma_f32_16x16x32_bf16 v[64:67], v[234:237], v[196:199], v[64:67]
	s_setprio 0
	s_barrier
	ds_read_b128 v[168:171], v212 offset:49152
	ds_read_b128 v[172:175], v212 offset:50176
	ds_read_b128 v[176:179], v212 offset:51200
	ds_read_b128 v[180:183], v212 offset:52224
	ds_read_b128 v[184:187], v212 offset:53248
	ds_read_b128 v[188:191], v212 offset:54272
	ds_read_b128 v[192:195], v212 offset:55296
	ds_read_b128 v[196:199], v212 offset:56320
	s_mov_b32 m0, s51
	v_lshl_add_u64 v[200:201], v[200:201], 0, s[18:19]
	global_load_lds_dwordx4 v[200:201], off
	v_lshl_add_u64 v[200:201], v[238:239], 0, s[18:19]
	s_mov_b32 m0, s52
	s_nop 0
	global_load_lds_dwordx4 v[200:201], off
	s_mov_b32 m0, s54
	v_lshl_add_u64 v[200:201], v[240:241], 0, s[18:19]
	global_load_lds_dwordx4 v[200:201], off
	v_lshl_add_u64 v[200:201], v[242:243], 0, s[18:19]
	s_mov_b32 m0, s55
	s_nop 0
	global_load_lds_dwordx4 v[200:201], off
	s_add_u32 s4, s4, 0x40080
	s_addc_u32 s5, s5, 0
	s_mov_b32 m0, s56
	v_lshl_add_u64 v[248:249], s[4:5], 0, v[144:145]
	global_load_lds_dwordx4 v[248:249], off
	v_lshl_add_u64 v[248:249], s[4:5], 0, v[146:147]
	s_mov_b32 m0, s57
	s_nop 0
	global_load_lds_dwordx4 v[248:249], off
	s_waitcnt lgkmcnt(0)
	s_waitcnt vmcnt(8)
	s_barrier
	s_setprio 1
	v_mfma_f32_16x16x32_bf16 v[60:63], v[128:131], v[168:171], v[60:63]
	v_mfma_f32_16x16x32_bf16 v[56:59], v[136:139], v[168:171], v[56:59]
	v_mfma_f32_16x16x32_bf16 v[44:47], v[128:131], v[176:179], v[44:47]
	v_mfma_f32_16x16x32_bf16 v[40:43], v[136:139], v[176:179], v[40:43]
	v_mfma_f32_16x16x32_bf16 v[28:31], v[128:131], v[184:187], v[28:31]
	v_mfma_f32_16x16x32_bf16 v[24:27], v[136:139], v[184:187], v[24:27]
	v_mfma_f32_16x16x32_bf16 v[12:15], v[128:131], v[192:195], v[12:15]
	v_mfma_f32_16x16x32_bf16 v[8:11], v[136:139], v[192:195], v[8:11]
	v_mfma_f32_16x16x32_bf16 v[60:63], v[132:135], v[172:175], v[60:63]
	v_mfma_f32_16x16x32_bf16 v[56:59], v[140:143], v[172:175], v[56:59]
	v_mfma_f32_16x16x32_bf16 v[44:47], v[132:135], v[180:183], v[44:47]
	v_mfma_f32_16x16x32_bf16 v[40:43], v[140:143], v[180:183], v[40:43]
	v_mfma_f32_16x16x32_bf16 v[28:31], v[132:135], v[188:191], v[28:31]
	v_mfma_f32_16x16x32_bf16 v[24:27], v[140:143], v[188:191], v[24:27]
	v_mfma_f32_16x16x32_bf16 v[12:15], v[132:135], v[196:199], v[12:15]
	v_mfma_f32_16x16x32_bf16 v[8:11], v[140:143], v[196:199], v[8:11]
	v_mfma_f32_16x16x32_bf16 v[52:55], v[222:225], v[168:171], v[52:55]
	v_mfma_f32_16x16x32_bf16 v[48:51], v[230:233], v[168:171], v[48:51]
	v_mfma_f32_16x16x32_bf16 v[36:39], v[222:225], v[176:179], v[36:39]
	v_mfma_f32_16x16x32_bf16 v[32:35], v[230:233], v[176:179], v[32:35]
	v_mfma_f32_16x16x32_bf16 v[20:23], v[222:225], v[184:187], v[20:23]
	v_mfma_f32_16x16x32_bf16 v[16:19], v[230:233], v[184:187], v[16:19]
	v_mfma_f32_16x16x32_bf16 v[4:7], v[222:225], v[192:195], v[4:7]
	v_mfma_f32_16x16x32_bf16 v[0:3], v[230:233], v[192:195], v[0:3]
	v_mfma_f32_16x16x32_bf16 v[52:55], v[226:229], v[172:175], v[52:55]
	v_mfma_f32_16x16x32_bf16 v[48:51], v[234:237], v[172:175], v[48:51]
	v_mfma_f32_16x16x32_bf16 v[36:39], v[226:229], v[180:183], v[36:39]
	v_mfma_f32_16x16x32_bf16 v[32:35], v[234:237], v[180:183], v[32:35]
	v_mfma_f32_16x16x32_bf16 v[20:23], v[226:229], v[188:191], v[20:23]
	v_mfma_f32_16x16x32_bf16 v[16:19], v[234:237], v[188:191], v[16:19]
	v_mfma_f32_16x16x32_bf16 v[4:7], v[226:229], v[196:199], v[4:7]
	v_mfma_f32_16x16x32_bf16 v[0:3], v[234:237], v[196:199], v[0:3]
	s_setprio 0
	s_add_i32 s69, s69, 2
	s_add_u32 s2, s2, 0x100
	s_addc_u32 s3, s3, 0
	s_add_u32 s38, s38, 0x100
	s_addc_u32 s39, s39, 0
	s_cmp_gt_u32 s69, 13
	s_barrier
	s_cbranch_scc0 .LBB0_274
	s_lshl_b32 s11, s67, 8
	s_cmp_eq_u32 s68, 0
	s_mov_b32 s2, 0x6200000
	s_cselect_b32 s2, s2, 0x6221000
	s_add_u32 s2, s22, s2
	v_add_u32_e32 v176, s11, v204
	s_addc_u32 s3, s23, 0
	v_ashrrev_i32_e32 v177, 31, v176
	v_add_u32_e32 v198, s11, v205
	v_add_u32_e32 v196, s11, v206
	v_add_u32_e32 v194, s11, v207
	v_add_u32_e32 v192, 0x80, v176
	v_add_u32_e32 v190, 0x90, v176
	v_add_u32_e32 v188, 0xa0, v176
	v_add_u32_e32 v186, 0xb0, v176
	v_lshl_add_u64 v[128:129], v[176:177], 2, s[2:3]
	v_ashrrev_i32_e32 v199, 31, v198
	v_ashrrev_i32_e32 v197, 31, v196
	v_ashrrev_i32_e32 v195, 31, v194
	v_ashrrev_i32_e32 v193, 31, v192
	v_ashrrev_i32_e32 v191, 31, v190
	v_ashrrev_i32_e32 v189, 31, v188
	v_ashrrev_i32_e32 v187, 31, v186
	v_lshl_add_u64 v[130:131], v[198:199], 2, s[2:3]
	v_lshl_add_u64 v[132:133], v[196:197], 2, s[2:3]
	v_lshl_add_u64 v[134:135], v[194:195], 2, s[2:3]
	v_lshl_add_u64 v[136:137], v[192:193], 2, s[2:3]
	v_lshl_add_u64 v[138:139], v[190:191], 2, s[2:3]
	v_lshl_add_u64 v[140:141], v[188:189], 2, s[2:3]
	v_lshl_add_u64 v[142:143], v[186:187], 2, s[2:3]
	global_load_dword v184, v[128:129], off
	global_load_dword v182, v[130:131], off
	global_load_dword v180, v[132:133], off
	global_load_dword v178, v[134:135], off
	global_load_dword v174, v[136:137], off
	global_load_dword v172, v[138:139], off
	global_load_dword v170, v[140:141], off
	global_load_dword v168, v[142:143], off
	s_cmp_lt_i32 s33, 2
	s_cselect_b64 s[38:39], -1, 0
	s_cmp_gt_i32 s33, 1
	s_cselect_b64 s[2:3], -1, 0
	v_cndmask_b32_e64 v128, 0, 1, s[2:3]
	s_cmp_lg_u32 s68, 0
	s_mov_b64 s[6:7], -1
	v_cmp_ne_u32_e64 s[4:5], 1, v128
	s_cbranch_scc0 .LBB0_293
	s_lshl_b32 s6, s33, 8
	s_and_b32 s6, s6, 0x100
	v_or_b32_e32 v169, s6, v210
	s_and_b64 s[6:7], s[38:39], exec
	s_mov_b32 s6, 0x8600000
	s_cselect_b32 s6, s6, 0x8a00000
	s_add_u32 s6, s20, s6
	v_lshlrev_b32_e32 v148, 1, v169
	s_addc_u32 s7, s21, 0
	v_lshlrev_b64 v[222:223], 11, v[176:177]
	v_lshl_add_u64 v[200:201], s[26:27], 0, v[148:149]
	v_lshl_add_u64 v[222:223], s[6:7], 0, v[222:223]
	v_lshlrev_b32_e32 v148, 2, v169
	s_waitcnt vmcnt(0)
	v_pk_mul_f32 v[130:131], v[126:127], v[184:185] op_sel_hi:[1,0]
	v_pk_mul_f32 v[128:129], v[124:125], v[184:185] op_sel_hi:[1,0]
	v_pk_mul_f32 v[134:135], v[122:123], v[184:185] op_sel_hi:[1,0]
	v_pk_mul_f32 v[132:133], v[120:121], v[184:185] op_sel_hi:[1,0]
	v_pk_mul_f32 v[138:139], v[118:119], v[184:185] op_sel_hi:[1,0]
	v_pk_mul_f32 v[136:137], v[116:117], v[184:185] op_sel_hi:[1,0]
	v_pk_mul_f32 v[142:143], v[114:115], v[184:185] op_sel_hi:[1,0]
	v_pk_mul_f32 v[140:141], v[112:113], v[184:185] op_sel_hi:[1,0]
	v_lshl_add_u64 v[222:223], v[222:223], 0, v[148:149]
	s_and_b64 vcc, exec, s[4:5]
	global_store_dwordx4 v[222:223], v[128:131], off
	global_store_dwordx4 v[222:223], v[132:135], off offset:16
	global_store_dwordx4 v[222:223], v[136:139], off offset:128
	global_store_dwordx4 v[222:223], v[140:143], off offset:144
	s_cbranch_vccnz .LBB0_278
	v_lshlrev_b64 v[222:223], 9, v[176:177]
	v_lshl_add_u64 v[222:223], v[222:223], 1, v[200:201]
	v_cvt_pk_bf16_f32 v128, v128, v129
	v_cvt_pk_bf16_f32 v129, v130, v131
	v_cvt_pk_bf16_f32 v130, v132, v133
	v_cvt_pk_bf16_f32 v131, v134, v135
	global_store_dwordx4 v[222:223], v[128:131], off nt
	s_nop 1
	v_cvt_pk_bf16_f32 v128, v136, v137
	v_cvt_pk_bf16_f32 v129, v138, v139
	v_cvt_pk_bf16_f32 v130, v140, v141
	v_cvt_pk_bf16_f32 v131, v142, v143
	global_store_dwordx4 v[222:223], v[128:131], off offset:64 nt

.LBB0_643:
	s_add_u32 s14, s10, s12
	ds_read_b128 v[144:147], v138
	ds_read_b128 v[148:151], v138 offset:1024
	ds_read_b128 v[152:155], v138 offset:2048
	ds_read_b128 v[156:159], v138 offset:3072
	s_addc_u32 s15, s11, s13
	s_add_u32 s14, s14, 0x159a4100
	s_addc_u32 s15, s15, 0
	s_add_u32 s47, s42, s12
	s_addc_u32 s48, s43, s13
	s_cmpk_eq_i32 s12, 0x700
	s_cselect_b32 s17, s5, s15
	s_cselect_b32 s16, s4, s14
	s_cselect_b32 s15, s7, s48
	s_cselect_b32 s14, s6, s47
	s_mov_b32 m0, s45
	v_lshl_add_u64 v[192:193], v[132:133], 0, s[12:13]
	ds_read_b128 v[160:163], v139
	ds_read_b128 v[164:167], v139 offset:1024
	ds_read_b128 v[168:171], v139 offset:2048
	ds_read_b128 v[172:175], v139 offset:3072
	ds_read_b128 v[176:179], v139 offset:4096
	ds_read_b128 v[180:183], v139 offset:5120
	ds_read_b128 v[184:187], v139 offset:6144
	ds_read_b128 v[188:191], v139 offset:7168
	global_load_lds_dwordx4 v[192:193], off
	v_lshl_add_u64 v[192:193], v[134:135], 0, s[12:13]
	s_mov_b32 m0, s46
	s_nop 0
	global_load_lds_dwordx4 v[192:193], off
	ds_read_b128 v[192:195], v140
	ds_read_b128 v[196:199], v140 offset:1024
	ds_read_b128 v[204:207], v140 offset:2048
	ds_read_b128 v[208:211], v140 offset:3072
	s_waitcnt lgkmcnt(0)
	s_waitcnt vmcnt(8)
	s_barrier
	s_setprio 1
	v_mfma_f32_16x16x32_bf16 v[124:127], v[144:147], v[160:163], v[124:127]
	v_mfma_f32_16x16x32_bf16 v[120:123], v[152:155], v[160:163], v[120:123]
	v_mfma_f32_16x16x32_bf16 v[108:111], v[144:147], v[168:171], v[108:111]
	v_mfma_f32_16x16x32_bf16 v[104:107], v[152:155], v[168:171], v[104:107]
	v_mfma_f32_16x16x32_bf16 v[92:95], v[144:147], v[176:179], v[92:95]
	v_mfma_f32_16x16x32_bf16 v[88:91], v[152:155], v[176:179], v[88:91]
	v_mfma_f32_16x16x32_bf16 v[76:79], v[144:147], v[184:187], v[76:79]
	v_mfma_f32_16x16x32_bf16 v[72:75], v[152:155], v[184:187], v[72:75]
	v_mfma_f32_16x16x32_bf16 v[124:127], v[148:151], v[164:167], v[124:127]
	v_mfma_f32_16x16x32_bf16 v[120:123], v[156:159], v[164:167], v[120:123]
	v_mfma_f32_16x16x32_bf16 v[108:111], v[148:151], v[172:175], v[108:111]
	v_mfma_f32_16x16x32_bf16 v[104:107], v[156:159], v[172:175], v[104:107]
	v_mfma_f32_16x16x32_bf16 v[92:95], v[148:151], v[180:183], v[92:95]
	v_mfma_f32_16x16x32_bf16 v[88:91], v[156:159], v[180:183], v[88:91]
	v_mfma_f32_16x16x32_bf16 v[76:79], v[148:151], v[188:191], v[76:79]
	v_mfma_f32_16x16x32_bf16 v[72:75], v[156:159], v[188:191], v[72:75]
	v_mfma_f32_16x16x32_bf16 v[116:119], v[192:195], v[160:163], v[116:119]
	v_mfma_f32_16x16x32_bf16 v[112:115], v[204:207], v[160:163], v[112:115]
	v_mfma_f32_16x16x32_bf16 v[100:103], v[192:195], v[168:171], v[100:103]
	v_mfma_f32_16x16x32_bf16 v[96:99], v[204:207], v[168:171], v[96:99]
	v_mfma_f32_16x16x32_bf16 v[84:87], v[192:195], v[176:179], v[84:87]
	v_mfma_f32_16x16x32_bf16 v[80:83], v[204:207], v[176:179], v[80:83]
	v_mfma_f32_16x16x32_bf16 v[68:71], v[192:195], v[184:187], v[68:71]
	v_mfma_f32_16x16x32_bf16 v[64:67], v[204:207], v[184:187], v[64:67]
	v_mfma_f32_16x16x32_bf16 v[116:119], v[196:199], v[164:167], v[116:119]
	v_mfma_f32_16x16x32_bf16 v[112:115], v[208:211], v[164:167], v[112:115]
	v_mfma_f32_16x16x32_bf16 v[100:103], v[196:199], v[172:175], v[100:103]
	v_mfma_f32_16x16x32_bf16 v[96:99], v[208:211], v[172:175], v[96:99]
	v_mfma_f32_16x16x32_bf16 v[84:87], v[196:199], v[180:183], v[84:87]
	v_mfma_f32_16x16x32_bf16 v[80:83], v[208:211], v[180:183], v[80:83]
	v_mfma_f32_16x16x32_bf16 v[68:71], v[196:199], v[188:191], v[68:71]
	v_mfma_f32_16x16x32_bf16 v[64:67], v[208:211], v[188:191], v[64:67]
	s_setprio 0
	s_barrier
	ds_read_b128 v[160:163], v139 offset:16384
	ds_read_b128 v[164:167], v139 offset:17408
	ds_read_b128 v[168:171], v139 offset:18432
	ds_read_b128 v[172:175], v139 offset:19456
	ds_read_b128 v[176:179], v139 offset:20480
	ds_read_b128 v[180:183], v139 offset:21504
	ds_read_b128 v[184:187], v139 offset:22528
	ds_read_b128 v[188:191], v139 offset:23552
	s_mov_b32 m0, s1
	v_lshl_add_u64 v[200:201], s[14:15], 0, v[130:131]
	global_load_lds_dwordx4 v[200:201], off
	v_lshl_add_u64 v[212:213], s[14:15], 0, v[128:129]
	s_mov_b32 m0, s28
	s_nop 0
	global_load_lds_dwordx4 v[212:213], off
	s_mov_b32 m0, s29
	v_lshl_add_u64 v[214:215], s[16:17], 0, v[130:131]
	global_load_lds_dwordx4 v[214:215], off
	v_lshl_add_u64 v[216:217], s[16:17], 0, v[128:129]
	s_mov_b32 m0, s30
	s_nop 0
	global_load_lds_dwordx4 v[216:217], off
	s_add_u32 s48, s14, 0x40000
	s_addc_u32 s49, s15, 0
	s_mov_b32 m0, s31
	v_lshl_add_u64 v[248:249], s[48:49], 0, v[130:131]
	global_load_lds_dwordx4 v[248:249], off
	v_lshl_add_u64 v[248:249], s[48:49], 0, v[128:129]
	s_mov_b32 m0, s33
	s_nop 0
	global_load_lds_dwordx4 v[248:249], off
	s_waitcnt lgkmcnt(0)
	s_waitcnt vmcnt(8)
	s_barrier
	s_setprio 1
	v_mfma_f32_16x16x32_bf16 v[60:63], v[144:147], v[160:163], v[60:63]
	v_mfma_f32_16x16x32_bf16 v[56:59], v[152:155], v[160:163], v[56:59]
	v_mfma_f32_16x16x32_bf16 v[44:47], v[144:147], v[168:171], v[44:47]
	v_mfma_f32_16x16x32_bf16 v[40:43], v[152:155], v[168:171], v[40:43]
	v_mfma_f32_16x16x32_bf16 v[28:31], v[144:147], v[176:179], v[28:31]
	v_mfma_f32_16x16x32_bf16 v[24:27], v[152:155], v[176:179], v[24:27]
	v_mfma_f32_16x16x32_bf16 v[12:15], v[144:147], v[184:187], v[12:15]
	v_mfma_f32_16x16x32_bf16 v[8:11], v[152:155], v[184:187], v[8:11]
	v_mfma_f32_16x16x32_bf16 v[60:63], v[148:151], v[164:167], v[60:63]
	v_mfma_f32_16x16x32_bf16 v[56:59], v[156:159], v[164:167], v[56:59]
	v_mfma_f32_16x16x32_bf16 v[44:47], v[148:151], v[172:175], v[44:47]
	v_mfma_f32_16x16x32_bf16 v[40:43], v[156:159], v[172:175], v[40:43]
	v_mfma_f32_16x16x32_bf16 v[28:31], v[148:151], v[180:183], v[28:31]
	v_mfma_f32_16x16x32_bf16 v[24:27], v[156:159], v[180:183], v[24:27]
	v_mfma_f32_16x16x32_bf16 v[12:15], v[148:151], v[188:191], v[12:15]
	v_mfma_f32_16x16x32_bf16 v[8:11], v[156:159], v[188:191], v[8:11]
	v_mfma_f32_16x16x32_bf16 v[52:55], v[192:195], v[160:163], v[52:55]
	v_mfma_f32_16x16x32_bf16 v[48:51], v[204:207], v[160:163], v[48:51]
	v_mfma_f32_16x16x32_bf16 v[36:39], v[192:195], v[168:171], v[36:39]
	v_mfma_f32_16x16x32_bf16 v[32:35], v[204:207], v[168:171], v[32:35]
	v_mfma_f32_16x16x32_bf16 v[20:23], v[192:195], v[176:179], v[20:23]
	v_mfma_f32_16x16x32_bf16 v[16:19], v[204:207], v[176:179], v[16:19]
	v_mfma_f32_16x16x32_bf16 v[4:7], v[192:195], v[184:187], v[4:7]
	v_mfma_f32_16x16x32_bf16 v[0:3], v[204:207], v[184:187], v[0:3]
	v_mfma_f32_16x16x32_bf16 v[52:55], v[196:199], v[164:167], v[52:55]
	v_mfma_f32_16x16x32_bf16 v[48:51], v[208:211], v[164:167], v[48:51]
	v_mfma_f32_16x16x32_bf16 v[36:39], v[196:199], v[172:175], v[36:39]
	v_mfma_f32_16x16x32_bf16 v[32:35], v[208:211], v[172:175], v[32:35]
	v_mfma_f32_16x16x32_bf16 v[20:23], v[196:199], v[180:183], v[20:23]
	v_mfma_f32_16x16x32_bf16 v[16:19], v[208:211], v[180:183], v[16:19]
	v_mfma_f32_16x16x32_bf16 v[4:7], v[196:199], v[188:191], v[4:7]
	v_mfma_f32_16x16x32_bf16 v[0:3], v[208:211], v[188:191], v[0:3]
	s_setprio 0
	s_barrier
	ds_read_b128 v[144:147], v141
	ds_read_b128 v[148:151], v141 offset:1024
	ds_read_b128 v[152:155], v141 offset:2048
	ds_read_b128 v[156:159], v141 offset:3072
	s_add_u32 s16, s16, 0x40000
	s_addc_u32 s17, s17, 0
	s_mov_b32 m0, s34
	v_lshl_add_u64 v[192:193], s[16:17], 0, v[130:131]
	ds_read_b128 v[160:163], v139 offset:32768
	ds_read_b128 v[164:167], v139 offset:33792
	ds_read_b128 v[168:171], v139 offset:34816
	ds_read_b128 v[172:175], v139 offset:35840
	ds_read_b128 v[176:179], v139 offset:36864
	ds_read_b128 v[180:183], v139 offset:37888
	ds_read_b128 v[184:187], v139 offset:38912
	ds_read_b128 v[188:191], v139 offset:39936
	global_load_lds_dwordx4 v[192:193], off
	v_lshl_add_u64 v[192:193], s[16:17], 0, v[128:129]
	s_mov_b32 m0, s35
	s_nop 0
	global_load_lds_dwordx4 v[192:193], off
	ds_read_b128 v[192:195], v142
	ds_read_b128 v[196:199], v142 offset:1024
	ds_read_b128 v[204:207], v142 offset:2048
	ds_read_b128 v[208:211], v142 offset:3072
	s_waitcnt lgkmcnt(0)
	s_waitcnt vmcnt(8)
	s_barrier
	s_setprio 1
	v_mfma_f32_16x16x32_bf16 v[124:127], v[144:147], v[160:163], v[124:127]
	v_mfma_f32_16x16x32_bf16 v[120:123], v[152:155], v[160:163], v[120:123]
	v_mfma_f32_16x16x32_bf16 v[108:111], v[144:147], v[168:171], v[108:111]
	v_mfma_f32_16x16x32_bf16 v[104:107], v[152:155], v[168:171], v[104:107]
	v_mfma_f32_16x16x32_bf16 v[92:95], v[144:147], v[176:179], v[92:95]
	v_mfma_f32_16x16x32_bf16 v[88:91], v[152:155], v[176:179], v[88:91]
	v_mfma_f32_16x16x32_bf16 v[76:79], v[144:147], v[184:187], v[76:79]
	v_mfma_f32_16x16x32_bf16 v[72:75], v[152:155], v[184:187], v[72:75]
	v_mfma_f32_16x16x32_bf16 v[124:127], v[148:151], v[164:167], v[124:127]
	v_mfma_f32_16x16x32_bf16 v[120:123], v[156:159], v[164:167], v[120:123]
	v_mfma_f32_16x16x32_bf16 v[108:111], v[148:151], v[172:175], v[108:111]
	v_mfma_f32_16x16x32_bf16 v[104:107], v[156:159], v[172:175], v[104:107]
	v_mfma_f32_16x16x32_bf16 v[92:95], v[148:151], v[180:183], v[92:95]
	v_mfma_f32_16x16x32_bf16 v[88:91], v[156:159], v[180:183], v[88:91]
	v_mfma_f32_16x16x32_bf16 v[76:79], v[148:151], v[188:191], v[76:79]
	v_mfma_f32_16x16x32_bf16 v[72:75], v[156:159], v[188:191], v[72:75]
	v_mfma_f32_16x16x32_bf16 v[116:119], v[192:195], v[160:163], v[116:119]
	v_mfma_f32_16x16x32_bf16 v[112:115], v[204:207], v[160:163], v[112:115]
	v_mfma_f32_16x16x32_bf16 v[100:103], v[192:195], v[168:171], v[100:103]
	v_mfma_f32_16x16x32_bf16 v[96:99], v[204:207], v[168:171], v[96:99]
	v_mfma_f32_16x16x32_bf16 v[84:87], v[192:195], v[176:179], v[84:87]
	v_mfma_f32_16x16x32_bf16 v[80:83], v[204:207], v[176:179], v[80:83]
	v_mfma_f32_16x16x32_bf16 v[68:71], v[192:195], v[184:187], v[68:71]
	v_mfma_f32_16x16x32_bf16 v[64:67], v[204:207], v[184:187], v[64:67]
	v_mfma_f32_16x16x32_bf16 v[116:119], v[196:199], v[164:167], v[116:119]
	v_mfma_f32_16x16x32_bf16 v[112:115], v[208:211], v[164:167], v[112:115]
	v_mfma_f32_16x16x32_bf16 v[100:103], v[196:199], v[172:175], v[100:103]
	v_mfma_f32_16x16x32_bf16 v[96:99], v[208:211], v[172:175], v[96:99]
	v_mfma_f32_16x16x32_bf16 v[84:87], v[196:199], v[180:183], v[84:87]
	v_mfma_f32_16x16x32_bf16 v[80:83], v[208:211], v[180:183], v[80:83]
	v_mfma_f32_16x16x32_bf16 v[68:71], v[196:199], v[188:191], v[68:71]
	v_mfma_f32_16x16x32_bf16 v[64:67], v[208:211], v[188:191], v[64:67]
	s_setprio 0
	s_barrier
	ds_read_b128 v[160:163], v139 offset:49152
	ds_read_b128 v[164:167], v139 offset:50176
	ds_read_b128 v[168:171], v139 offset:51200
	ds_read_b128 v[172:175], v139 offset:52224
	ds_read_b128 v[176:179], v139 offset:53248
	ds_read_b128 v[180:183], v139 offset:54272
	ds_read_b128 v[184:187], v139 offset:55296
	ds_read_b128 v[188:191], v139 offset:56320
	s_mov_b32 m0, s36
	v_lshl_add_u64 v[200:201], v[200:201], 0, s[8:9]
	global_load_lds_dwordx4 v[200:201], off
	v_lshl_add_u64 v[200:201], v[212:213], 0, s[8:9]
	s_mov_b32 m0, s37
	s_nop 0
	global_load_lds_dwordx4 v[200:201], off
	s_mov_b32 m0, s38
	v_lshl_add_u64 v[200:201], v[214:215], 0, s[8:9]
	global_load_lds_dwordx4 v[200:201], off
	v_lshl_add_u64 v[200:201], v[216:217], 0, s[8:9]
	s_mov_b32 m0, s39
	s_nop 0
	global_load_lds_dwordx4 v[200:201], off
	s_add_u32 s14, s14, 0x40080
	s_addc_u32 s15, s15, 0
	s_mov_b32 m0, s40
	v_lshl_add_u64 v[248:249], s[14:15], 0, v[130:131]
	global_load_lds_dwordx4 v[248:249], off
	v_lshl_add_u64 v[248:249], s[14:15], 0, v[128:129]
	s_mov_b32 m0, s41
	s_nop 0
	global_load_lds_dwordx4 v[248:249], off
	s_waitcnt lgkmcnt(0)
	s_waitcnt vmcnt(8)
	s_barrier
	s_setprio 1
	v_mfma_f32_16x16x32_bf16 v[60:63], v[144:147], v[160:163], v[60:63]
	v_mfma_f32_16x16x32_bf16 v[56:59], v[152:155], v[160:163], v[56:59]
	v_mfma_f32_16x16x32_bf16 v[44:47], v[144:147], v[168:171], v[44:47]
	v_mfma_f32_16x16x32_bf16 v[40:43], v[152:155], v[168:171], v[40:43]
	v_mfma_f32_16x16x32_bf16 v[28:31], v[144:147], v[176:179], v[28:31]
	v_mfma_f32_16x16x32_bf16 v[24:27], v[152:155], v[176:179], v[24:27]
	v_mfma_f32_16x16x32_bf16 v[12:15], v[144:147], v[184:187], v[12:15]
	v_mfma_f32_16x16x32_bf16 v[8:11], v[152:155], v[184:187], v[8:11]
	v_mfma_f32_16x16x32_bf16 v[60:63], v[148:151], v[164:167], v[60:63]
	v_mfma_f32_16x16x32_bf16 v[56:59], v[156:159], v[164:167], v[56:59]
	v_mfma_f32_16x16x32_bf16 v[44:47], v[148:151], v[172:175], v[44:47]
	v_mfma_f32_16x16x32_bf16 v[40:43], v[156:159], v[172:175], v[40:43]
	v_mfma_f32_16x16x32_bf16 v[28:31], v[148:151], v[180:183], v[28:31]
	v_mfma_f32_16x16x32_bf16 v[24:27], v[156:159], v[180:183], v[24:27]
	v_mfma_f32_16x16x32_bf16 v[12:15], v[148:151], v[188:191], v[12:15]
	v_mfma_f32_16x16x32_bf16 v[8:11], v[156:159], v[188:191], v[8:11]
	v_mfma_f32_16x16x32_bf16 v[52:55], v[192:195], v[160:163], v[52:55]
	v_mfma_f32_16x16x32_bf16 v[48:51], v[204:207], v[160:163], v[48:51]
	v_mfma_f32_16x16x32_bf16 v[36:39], v[192:195], v[168:171], v[36:39]
	v_mfma_f32_16x16x32_bf16 v[32:35], v[204:207], v[168:171], v[32:35]
	v_mfma_f32_16x16x32_bf16 v[20:23], v[192:195], v[176:179], v[20:23]
	v_mfma_f32_16x16x32_bf16 v[16:19], v[204:207], v[176:179], v[16:19]
	v_mfma_f32_16x16x32_bf16 v[4:7], v[192:195], v[184:187], v[4:7]
	v_mfma_f32_16x16x32_bf16 v[0:3], v[204:207], v[184:187], v[0:3]
	v_mfma_f32_16x16x32_bf16 v[52:55], v[196:199], v[164:167], v[52:55]
	v_mfma_f32_16x16x32_bf16 v[48:51], v[208:211], v[164:167], v[48:51]
	v_mfma_f32_16x16x32_bf16 v[36:39], v[196:199], v[172:175], v[36:39]
	v_mfma_f32_16x16x32_bf16 v[32:35], v[208:211], v[172:175], v[32:35]
	v_mfma_f32_16x16x32_bf16 v[20:23], v[196:199], v[180:183], v[20:23]
	v_mfma_f32_16x16x32_bf16 v[16:19], v[208:211], v[180:183], v[16:19]
	v_mfma_f32_16x16x32_bf16 v[4:7], v[196:199], v[188:191], v[4:7]
	v_mfma_f32_16x16x32_bf16 v[0:3], v[208:211], v[188:191], v[0:3]
	s_setprio 0
	s_add_i32 s44, s44, 2
	s_add_u32 s12, s12, 0x100
	s_addc_u32 s13, s13, 0
	s_cmp_gt_u32 s44, 13
	s_barrier
	s_cbranch_scc0 .LBB0_643
	v_lshlrev_b32_e32 v128, 3, v136
	v_lshl_or_b32 v128, s26, 6, v128
	s_add_u32 s4, s22, 0x1c00000
	v_lshl_or_b32 v128, s0, 8, v128
	v_mov_b32_e32 v165, 0
	s_addc_u32 s5, s23, 0
	v_lshl_add_u32 v160, s27, 8, v137
	v_lshlrev_b32_e32 v164, 1, v128
	v_mov_b32_e32 v161, v165
	v_lshl_add_u64 v[128:129], s[4:5], 0, v[164:165]
	v_lshlrev_b64 v[174:175], 11, v[160:161]
	v_lshl_add_u64 v[130:131], v[128:129], 0, v[174:175]
	global_load_dwordx4 v[176:179], v[130:131], off
	global_load_dwordx4 v[180:183], v[130:131], off offset:64
	v_or_b32_e32 v130, 16, v160
	v_mov_b32_e32 v131, v165
	v_add_u32_e32 v168, 0x80, v160
	v_mov_b32_e32 v169, v165
	v_or_b32_e32 v132, 32, v160
	v_mov_b32_e32 v133, v165
	v_lshlrev_b64 v[172:173], 11, v[130:131]
	v_lshlrev_b64 v[130:131], 11, v[168:169]
	v_or_b32_e32 v134, 48, v160
	v_mov_b32_e32 v135, v165
	v_lshlrev_b64 v[170:171], 11, v[132:133]
	v_lshl_add_u64 v[130:131], s[4:5], 0, v[130:131]
	v_cmp_eq_u32_e32 vcc, 0, v136
	v_lshlrev_b64 v[166:167], 11, v[134:135]
	v_lshl_add_u64 v[162:163], v[130:131], 0, v[164:165]
	v_lshl_add_u64 v[136:137], v[128:129], 0, v[172:173]
	v_lshl_add_u64 v[138:139], v[128:129], 0, v[170:171]
	v_lshl_add_u64 v[184:185], v[128:129], 0, v[166:167]
	global_load_dwordx4 v[132:135], v[162:163], off
	global_load_dwordx4 v[128:131], v[162:163], off offset:64
	global_load_dwordx4 v[156:159], v[136:137], off
	global_load_dwordx4 v[152:155], v[136:137], off offset:64
	global_load_dwordx4 v[148:151], v[138:139], off
	global_load_dwordx4 v[144:147], v[138:139], off offset:64
	global_load_dwordx4 v[140:143], v[184:185], off
	s_nop 0
	global_load_dwordx4 v[136:139], v[184:185], off offset:64
	v_mbcnt_lo_u32_b32 v186, -1, 0
	v_mbcnt_hi_u32_b32 v169, -1, v186
	v_and_b32_e32 v185, 64, v169
	v_xor_b32_e32 v184, 16, v169
	v_add_u32_e32 v185, 64, v185
	v_xor_b32_e32 v186, 32, v169
	v_cmp_lt_i32_e64 s[0:1], v184, v185
	v_lshl_add_u64 v[174:175], s[4:5], 0, v[174:175]
	s_add_u32 s6, s22, 0x18ba4000
	v_cndmask_b32_e64 v187, v169, v184, s[0:1]
	v_cmp_lt_i32_e64 s[0:1], v186, v185
	v_lshl_add_u64 v[184:185], v[174:175], 0, v[164:165]
	v_lshlrev_b32_e32 v174, 2, v187
	v_cndmask_b32_e64 v169, v169, v186, s[0:1]
	v_lshlrev_b32_e32 v169, 2, v169
	s_addc_u32 s7, s23, 0
	s_and_b32 s8, s25, -4
	s_or_b32 s9, s26, s8
	s_mul_hi_u32 s8, s9, 0x21000
	s_mul_i32 s9, s9, 0x21000
	s_waitcnt vmcnt(0)
	v_lshlrev_b32_e32 v186, 16, v176
	v_and_b32_e32 v187, 0xffff0000, v176
	v_lshlrev_b32_e32 v176, 16, v177
	v_and_b32_e32 v177, 0xffff0000, v177
	v_lshlrev_b32_e32 v192, 16, v182
	v_and_b32_e32 v193, 0xffff0000, v182
	v_lshlrev_b32_e32 v182, 16, v183
	v_and_b32_e32 v183, 0xffff0000, v183
	v_pk_add_f32 v[126:127], v[126:127], v[176:177]
	v_pk_add_f32 v[124:125], v[124:125], v[186:187]
	v_lshlrev_b32_e32 v188, 16, v178
	v_and_b32_e32 v189, 0xffff0000, v178
	v_lshlrev_b32_e32 v178, 16, v179
	v_and_b32_e32 v179, 0xffff0000, v179
	v_pk_add_f32 v[176:177], v[114:115], v[182:183]
	v_mul_f32_e32 v114, v125, v125
	v_mul_f32_e32 v115, v127, v127
	v_pk_add_f32 v[122:123], v[122:123], v[178:179]
	v_pk_add_f32 v[120:121], v[120:121], v[188:189]
	v_fmac_f32_e32 v114, v124, v124
	v_fmac_f32_e32 v115, v126, v126
	v_pk_add_f32 v[178:179], v[112:113], v[192:193]
	v_cvt_pk_bf16_f32 v112, v124, v125
	v_add_f32_e32 v114, v114, v115
	v_mul_f32_e32 v115, v121, v121
	v_mul_f32_e32 v124, v123, v123
	v_lshlrev_b32_e32 v190, 16, v180
	v_and_b32_e32 v191, 0xffff0000, v180
	v_lshlrev_b32_e32 v180, 16, v181
	v_and_b32_e32 v181, 0xffff0000, v181
	v_fmac_f32_e32 v115, v120, v120
	v_fmac_f32_e32 v124, v122, v122
	v_pk_add_f32 v[118:119], v[118:119], v[180:181]
	v_pk_add_f32 v[116:117], v[116:117], v[190:191]
	v_add_f32_e32 v115, v115, v124
	v_add_f32_e32 v114, v114, v115
	v_mul_f32_e32 v115, v117, v117
	v_mul_f32_e32 v124, v119, v119
	v_fmac_f32_e32 v115, v116, v116
	v_fmac_f32_e32 v124, v118, v118
	v_add_f32_e32 v115, v115, v124
	v_mul_f32_e32 v124, v179, v179
	v_mul_f32_e32 v125, v177, v177
	v_fmac_f32_e32 v124, v178, v178
	v_fmac_f32_e32 v125, v176, v176
	v_add_f32_e32 v124, v124, v125
	v_add_f32_e32 v115, v115, v124
	v_add_f32_e32 v124, v114, v115
	ds_bpermute_b32 v125, v174, v124
	v_cvt_pk_bf16_f32 v113, v126, v127
	v_cvt_pk_bf16_f32 v114, v120, v121
	v_cvt_pk_bf16_f32 v115, v122, v123
	global_store_dwordx4 v[184:185], v[112:115], off
	s_waitcnt lgkmcnt(0)
	s_nop 0
	v_add_f32_e32 v112, v124, v125
	ds_bpermute_b32 v113, v169, v112
	v_cvt_pk_bf16_f32 v114, v116, v117
	v_cvt_pk_bf16_f32 v115, v118, v119
	v_cvt_pk_bf16_f32 v116, v178, v179
	v_cvt_pk_bf16_f32 v117, v176, v177
	global_store_dwordx4 v[184:185], v[114:117], off offset:64
	s_and_saveexec_b64 s[0:1], vcc
	s_cbranch_execz .LBB0_646
	s_add_u32 s10, s6, s9
	s_addc_u32 s11, s7, s8
	s_waitcnt lgkmcnt(0)
	v_add_f32_e32 v114, v112, v113
	v_lshl_add_u64 v[112:113], v[160:161], 2, s[10:11]
	global_store_dword v[112:113], v114, off

.LBB0_774:
	s_add_u32 s12, s8, s10
	ds_read_b128 v[148:151], v143
	ds_read_b128 v[152:155], v143 offset:1024
	ds_read_b128 v[156:159], v143 offset:2048
	ds_read_b128 v[160:163], v143 offset:3072
	s_addc_u32 s13, s9, s11
	s_add_u32 s12, s12, 0x5c00100
	s_addc_u32 s13, s13, 0
	s_add_u32 s43, s38, s10
	s_addc_u32 s44, s39, s11
	s_cmpk_eq_i32 s10, 0x700
	s_cselect_b32 s15, s1, s13
	s_cselect_b32 s14, s0, s12
	s_cselect_b32 s13, s5, s44
	s_cselect_b32 s12, s4, s43
	s_mov_b32 m0, s41
	v_lshl_add_u64 v[196:197], v[134:135], 0, s[10:11]
	ds_read_b128 v[164:167], v144
	ds_read_b128 v[168:171], v144 offset:1024
	ds_read_b128 v[172:175], v144 offset:2048
	ds_read_b128 v[176:179], v144 offset:3072
	ds_read_b128 v[180:183], v144 offset:4096
	ds_read_b128 v[184:187], v144 offset:5120
	ds_read_b128 v[188:191], v144 offset:6144
	ds_read_b128 v[192:195], v144 offset:7168
	global_load_lds_dwordx4 v[196:197], off
	v_lshl_add_u64 v[196:197], v[136:137], 0, s[10:11]
	s_mov_b32 m0, s42
	s_nop 0
	global_load_lds_dwordx4 v[196:197], off
	ds_read_b128 v[196:199], v145
	ds_read_b128 v[204:207], v145 offset:1024
	ds_read_b128 v[208:211], v145 offset:2048
	ds_read_b128 v[212:215], v145 offset:3072
	s_waitcnt lgkmcnt(0)
	s_waitcnt vmcnt(8)
	s_barrier
	s_setprio 1
	v_mfma_f32_16x16x32_bf16 v[124:127], v[148:151], v[164:167], v[124:127]
	v_mfma_f32_16x16x32_bf16 v[120:123], v[156:159], v[164:167], v[120:123]
	v_mfma_f32_16x16x32_bf16 v[108:111], v[148:151], v[172:175], v[108:111]
	v_mfma_f32_16x16x32_bf16 v[104:107], v[156:159], v[172:175], v[104:107]
	v_mfma_f32_16x16x32_bf16 v[92:95], v[148:151], v[180:183], v[92:95]
	v_mfma_f32_16x16x32_bf16 v[88:91], v[156:159], v[180:183], v[88:91]
	v_mfma_f32_16x16x32_bf16 v[76:79], v[148:151], v[188:191], v[76:79]
	v_mfma_f32_16x16x32_bf16 v[72:75], v[156:159], v[188:191], v[72:75]
	v_mfma_f32_16x16x32_bf16 v[124:127], v[152:155], v[168:171], v[124:127]
	v_mfma_f32_16x16x32_bf16 v[120:123], v[160:163], v[168:171], v[120:123]
	v_mfma_f32_16x16x32_bf16 v[108:111], v[152:155], v[176:179], v[108:111]
	v_mfma_f32_16x16x32_bf16 v[104:107], v[160:163], v[176:179], v[104:107]
	v_mfma_f32_16x16x32_bf16 v[92:95], v[152:155], v[184:187], v[92:95]
	v_mfma_f32_16x16x32_bf16 v[88:91], v[160:163], v[184:187], v[88:91]
	v_mfma_f32_16x16x32_bf16 v[76:79], v[152:155], v[192:195], v[76:79]
	v_mfma_f32_16x16x32_bf16 v[72:75], v[160:163], v[192:195], v[72:75]
	v_mfma_f32_16x16x32_bf16 v[116:119], v[196:199], v[164:167], v[116:119]
	v_mfma_f32_16x16x32_bf16 v[112:115], v[208:211], v[164:167], v[112:115]
	v_mfma_f32_16x16x32_bf16 v[100:103], v[196:199], v[172:175], v[100:103]
	v_mfma_f32_16x16x32_bf16 v[96:99], v[208:211], v[172:175], v[96:99]
	v_mfma_f32_16x16x32_bf16 v[84:87], v[196:199], v[180:183], v[84:87]
	v_mfma_f32_16x16x32_bf16 v[80:83], v[208:211], v[180:183], v[80:83]
	v_mfma_f32_16x16x32_bf16 v[68:71], v[196:199], v[188:191], v[68:71]
	v_mfma_f32_16x16x32_bf16 v[64:67], v[208:211], v[188:191], v[64:67]
	v_mfma_f32_16x16x32_bf16 v[116:119], v[204:207], v[168:171], v[116:119]
	v_mfma_f32_16x16x32_bf16 v[112:115], v[212:215], v[168:171], v[112:115]
	v_mfma_f32_16x16x32_bf16 v[100:103], v[204:207], v[176:179], v[100:103]
	v_mfma_f32_16x16x32_bf16 v[96:99], v[212:215], v[176:179], v[96:99]
	v_mfma_f32_16x16x32_bf16 v[84:87], v[204:207], v[184:187], v[84:87]
	v_mfma_f32_16x16x32_bf16 v[80:83], v[212:215], v[184:187], v[80:83]
	v_mfma_f32_16x16x32_bf16 v[68:71], v[204:207], v[192:195], v[68:71]
	v_mfma_f32_16x16x32_bf16 v[64:67], v[212:215], v[192:195], v[64:67]
	s_setprio 0
	s_barrier
	ds_read_b128 v[164:167], v144 offset:16384
	ds_read_b128 v[168:171], v144 offset:17408
	ds_read_b128 v[172:175], v144 offset:18432
	ds_read_b128 v[176:179], v144 offset:19456
	ds_read_b128 v[180:183], v144 offset:20480
	ds_read_b128 v[184:187], v144 offset:21504
	ds_read_b128 v[188:191], v144 offset:22528
	ds_read_b128 v[192:195], v144 offset:23552
	s_mov_b32 m0, s19
	v_lshl_add_u64 v[200:201], s[12:13], 0, v[132:133]
	global_load_lds_dwordx4 v[200:201], off
	v_lshl_add_u64 v[216:217], s[12:13], 0, v[130:131]
	s_mov_b32 m0, s24
	s_nop 0
	global_load_lds_dwordx4 v[216:217], off
	s_mov_b32 m0, s25
	v_lshl_add_u64 v[218:219], s[14:15], 0, v[132:133]
	global_load_lds_dwordx4 v[218:219], off
	v_lshl_add_u64 v[220:221], s[14:15], 0, v[130:131]
	s_mov_b32 m0, s26
	s_nop 0
	global_load_lds_dwordx4 v[220:221], off
	s_add_u32 s44, s12, 0x40000
	s_addc_u32 s45, s13, 0
	s_mov_b32 m0, s27
	v_lshl_add_u64 v[248:249], s[44:45], 0, v[132:133]
	global_load_lds_dwordx4 v[248:249], off
	v_lshl_add_u64 v[248:249], s[44:45], 0, v[130:131]
	s_mov_b32 m0, s28
	s_nop 0
	global_load_lds_dwordx4 v[248:249], off
	s_waitcnt lgkmcnt(0)
	s_waitcnt vmcnt(8)
	s_barrier
	s_setprio 1
	v_mfma_f32_16x16x32_bf16 v[60:63], v[148:151], v[164:167], v[60:63]
	v_mfma_f32_16x16x32_bf16 v[56:59], v[156:159], v[164:167], v[56:59]
	v_mfma_f32_16x16x32_bf16 v[44:47], v[148:151], v[172:175], v[44:47]
	v_mfma_f32_16x16x32_bf16 v[40:43], v[156:159], v[172:175], v[40:43]
	v_mfma_f32_16x16x32_bf16 v[28:31], v[148:151], v[180:183], v[28:31]
	v_mfma_f32_16x16x32_bf16 v[24:27], v[156:159], v[180:183], v[24:27]
	v_mfma_f32_16x16x32_bf16 v[12:15], v[148:151], v[188:191], v[12:15]
	v_mfma_f32_16x16x32_bf16 v[8:11], v[156:159], v[188:191], v[8:11]
	v_mfma_f32_16x16x32_bf16 v[60:63], v[152:155], v[168:171], v[60:63]
	v_mfma_f32_16x16x32_bf16 v[56:59], v[160:163], v[168:171], v[56:59]
	v_mfma_f32_16x16x32_bf16 v[44:47], v[152:155], v[176:179], v[44:47]
	v_mfma_f32_16x16x32_bf16 v[40:43], v[160:163], v[176:179], v[40:43]
	v_mfma_f32_16x16x32_bf16 v[28:31], v[152:155], v[184:187], v[28:31]
	v_mfma_f32_16x16x32_bf16 v[24:27], v[160:163], v[184:187], v[24:27]
	v_mfma_f32_16x16x32_bf16 v[12:15], v[152:155], v[192:195], v[12:15]
	v_mfma_f32_16x16x32_bf16 v[8:11], v[160:163], v[192:195], v[8:11]
	v_mfma_f32_16x16x32_bf16 v[52:55], v[196:199], v[164:167], v[52:55]
	v_mfma_f32_16x16x32_bf16 v[48:51], v[208:211], v[164:167], v[48:51]
	v_mfma_f32_16x16x32_bf16 v[36:39], v[196:199], v[172:175], v[36:39]
	v_mfma_f32_16x16x32_bf16 v[32:35], v[208:211], v[172:175], v[32:35]
	v_mfma_f32_16x16x32_bf16 v[20:23], v[196:199], v[180:183], v[20:23]
	v_mfma_f32_16x16x32_bf16 v[16:19], v[208:211], v[180:183], v[16:19]
	v_mfma_f32_16x16x32_bf16 v[4:7], v[196:199], v[188:191], v[4:7]
	v_mfma_f32_16x16x32_bf16 v[0:3], v[208:211], v[188:191], v[0:3]
	v_mfma_f32_16x16x32_bf16 v[52:55], v[204:207], v[168:171], v[52:55]
	v_mfma_f32_16x16x32_bf16 v[48:51], v[212:215], v[168:171], v[48:51]
	v_mfma_f32_16x16x32_bf16 v[36:39], v[204:207], v[176:179], v[36:39]
	v_mfma_f32_16x16x32_bf16 v[32:35], v[212:215], v[176:179], v[32:35]
	v_mfma_f32_16x16x32_bf16 v[20:23], v[204:207], v[184:187], v[20:23]
	v_mfma_f32_16x16x32_bf16 v[16:19], v[212:215], v[184:187], v[16:19]
	v_mfma_f32_16x16x32_bf16 v[4:7], v[204:207], v[192:195], v[4:7]
	v_mfma_f32_16x16x32_bf16 v[0:3], v[212:215], v[192:195], v[0:3]
	s_setprio 0
	s_barrier
	ds_read_b128 v[148:151], v146
	ds_read_b128 v[152:155], v146 offset:1024
	ds_read_b128 v[156:159], v146 offset:2048
	ds_read_b128 v[160:163], v146 offset:3072
	s_add_u32 s14, s14, 0x40000
	s_addc_u32 s15, s15, 0
	s_mov_b32 m0, s29
	v_lshl_add_u64 v[196:197], s[14:15], 0, v[132:133]
	ds_read_b128 v[164:167], v144 offset:32768
	ds_read_b128 v[168:171], v144 offset:33792
	ds_read_b128 v[172:175], v144 offset:34816
	ds_read_b128 v[176:179], v144 offset:35840
	ds_read_b128 v[180:183], v144 offset:36864
	ds_read_b128 v[184:187], v144 offset:37888
	ds_read_b128 v[188:191], v144 offset:38912
	ds_read_b128 v[192:195], v144 offset:39936
	global_load_lds_dwordx4 v[196:197], off
	v_lshl_add_u64 v[196:197], s[14:15], 0, v[130:131]
	s_mov_b32 m0, s30
	s_nop 0
	global_load_lds_dwordx4 v[196:197], off
	ds_read_b128 v[196:199], v147
	ds_read_b128 v[204:207], v147 offset:1024
	ds_read_b128 v[208:211], v147 offset:2048
	ds_read_b128 v[212:215], v147 offset:3072
	s_waitcnt lgkmcnt(0)
	s_waitcnt vmcnt(8)
	s_barrier
	s_setprio 1
	v_mfma_f32_16x16x32_bf16 v[124:127], v[148:151], v[164:167], v[124:127]
	v_mfma_f32_16x16x32_bf16 v[120:123], v[156:159], v[164:167], v[120:123]
	v_mfma_f32_16x16x32_bf16 v[108:111], v[148:151], v[172:175], v[108:111]
	v_mfma_f32_16x16x32_bf16 v[104:107], v[156:159], v[172:175], v[104:107]
	v_mfma_f32_16x16x32_bf16 v[92:95], v[148:151], v[180:183], v[92:95]
	v_mfma_f32_16x16x32_bf16 v[88:91], v[156:159], v[180:183], v[88:91]
	v_mfma_f32_16x16x32_bf16 v[76:79], v[148:151], v[188:191], v[76:79]
	v_mfma_f32_16x16x32_bf16 v[72:75], v[156:159], v[188:191], v[72:75]
	v_mfma_f32_16x16x32_bf16 v[124:127], v[152:155], v[168:171], v[124:127]
	v_mfma_f32_16x16x32_bf16 v[120:123], v[160:163], v[168:171], v[120:123]
	v_mfma_f32_16x16x32_bf16 v[108:111], v[152:155], v[176:179], v[108:111]
	v_mfma_f32_16x16x32_bf16 v[104:107], v[160:163], v[176:179], v[104:107]
	v_mfma_f32_16x16x32_bf16 v[92:95], v[152:155], v[184:187], v[92:95]
	v_mfma_f32_16x16x32_bf16 v[88:91], v[160:163], v[184:187], v[88:91]
	v_mfma_f32_16x16x32_bf16 v[76:79], v[152:155], v[192:195], v[76:79]
	v_mfma_f32_16x16x32_bf16 v[72:75], v[160:163], v[192:195], v[72:75]
	v_mfma_f32_16x16x32_bf16 v[116:119], v[196:199], v[164:167], v[116:119]
	v_mfma_f32_16x16x32_bf16 v[112:115], v[208:211], v[164:167], v[112:115]
	v_mfma_f32_16x16x32_bf16 v[100:103], v[196:199], v[172:175], v[100:103]
	v_mfma_f32_16x16x32_bf16 v[96:99], v[208:211], v[172:175], v[96:99]
	v_mfma_f32_16x16x32_bf16 v[84:87], v[196:199], v[180:183], v[84:87]
	v_mfma_f32_16x16x32_bf16 v[80:83], v[208:211], v[180:183], v[80:83]
	v_mfma_f32_16x16x32_bf16 v[68:71], v[196:199], v[188:191], v[68:71]
	v_mfma_f32_16x16x32_bf16 v[64:67], v[208:211], v[188:191], v[64:67]
	v_mfma_f32_16x16x32_bf16 v[116:119], v[204:207], v[168:171], v[116:119]
	v_mfma_f32_16x16x32_bf16 v[112:115], v[212:215], v[168:171], v[112:115]
	v_mfma_f32_16x16x32_bf16 v[100:103], v[204:207], v[176:179], v[100:103]
	v_mfma_f32_16x16x32_bf16 v[96:99], v[212:215], v[176:179], v[96:99]
	v_mfma_f32_16x16x32_bf16 v[84:87], v[204:207], v[184:187], v[84:87]
	v_mfma_f32_16x16x32_bf16 v[80:83], v[212:215], v[184:187], v[80:83]
	v_mfma_f32_16x16x32_bf16 v[68:71], v[204:207], v[192:195], v[68:71]
	v_mfma_f32_16x16x32_bf16 v[64:67], v[212:215], v[192:195], v[64:67]
	s_setprio 0
	s_barrier
	ds_read_b128 v[164:167], v144 offset:49152
	ds_read_b128 v[168:171], v144 offset:50176
	ds_read_b128 v[172:175], v144 offset:51200
	ds_read_b128 v[176:179], v144 offset:52224
	ds_read_b128 v[180:183], v144 offset:53248
	ds_read_b128 v[184:187], v144 offset:54272
	ds_read_b128 v[188:191], v144 offset:55296
	ds_read_b128 v[192:195], v144 offset:56320
	s_mov_b32 m0, s31
	v_lshl_add_u64 v[200:201], v[200:201], 0, s[6:7]
	global_load_lds_dwordx4 v[200:201], off
	v_lshl_add_u64 v[200:201], v[216:217], 0, s[6:7]
	s_mov_b32 m0, s33
	s_nop 0
	global_load_lds_dwordx4 v[200:201], off
	s_mov_b32 m0, s34
	v_lshl_add_u64 v[200:201], v[218:219], 0, s[6:7]
	global_load_lds_dwordx4 v[200:201], off
	v_lshl_add_u64 v[200:201], v[220:221], 0, s[6:7]
	s_mov_b32 m0, s35
	s_nop 0
	global_load_lds_dwordx4 v[200:201], off
	s_add_u32 s12, s12, 0x40080
	s_addc_u32 s13, s13, 0
	s_mov_b32 m0, s36
	v_lshl_add_u64 v[248:249], s[12:13], 0, v[132:133]
	global_load_lds_dwordx4 v[248:249], off
	v_lshl_add_u64 v[248:249], s[12:13], 0, v[130:131]
	s_mov_b32 m0, s37
	s_nop 0
	global_load_lds_dwordx4 v[248:249], off
	s_waitcnt lgkmcnt(0)
	s_waitcnt vmcnt(8)
	s_barrier
	s_setprio 1
	v_mfma_f32_16x16x32_bf16 v[60:63], v[148:151], v[164:167], v[60:63]
	v_mfma_f32_16x16x32_bf16 v[56:59], v[156:159], v[164:167], v[56:59]
	v_mfma_f32_16x16x32_bf16 v[44:47], v[148:151], v[172:175], v[44:47]
	v_mfma_f32_16x16x32_bf16 v[40:43], v[156:159], v[172:175], v[40:43]
	v_mfma_f32_16x16x32_bf16 v[28:31], v[148:151], v[180:183], v[28:31]
	v_mfma_f32_16x16x32_bf16 v[24:27], v[156:159], v[180:183], v[24:27]
	v_mfma_f32_16x16x32_bf16 v[12:15], v[148:151], v[188:191], v[12:15]
	v_mfma_f32_16x16x32_bf16 v[8:11], v[156:159], v[188:191], v[8:11]
	v_mfma_f32_16x16x32_bf16 v[60:63], v[152:155], v[168:171], v[60:63]
	v_mfma_f32_16x16x32_bf16 v[56:59], v[160:163], v[168:171], v[56:59]
	v_mfma_f32_16x16x32_bf16 v[44:47], v[152:155], v[176:179], v[44:47]
	v_mfma_f32_16x16x32_bf16 v[40:43], v[160:163], v[176:179], v[40:43]
	v_mfma_f32_16x16x32_bf16 v[28:31], v[152:155], v[184:187], v[28:31]
	v_mfma_f32_16x16x32_bf16 v[24:27], v[160:163], v[184:187], v[24:27]
	v_mfma_f32_16x16x32_bf16 v[12:15], v[152:155], v[192:195], v[12:15]
	v_mfma_f32_16x16x32_bf16 v[8:11], v[160:163], v[192:195], v[8:11]
	v_mfma_f32_16x16x32_bf16 v[52:55], v[196:199], v[164:167], v[52:55]
	v_mfma_f32_16x16x32_bf16 v[48:51], v[208:211], v[164:167], v[48:51]
	v_mfma_f32_16x16x32_bf16 v[36:39], v[196:199], v[172:175], v[36:39]
	v_mfma_f32_16x16x32_bf16 v[32:35], v[208:211], v[172:175], v[32:35]
	v_mfma_f32_16x16x32_bf16 v[20:23], v[196:199], v[180:183], v[20:23]
	v_mfma_f32_16x16x32_bf16 v[16:19], v[208:211], v[180:183], v[16:19]
	v_mfma_f32_16x16x32_bf16 v[4:7], v[196:199], v[188:191], v[4:7]
	v_mfma_f32_16x16x32_bf16 v[0:3], v[208:211], v[188:191], v[0:3]
	v_mfma_f32_16x16x32_bf16 v[52:55], v[204:207], v[168:171], v[52:55]
	v_mfma_f32_16x16x32_bf16 v[48:51], v[212:215], v[168:171], v[48:51]
	v_mfma_f32_16x16x32_bf16 v[36:39], v[204:207], v[176:179], v[36:39]
	v_mfma_f32_16x16x32_bf16 v[32:35], v[212:215], v[176:179], v[32:35]
	v_mfma_f32_16x16x32_bf16 v[20:23], v[204:207], v[184:187], v[20:23]
	v_mfma_f32_16x16x32_bf16 v[16:19], v[212:215], v[184:187], v[16:19]
	v_mfma_f32_16x16x32_bf16 v[4:7], v[204:207], v[192:195], v[4:7]
	v_mfma_f32_16x16x32_bf16 v[0:3], v[212:215], v[192:195], v[0:3]
	s_setprio 0
	s_add_i32 s40, s40, 2
	s_add_u32 s10, s10, 0x100
	s_addc_u32 s11, s11, 0
	s_cmp_gt_u32 s40, 13
	s_barrier
	s_cbranch_scc0 .LBB0_774
	v_mul_u32_u24_e32 v130, 0x21000, v141
	v_mov_b32_e32 v133, 0
	v_lshlrev_b32_e32 v130, 2, v130
	v_mov_b32_e32 v131, v133
	v_lshl_add_u32 v132, s18, 8, v142
	v_lshl_add_u64 v[130:131], s[22:23], 0, v[130:131]
	v_lshl_add_u64 v[130:131], v[132:133], 2, v[130:131]
	s_mov_b64 s[0:1], 0x18ba4000
	v_lshl_add_u64 v[134:135], v[130:131], 0, s[0:1]
	s_mov_b32 s0, 0x18ba4000
	v_add_co_u32_e32 v136, vcc, s0, v130
	s_mov_b32 s0, 0x18bc5000
	s_nop 0
	v_addc_co_u32_e32 v137, vcc, 0, v131, vcc
	v_add_co_u32_e32 v142, vcc, s0, v130
	s_mov_b32 s0, 0x18be6000
	s_nop 0
	v_addc_co_u32_e32 v143, vcc, 0, v131, vcc
	v_add_co_u32_e32 v144, vcc, s0, v130
	s_mov_b32 s0, 0x18c07000
	s_nop 0
	v_addc_co_u32_e32 v145, vcc, 0, v131, vcc
	v_add_co_u32_e32 v130, vcc, s0, v130
	v_mov_b32_e32 v151, 0x358637bd
	s_nop 0
	v_addc_co_u32_e32 v131, vcc, 0, v131, vcc
	global_load_dword v146, v[142:143], off
	global_load_dword v150, v[142:143], off offset:64
	global_load_dword v149, v[144:145], off
	global_load_dword v152, v[144:145], off offset:64
	global_load_dword v147, v[130:131], off
	global_load_dword v153, v[130:131], off offset:64
	global_load_dword v148, v[136:137], off
	global_load_dword v154, v[134:135], off offset:64
	global_load_dword v155, v[134:135], off offset:128
	global_load_dword v156, v[142:143], off offset:128
	global_load_dword v157, v[144:145], off offset:128
	global_load_dword v158, v[130:131], off offset:128
	global_load_dword v159, v[134:135], off offset:192
	global_load_dword v160, v[142:143], off offset:192
	global_load_dword v161, v[144:145], off offset:192
	global_load_dword v162, v[130:131], off offset:192
	global_load_dword v163, v[134:135], off offset:512
	global_load_dword v164, v[142:143], off offset:512
	global_load_dword v165, v[144:145], off offset:512
	global_load_dword v166, v[130:131], off offset:512
	global_load_dword v167, v[134:135], off offset:576
	global_load_dword v168, v[142:143], off offset:576
	global_load_dword v169, v[144:145], off offset:576
	global_load_dword v170, v[130:131], off offset:576
	global_load_dword v171, v[134:135], off offset:640
	global_load_dword v172, v[142:143], off offset:640
	global_load_dword v173, v[144:145], off offset:640
	global_load_dword v174, v[130:131], off offset:640
	s_nop 0
	global_load_dword v135, v[134:135], off offset:704
	s_nop 0
	global_load_dword v142, v[142:143], off offset:704
	s_nop 0
	global_load_dword v143, v[144:145], off offset:704
	s_nop 0
	global_load_dword v144, v[130:131], off offset:704
	v_mbcnt_lo_u32_b32 v131, -1, 0
	v_mbcnt_hi_u32_b32 v131, -1, v131
	v_and_b32_e32 v136, 64, v131
	v_xor_b32_e32 v134, 16, v131
	v_add_u32_e32 v136, 64, v136
	v_xor_b32_e32 v137, 32, v131
	v_cmp_lt_i32_e64 s[0:1], v134, v136
	s_add_u32 s4, s22, 0x195cc000
	s_addc_u32 s5, s23, 0
	v_cndmask_b32_e64 v134, v131, v134, s[0:1]
	v_cmp_lt_i32_e64 s[0:1], v137, v136
	s_add_u32 s6, s22, 0x18fc4000
	s_addc_u32 s7, s23, 0
	v_cndmask_b32_e64 v136, v131, v137, s[0:1]
	v_lshlrev_b32_e32 v131, 2, v134
	v_lshlrev_b32_e32 v134, 2, v136
	s_lshl_b32 s8, s17, 6
	s_lshl_b32 s0, s2, 8
	v_lshlrev_b32_e32 v130, 3, v141
	s_or_b32 s0, s8, s0
	v_cmp_eq_u32_e32 vcc, 0, v141
	s_waitcnt vmcnt(0)
	v_pk_add_f32 v[136:137], v[148:149], v[146:147]
	s_nop 0
	v_add_f32_e32 v136, v136, v137
	ds_bpermute_b32 v137, v131, v136
	v_add_f32_e32 v145, v154, v150
	v_add_f32_e32 v147, v155, v156
	v_add_f32_e32 v148, v157, v158
	v_add_f32_e32 v147, v147, v148
	s_waitcnt lgkmcnt(0)
	v_add_f32_e32 v136, v136, v137
	ds_bpermute_b32 v137, v134, v136
	v_add_f32_e32 v149, v159, v160
	ds_bpermute_b32 v148, v131, v147
	v_or_b32_e32 v160, s0, v130
	v_add_f32_e32 v146, v152, v153
	s_waitcnt lgkmcnt(1)
	v_add_f32_e32 v136, v136, v137
	v_fmamk_f32 v136, v136, 0x3a800000, v151
	v_rsq_f32_e32 v154, v136
	v_add_f32_e32 v136, v161, v162
	v_add_f32_e32 v136, v149, v136
	ds_bpermute_b32 v137, v131, v136
	s_waitcnt lgkmcnt(1)
	v_add_f32_e32 v149, v147, v148
	v_add_f32_e32 v155, v171, v172
	v_add_f32_e32 v156, v173, v174
	v_add_f32_e32 v155, v155, v156
	s_waitcnt lgkmcnt(0)
	v_add_f32_e32 v147, v136, v137
	v_add_f32_e32 v136, v167, v168
	v_add_f32_e32 v137, v169, v170
	v_add_f32_e32 v135, v135, v142
	v_add_f32_e32 v142, v143, v144
	v_add_f32_e32 v136, v136, v137
	v_add_f32_e32 v135, v135, v142
	ds_bpermute_b32 v137, v131, v136
	ds_bpermute_b32 v156, v131, v155
	ds_bpermute_b32 v157, v131, v135
	v_pk_mul_f32 v[126:127], v[126:127], v[154:155] op_sel_hi:[1,0]
	v_pk_mul_f32 v[124:125], v[124:125], v[154:155] op_sel_hi:[1,0]
	s_waitcnt lgkmcnt(2)
	v_add_f32_e32 v143, v136, v137
	s_waitcnt lgkmcnt(1)
	v_add_f32_e32 v137, v155, v156
	s_waitcnt lgkmcnt(0)
	v_add_f32_e32 v135, v135, v157
	v_pk_mul_f32 v[122:123], v[122:123], v[154:155] op_sel_hi:[1,0]
	v_pk_mul_f32 v[120:121], v[120:121], v[154:155] op_sel_hi:[1,0]
	v_pk_mul_f32 v[118:119], v[118:119], v[154:155] op_sel_hi:[1,0]
	v_pk_mul_f32 v[156:157], v[116:117], v[154:155] op_sel_hi:[1,0]
	v_pk_mul_f32 v[158:159], v[114:115], v[154:155] op_sel_hi:[1,0]
	v_pk_mul_f32 v[154:155], v[112:113], v[154:155] op_sel_hi:[1,0]
	v_lshlrev_b64 v[112:113], 10, v[132:133]
	v_mul_f32_e32 v116, v125, v125
	v_mul_f32_e32 v117, v127, v127
	v_lshl_add_u64 v[114:115], s[4:5], 0, v[112:113]
	v_lshlrev_b32_e32 v112, 1, v160
	v_mov_b32_e32 v113, v133
	v_fmac_f32_e32 v116, v124, v124
	v_fmac_f32_e32 v117, v126, v126
	v_lshl_add_u64 v[160:161], v[114:115], 0, v[112:113]
	v_cvt_pk_bf16_f32 v114, v124, v125
	v_add_f32_e32 v116, v116, v117
	v_mul_f32_e32 v117, v121, v121
	v_mul_f32_e32 v124, v123, v123
	v_fmac_f32_e32 v117, v120, v120
	v_fmac_f32_e32 v124, v122, v122
	v_add_f32_e32 v145, v145, v146
	v_add_f32_e32 v117, v117, v124
	ds_bpermute_b32 v146, v131, v145
	v_add_f32_e32 v116, v116, v117
	v_mul_f32_e32 v117, v157, v157
	v_mul_f32_e32 v124, v119, v119
	v_fmac_f32_e32 v117, v156, v156
	v_fmac_f32_e32 v124, v118, v118
	v_add_f32_e32 v117, v117, v124
	v_mul_f32_e32 v124, v155, v155
	v_mul_f32_e32 v125, v159, v159
	v_fmac_f32_e32 v124, v154, v154
	v_fmac_f32_e32 v125, v158, v158
	v_add_f32_e32 v124, v124, v125
	s_waitcnt lgkmcnt(0)
	v_add_f32_e32 v152, v145, v146
	v_add_f32_e32 v145, v163, v164
	v_add_f32_e32 v146, v165, v166
	v_add_f32_e32 v117, v117, v124
	v_add_f32_e32 v145, v145, v146
	v_add_f32_e32 v124, v116, v117
	ds_bpermute_b32 v146, v131, v145
	ds_bpermute_b32 v125, v131, v124
	v_cvt_pk_bf16_f32 v115, v126, v127
	v_cvt_pk_bf16_f32 v116, v120, v121
	v_cvt_pk_bf16_f32 v117, v122, v123
	s_waitcnt lgkmcnt(1)
	v_add_f32_e32 v145, v145, v146
	global_store_dwordx4 v[160:161], v[114:117], off
	ds_bpermute_b32 v153, v134, v152
	ds_bpermute_b32 v150, v134, v149
	s_waitcnt lgkmcnt(2)
	v_add_f32_e32 v114, v124, v125
	ds_bpermute_b32 v148, v134, v147
	ds_bpermute_b32 v146, v134, v145
	ds_bpermute_b32 v144, v134, v143
	ds_bpermute_b32 v142, v134, v137
	ds_bpermute_b32 v136, v134, v135
	ds_bpermute_b32 v115, v134, v114
	s_and_b32 s0, s16, -4
	s_or_b32 s8, s17, s0
	s_mul_hi_u32 s2, s8, 0x21000
	s_mul_i32 s8, s8, 0x21000
	v_cvt_pk_bf16_f32 v116, v156, v157
	v_cvt_pk_bf16_f32 v117, v118, v119
	v_cvt_pk_bf16_f32 v118, v154, v155
	v_cvt_pk_bf16_f32 v119, v158, v159
	global_store_dwordx4 v[160:161], v[116:119], off offset:64
	s_and_saveexec_b64 s[0:1], vcc
	s_cbranch_execz .LBB0_777
	s_add_u32 s10, s6, s8
	s_addc_u32 s11, s7, s2
	v_lshl_add_u64 v[116:117], v[132:133], 2, s[10:11]
	s_waitcnt lgkmcnt(0)
	v_add_f32_e32 v114, v114, v115
	global_store_dword v[116:117], v114, off

.LBB0_883:
	ds_read_b128 v[128:131], v186
	ds_read_b128 v[132:135], v186 offset:1024
	ds_read_b128 v[136:139], v186 offset:2048
	ds_read_b128 v[140:143], v186 offset:3072
	s_add_u32 s28, s26, 0xfffc0080
	s_addc_u32 s29, s27, -1
	s_cmp_eq_u32 s40, 12
	s_cselect_b32 s31, s25, s29
	s_cselect_b32 s30, s34, s28
	s_cselect_b32 s29, s36, s39
	s_cselect_b32 s28, s37, s38
	v_lshl_add_u64 v[182:183], s[26:27], 0, v[164:165]
	s_add_i32 m0, s45, 0xc000
	ds_read_b128 v[144:147], v187
	ds_read_b128 v[148:151], v187 offset:1024
	ds_read_b128 v[152:155], v187 offset:2048
	ds_read_b128 v[156:159], v187 offset:3072
	ds_read_b128 v[170:173], v187 offset:4096
	ds_read_b128 v[174:177], v187 offset:5120
	ds_read_b128 v[178:181], v187 offset:6144
	ds_read_b128 v[192:195], v187 offset:7168
	global_load_lds_dwordx4 v[182:183], off
	v_lshl_add_u64 v[182:183], s[26:27], 0, v[166:167]
	s_add_i32 m0, s45, 0xe000
	s_nop 0
	global_load_lds_dwordx4 v[182:183], off
	ds_read_b128 v[196:199], v188
	ds_read_b128 v[204:207], v188 offset:1024
	ds_read_b128 v[208:211], v188 offset:2048
	ds_read_b128 v[212:215], v188 offset:3072
	s_waitcnt lgkmcnt(0)
	s_waitcnt vmcnt(8)
	s_barrier
	s_setprio 1
	v_mfma_f32_16x16x32_bf16 v[124:127], v[128:131], v[144:147], v[124:127]
	v_mfma_f32_16x16x32_bf16 v[120:123], v[136:139], v[144:147], v[120:123]
	v_mfma_f32_16x16x32_bf16 v[108:111], v[128:131], v[152:155], v[108:111]
	v_mfma_f32_16x16x32_bf16 v[104:107], v[136:139], v[152:155], v[104:107]
	v_mfma_f32_16x16x32_bf16 v[92:95], v[128:131], v[170:173], v[92:95]
	v_mfma_f32_16x16x32_bf16 v[88:91], v[136:139], v[170:173], v[88:91]
	v_mfma_f32_16x16x32_bf16 v[76:79], v[128:131], v[178:181], v[76:79]
	v_mfma_f32_16x16x32_bf16 v[72:75], v[136:139], v[178:181], v[72:75]
	v_mfma_f32_16x16x32_bf16 v[124:127], v[132:135], v[148:151], v[124:127]
	v_mfma_f32_16x16x32_bf16 v[120:123], v[140:143], v[148:151], v[120:123]
	v_mfma_f32_16x16x32_bf16 v[108:111], v[132:135], v[156:159], v[108:111]
	v_mfma_f32_16x16x32_bf16 v[104:107], v[140:143], v[156:159], v[104:107]
	v_mfma_f32_16x16x32_bf16 v[92:95], v[132:135], v[174:177], v[92:95]
	v_mfma_f32_16x16x32_bf16 v[88:91], v[140:143], v[174:177], v[88:91]
	v_mfma_f32_16x16x32_bf16 v[76:79], v[132:135], v[192:195], v[76:79]
	v_mfma_f32_16x16x32_bf16 v[72:75], v[140:143], v[192:195], v[72:75]
	v_mfma_f32_16x16x32_bf16 v[116:119], v[196:199], v[144:147], v[116:119]
	v_mfma_f32_16x16x32_bf16 v[112:115], v[208:211], v[144:147], v[112:115]
	v_mfma_f32_16x16x32_bf16 v[100:103], v[196:199], v[152:155], v[100:103]
	v_mfma_f32_16x16x32_bf16 v[96:99], v[208:211], v[152:155], v[96:99]
	v_mfma_f32_16x16x32_bf16 v[84:87], v[196:199], v[170:173], v[84:87]
	v_mfma_f32_16x16x32_bf16 v[80:83], v[208:211], v[170:173], v[80:83]
	v_mfma_f32_16x16x32_bf16 v[68:71], v[196:199], v[178:181], v[68:71]
	v_mfma_f32_16x16x32_bf16 v[64:67], v[208:211], v[178:181], v[64:67]
	v_mfma_f32_16x16x32_bf16 v[116:119], v[204:207], v[148:151], v[116:119]
	v_mfma_f32_16x16x32_bf16 v[112:115], v[212:215], v[148:151], v[112:115]
	v_mfma_f32_16x16x32_bf16 v[100:103], v[204:207], v[156:159], v[100:103]
	v_mfma_f32_16x16x32_bf16 v[96:99], v[212:215], v[156:159], v[96:99]
	v_mfma_f32_16x16x32_bf16 v[84:87], v[204:207], v[174:177], v[84:87]
	v_mfma_f32_16x16x32_bf16 v[80:83], v[212:215], v[174:177], v[80:83]
	v_mfma_f32_16x16x32_bf16 v[68:71], v[204:207], v[192:195], v[68:71]
	v_mfma_f32_16x16x32_bf16 v[64:67], v[212:215], v[192:195], v[64:67]
	s_setprio 0
	s_barrier
	ds_read_b128 v[144:147], v187 offset:16384
	ds_read_b128 v[148:151], v187 offset:17408
	ds_read_b128 v[152:155], v187 offset:18432
	ds_read_b128 v[156:159], v187 offset:19456
	ds_read_b128 v[170:173], v187 offset:20480
	ds_read_b128 v[174:177], v187 offset:21504
	ds_read_b128 v[178:181], v187 offset:22528
	ds_read_b128 v[192:195], v187 offset:23552
	s_mov_b32 m0, s43
	v_lshl_add_u64 v[182:183], s[28:29], 0, v[160:161]
	global_load_lds_dwordx4 v[182:183], off
	v_lshl_add_u64 v[200:201], s[28:29], 0, v[162:163]
	s_mov_b32 m0, s44
	s_nop 0
	global_load_lds_dwordx4 v[200:201], off
	s_mov_b32 m0, s45
	v_lshl_add_u64 v[216:217], s[30:31], 0, v[160:161]
	global_load_lds_dwordx4 v[216:217], off
	v_lshl_add_u64 v[218:219], s[30:31], 0, v[162:163]
	s_mov_b32 m0, s46
	s_nop 0
	global_load_lds_dwordx4 v[218:219], off
	s_add_u32 s66, s28, 0x40000
	s_addc_u32 s67, s29, 0
	s_mov_b32 m0, s47
	v_lshl_add_u64 v[248:249], s[66:67], 0, v[160:161]
	global_load_lds_dwordx4 v[248:249], off
	v_lshl_add_u64 v[248:249], s[66:67], 0, v[162:163]
	s_mov_b32 m0, s48
	s_nop 0
	global_load_lds_dwordx4 v[248:249], off
	s_waitcnt lgkmcnt(0)
	s_waitcnt vmcnt(8)
	s_barrier
	s_setprio 1
	v_mfma_f32_16x16x32_bf16 v[60:63], v[128:131], v[144:147], v[60:63]
	v_mfma_f32_16x16x32_bf16 v[56:59], v[136:139], v[144:147], v[56:59]
	v_mfma_f32_16x16x32_bf16 v[44:47], v[128:131], v[152:155], v[44:47]
	v_mfma_f32_16x16x32_bf16 v[40:43], v[136:139], v[152:155], v[40:43]
	v_mfma_f32_16x16x32_bf16 v[28:31], v[128:131], v[170:173], v[28:31]
	v_mfma_f32_16x16x32_bf16 v[24:27], v[136:139], v[170:173], v[24:27]
	v_mfma_f32_16x16x32_bf16 v[12:15], v[128:131], v[178:181], v[12:15]
	v_mfma_f32_16x16x32_bf16 v[8:11], v[136:139], v[178:181], v[8:11]
	v_mfma_f32_16x16x32_bf16 v[60:63], v[132:135], v[148:151], v[60:63]
	v_mfma_f32_16x16x32_bf16 v[56:59], v[140:143], v[148:151], v[56:59]
	v_mfma_f32_16x16x32_bf16 v[44:47], v[132:135], v[156:159], v[44:47]
	v_mfma_f32_16x16x32_bf16 v[40:43], v[140:143], v[156:159], v[40:43]
	v_mfma_f32_16x16x32_bf16 v[28:31], v[132:135], v[174:177], v[28:31]
	v_mfma_f32_16x16x32_bf16 v[24:27], v[140:143], v[174:177], v[24:27]
	v_mfma_f32_16x16x32_bf16 v[12:15], v[132:135], v[192:195], v[12:15]
	v_mfma_f32_16x16x32_bf16 v[8:11], v[140:143], v[192:195], v[8:11]
	v_mfma_f32_16x16x32_bf16 v[52:55], v[196:199], v[144:147], v[52:55]
	v_mfma_f32_16x16x32_bf16 v[48:51], v[208:211], v[144:147], v[48:51]
	v_mfma_f32_16x16x32_bf16 v[36:39], v[196:199], v[152:155], v[36:39]
	v_mfma_f32_16x16x32_bf16 v[32:35], v[208:211], v[152:155], v[32:35]
	v_mfma_f32_16x16x32_bf16 v[20:23], v[196:199], v[170:173], v[20:23]
	v_mfma_f32_16x16x32_bf16 v[16:19], v[208:211], v[170:173], v[16:19]
	v_mfma_f32_16x16x32_bf16 v[4:7], v[196:199], v[178:181], v[4:7]
	v_mfma_f32_16x16x32_bf16 v[0:3], v[208:211], v[178:181], v[0:3]
	v_mfma_f32_16x16x32_bf16 v[52:55], v[204:207], v[148:151], v[52:55]
	v_mfma_f32_16x16x32_bf16 v[48:51], v[212:215], v[148:151], v[48:51]
	v_mfma_f32_16x16x32_bf16 v[36:39], v[204:207], v[156:159], v[36:39]
	v_mfma_f32_16x16x32_bf16 v[32:35], v[212:215], v[156:159], v[32:35]
	v_mfma_f32_16x16x32_bf16 v[20:23], v[204:207], v[174:177], v[20:23]
	v_mfma_f32_16x16x32_bf16 v[16:19], v[212:215], v[174:177], v[16:19]
	v_mfma_f32_16x16x32_bf16 v[4:7], v[204:207], v[192:195], v[4:7]
	v_mfma_f32_16x16x32_bf16 v[0:3], v[212:215], v[192:195], v[0:3]
	s_setprio 0
	s_barrier
	ds_read_b128 v[128:131], v189
	ds_read_b128 v[132:135], v189 offset:1024
	ds_read_b128 v[136:139], v189 offset:2048
	ds_read_b128 v[140:143], v189 offset:3072
	s_add_u32 s30, s30, 0x40000
	s_addc_u32 s31, s31, 0
	s_mov_b32 m0, s49
	v_lshl_add_u64 v[196:197], s[30:31], 0, v[160:161]
	ds_read_b128 v[144:147], v187 offset:32768
	ds_read_b128 v[148:151], v187 offset:33792
	ds_read_b128 v[152:155], v187 offset:34816
	ds_read_b128 v[156:159], v187 offset:35840
	ds_read_b128 v[170:173], v187 offset:36864
	ds_read_b128 v[174:177], v187 offset:37888
	ds_read_b128 v[178:181], v187 offset:38912
	ds_read_b128 v[192:195], v187 offset:39936
	global_load_lds_dwordx4 v[196:197], off
	v_lshl_add_u64 v[196:197], s[30:31], 0, v[162:163]
	s_mov_b32 m0, s50
	s_nop 0
	global_load_lds_dwordx4 v[196:197], off
	ds_read_b128 v[196:199], v190
	ds_read_b128 v[204:207], v190 offset:1024
	ds_read_b128 v[208:211], v190 offset:2048
	ds_read_b128 v[212:215], v190 offset:3072
	s_waitcnt lgkmcnt(0)
	s_waitcnt vmcnt(8)
	s_barrier
	s_setprio 1
	v_mfma_f32_16x16x32_bf16 v[124:127], v[128:131], v[144:147], v[124:127]
	v_mfma_f32_16x16x32_bf16 v[120:123], v[136:139], v[144:147], v[120:123]
	v_mfma_f32_16x16x32_bf16 v[108:111], v[128:131], v[152:155], v[108:111]
	v_mfma_f32_16x16x32_bf16 v[104:107], v[136:139], v[152:155], v[104:107]
	v_mfma_f32_16x16x32_bf16 v[92:95], v[128:131], v[170:173], v[92:95]
	v_mfma_f32_16x16x32_bf16 v[88:91], v[136:139], v[170:173], v[88:91]
	v_mfma_f32_16x16x32_bf16 v[76:79], v[128:131], v[178:181], v[76:79]
	v_mfma_f32_16x16x32_bf16 v[72:75], v[136:139], v[178:181], v[72:75]
	v_mfma_f32_16x16x32_bf16 v[124:127], v[132:135], v[148:151], v[124:127]
	v_mfma_f32_16x16x32_bf16 v[120:123], v[140:143], v[148:151], v[120:123]
	v_mfma_f32_16x16x32_bf16 v[108:111], v[132:135], v[156:159], v[108:111]
	v_mfma_f32_16x16x32_bf16 v[104:107], v[140:143], v[156:159], v[104:107]
	v_mfma_f32_16x16x32_bf16 v[92:95], v[132:135], v[174:177], v[92:95]
	v_mfma_f32_16x16x32_bf16 v[88:91], v[140:143], v[174:177], v[88:91]
	v_mfma_f32_16x16x32_bf16 v[76:79], v[132:135], v[192:195], v[76:79]
	v_mfma_f32_16x16x32_bf16 v[72:75], v[140:143], v[192:195], v[72:75]
	v_mfma_f32_16x16x32_bf16 v[116:119], v[196:199], v[144:147], v[116:119]
	v_mfma_f32_16x16x32_bf16 v[112:115], v[208:211], v[144:147], v[112:115]
	v_mfma_f32_16x16x32_bf16 v[100:103], v[196:199], v[152:155], v[100:103]
	v_mfma_f32_16x16x32_bf16 v[96:99], v[208:211], v[152:155], v[96:99]
	v_mfma_f32_16x16x32_bf16 v[84:87], v[196:199], v[170:173], v[84:87]
	v_mfma_f32_16x16x32_bf16 v[80:83], v[208:211], v[170:173], v[80:83]
	v_mfma_f32_16x16x32_bf16 v[68:71], v[196:199], v[178:181], v[68:71]
	v_mfma_f32_16x16x32_bf16 v[64:67], v[208:211], v[178:181], v[64:67]
	v_mfma_f32_16x16x32_bf16 v[116:119], v[204:207], v[148:151], v[116:119]
	v_mfma_f32_16x16x32_bf16 v[112:115], v[212:215], v[148:151], v[112:115]
	v_mfma_f32_16x16x32_bf16 v[100:103], v[204:207], v[156:159], v[100:103]
	v_mfma_f32_16x16x32_bf16 v[96:99], v[212:215], v[156:159], v[96:99]
	v_mfma_f32_16x16x32_bf16 v[84:87], v[204:207], v[174:177], v[84:87]
	v_mfma_f32_16x16x32_bf16 v[80:83], v[212:215], v[174:177], v[80:83]
	v_mfma_f32_16x16x32_bf16 v[68:71], v[204:207], v[192:195], v[68:71]
	v_mfma_f32_16x16x32_bf16 v[64:67], v[212:215], v[192:195], v[64:67]
	s_setprio 0
	s_barrier
	ds_read_b128 v[144:147], v187 offset:49152
	ds_read_b128 v[148:151], v187 offset:50176
	ds_read_b128 v[152:155], v187 offset:51200
	ds_read_b128 v[156:159], v187 offset:52224
	ds_read_b128 v[170:173], v187 offset:53248
	ds_read_b128 v[174:177], v187 offset:54272
	ds_read_b128 v[178:181], v187 offset:55296
	ds_read_b128 v[192:195], v187 offset:56320
	s_mov_b32 m0, s54
	v_lshl_add_u64 v[182:183], v[182:183], 0, s[12:13]
	global_load_lds_dwordx4 v[182:183], off
	v_lshl_add_u64 v[182:183], v[200:201], 0, s[12:13]
	s_mov_b32 m0, s55
	s_nop 0
	global_load_lds_dwordx4 v[182:183], off
	s_mov_b32 m0, s56
	v_lshl_add_u64 v[182:183], v[216:217], 0, s[12:13]
	global_load_lds_dwordx4 v[182:183], off
	v_lshl_add_u64 v[182:183], v[218:219], 0, s[12:13]
	s_mov_b32 m0, s57
	s_nop 0
	global_load_lds_dwordx4 v[182:183], off
	s_add_u32 s28, s28, 0x40080
	s_addc_u32 s29, s29, 0
	s_mov_b32 m0, s58
	v_lshl_add_u64 v[248:249], s[28:29], 0, v[160:161]
	global_load_lds_dwordx4 v[248:249], off
	v_lshl_add_u64 v[248:249], s[28:29], 0, v[162:163]
	s_mov_b32 m0, s59
	s_nop 0
	global_load_lds_dwordx4 v[248:249], off
	s_waitcnt lgkmcnt(0)
	s_waitcnt vmcnt(8)
	s_barrier
	s_setprio 1
	v_mfma_f32_16x16x32_bf16 v[60:63], v[128:131], v[144:147], v[60:63]
	v_mfma_f32_16x16x32_bf16 v[56:59], v[136:139], v[144:147], v[56:59]
	v_mfma_f32_16x16x32_bf16 v[44:47], v[128:131], v[152:155], v[44:47]
	v_mfma_f32_16x16x32_bf16 v[40:43], v[136:139], v[152:155], v[40:43]
	v_mfma_f32_16x16x32_bf16 v[28:31], v[128:131], v[170:173], v[28:31]
	v_mfma_f32_16x16x32_bf16 v[24:27], v[136:139], v[170:173], v[24:27]
	v_mfma_f32_16x16x32_bf16 v[12:15], v[128:131], v[178:181], v[12:15]
	v_mfma_f32_16x16x32_bf16 v[8:11], v[136:139], v[178:181], v[8:11]
	v_mfma_f32_16x16x32_bf16 v[60:63], v[132:135], v[148:151], v[60:63]
	v_mfma_f32_16x16x32_bf16 v[56:59], v[140:143], v[148:151], v[56:59]
	v_mfma_f32_16x16x32_bf16 v[44:47], v[132:135], v[156:159], v[44:47]
	v_mfma_f32_16x16x32_bf16 v[40:43], v[140:143], v[156:159], v[40:43]
	v_mfma_f32_16x16x32_bf16 v[28:31], v[132:135], v[174:177], v[28:31]
	v_mfma_f32_16x16x32_bf16 v[24:27], v[140:143], v[174:177], v[24:27]
	v_mfma_f32_16x16x32_bf16 v[12:15], v[132:135], v[192:195], v[12:15]
	v_mfma_f32_16x16x32_bf16 v[8:11], v[140:143], v[192:195], v[8:11]
	v_mfma_f32_16x16x32_bf16 v[52:55], v[196:199], v[144:147], v[52:55]
	v_mfma_f32_16x16x32_bf16 v[48:51], v[208:211], v[144:147], v[48:51]
	v_mfma_f32_16x16x32_bf16 v[36:39], v[196:199], v[152:155], v[36:39]
	v_mfma_f32_16x16x32_bf16 v[32:35], v[208:211], v[152:155], v[32:35]
	v_mfma_f32_16x16x32_bf16 v[20:23], v[196:199], v[170:173], v[20:23]
	v_mfma_f32_16x16x32_bf16 v[16:19], v[208:211], v[170:173], v[16:19]
	v_mfma_f32_16x16x32_bf16 v[4:7], v[196:199], v[178:181], v[4:7]
	v_mfma_f32_16x16x32_bf16 v[0:3], v[208:211], v[178:181], v[0:3]
	v_mfma_f32_16x16x32_bf16 v[52:55], v[204:207], v[148:151], v[52:55]
	v_mfma_f32_16x16x32_bf16 v[48:51], v[212:215], v[148:151], v[48:51]
	v_mfma_f32_16x16x32_bf16 v[36:39], v[204:207], v[156:159], v[36:39]
	v_mfma_f32_16x16x32_bf16 v[32:35], v[212:215], v[156:159], v[32:35]
	v_mfma_f32_16x16x32_bf16 v[20:23], v[204:207], v[174:177], v[20:23]
	v_mfma_f32_16x16x32_bf16 v[16:19], v[212:215], v[174:177], v[16:19]
	v_mfma_f32_16x16x32_bf16 v[4:7], v[204:207], v[192:195], v[4:7]
	v_mfma_f32_16x16x32_bf16 v[0:3], v[212:215], v[192:195], v[0:3]
	s_setprio 0
	s_add_i32 s40, s40, 2
	s_add_u32 s26, s26, 0x100
	s_addc_u32 s27, s27, 0
	s_add_u32 s38, s38, 0x100
	s_addc_u32 s39, s39, 0
	s_cmp_gt_u32 s40, 13
	s_barrier
	s_cbranch_scc0 .LBB0_883
	v_lshl_or_b32 v128, s65, 8, v185
	v_lshl_add_u32 v170, s24, 8, v184
	v_ashrrev_i32_e32 v129, 31, v128
	v_lshlrev_b64 v[174:175], 1, v[128:129]
	v_ashrrev_i32_e32 v171, 31, v170
	v_lshl_add_u64 v[128:129], s[10:11], 0, v[174:175]
	v_lshlrev_b64 v[204:205], 11, v[170:171]
	v_lshl_add_u64 v[130:131], v[128:129], 0, v[204:205]
	global_load_dwordx4 v[194:197], v[130:131], off
	global_load_dwordx4 v[198:201], v[130:131], off offset:64
	v_or_b32_e32 v130, 16, v170
	v_or_b32_e32 v132, 32, v170
	v_or_b32_e32 v134, 48, v170
	v_ashrrev_i32_e32 v131, 31, v130
	v_ashrrev_i32_e32 v133, 31, v132
	v_ashrrev_i32_e32 v135, 31, v134
	v_lshlrev_b64 v[182:183], 11, v[130:131]
	v_add_u32_e32 v178, 0x80, v170
	v_lshlrev_b64 v[180:181], 11, v[132:133]
	v_lshlrev_b64 v[176:177], 11, v[134:135]
	v_lshl_add_u64 v[132:133], v[128:129], 0, v[182:183]
	v_ashrrev_i32_e32 v179, 31, v178
	v_lshl_add_u64 v[134:135], v[128:129], 0, v[180:181]
	v_lshl_add_u64 v[128:129], v[128:129], 0, v[176:177]
	global_load_dwordx4 v[156:159], v[132:133], off
	global_load_dwordx4 v[152:155], v[132:133], off offset:64
	global_load_dwordx4 v[148:151], v[134:135], off
	global_load_dwordx4 v[144:147], v[134:135], off offset:64
	global_load_dwordx4 v[140:143], v[128:129], off
	global_load_dwordx4 v[136:139], v[128:129], off offset:64
	v_lshlrev_b64 v[130:131], 11, v[178:179]
	v_lshl_add_u64 v[130:131], s[10:11], 0, v[130:131]
	v_lshl_add_u64 v[172:173], v[130:131], 0, v[174:175]
	global_load_dwordx4 v[132:135], v[172:173], off
	global_load_dwordx4 v[128:131], v[172:173], off offset:64
	v_and_b32_e32 v192, 64, v191
	v_xor_b32_e32 v179, 16, v191
	v_add_u32_e32 v192, 64, v192
	v_xor_b32_e32 v193, 32, v191
	v_cmp_lt_i32_e32 vcc, v179, v192
	v_lshl_add_u64 v[204:205], s[10:11], 0, v[204:205]
	v_lshl_add_u64 v[204:205], v[204:205], 0, v[174:175]
	v_cndmask_b32_e32 v179, v191, v179, vcc
	v_cmp_lt_i32_e32 vcc, v193, v192
	v_lshlrev_b32_e32 v192, 2, v179
	s_lshl_b32 s24, s65, 2
	v_cndmask_b32_e32 v193, v191, v193, vcc
	v_lshlrev_b32_e32 v179, 2, v193
	s_or_b32 s27, s24, s53
	s_mul_hi_i32 s26, s27, 0x21000
	s_mul_i32 s27, s27, 0x21000
	s_waitcnt vmcnt(0)
	v_lshlrev_b32_e32 v206, 16, v194
	v_and_b32_e32 v207, 0xffff0000, v194
	v_lshlrev_b32_e32 v194, 16, v195
	v_and_b32_e32 v195, 0xffff0000, v195
	v_lshlrev_b32_e32 v208, 16, v196
	v_and_b32_e32 v209, 0xffff0000, v196
	v_lshlrev_b32_e32 v196, 16, v197
	v_and_b32_e32 v197, 0xffff0000, v197
	v_lshlrev_b32_e32 v212, 16, v200
	v_and_b32_e32 v213, 0xffff0000, v200
	v_lshlrev_b32_e32 v200, 16, v201
	v_and_b32_e32 v201, 0xffff0000, v201
	v_pk_add_f32 v[126:127], v[126:127], v[194:195]
	v_pk_add_f32 v[124:125], v[124:125], v[206:207]
	v_pk_add_f32 v[122:123], v[122:123], v[196:197]
	v_pk_add_f32 v[120:121], v[120:121], v[208:209]
	v_lshlrev_b32_e32 v210, 16, v198
	v_and_b32_e32 v211, 0xffff0000, v198
	v_lshlrev_b32_e32 v198, 16, v199
	v_and_b32_e32 v199, 0xffff0000, v199
	v_pk_add_f32 v[194:195], v[114:115], v[200:201]
	v_pk_add_f32 v[196:197], v[112:113], v[212:213]
	v_cvt_pk_bf16_f32 v112, v124, v125
	v_cvt_pk_bf16_f32 v113, v126, v127
	v_mul_f32_e32 v114, v125, v125
	v_mul_f32_e32 v115, v127, v127
	v_mul_f32_e32 v125, v121, v121
	v_mul_f32_e32 v127, v123, v123
	v_pk_add_f32 v[118:119], v[118:119], v[198:199]
	v_pk_add_f32 v[116:117], v[116:117], v[210:211]
	v_fmac_f32_e32 v114, v124, v124
	v_fmac_f32_e32 v115, v126, v126
	v_fmac_f32_e32 v125, v120, v120
	v_fmac_f32_e32 v127, v122, v122
	v_mul_f32_e32 v193, v117, v117
	v_mul_f32_e32 v198, v119, v119
	v_add_f32_e32 v114, v114, v115
	v_add_f32_e32 v115, v125, v127
	v_mul_f32_e32 v124, v197, v197
	v_mul_f32_e32 v125, v195, v195
	v_fmac_f32_e32 v193, v116, v116
	v_fmac_f32_e32 v198, v118, v118
	v_fmac_f32_e32 v124, v196, v196
	v_fmac_f32_e32 v125, v194, v194
	v_add_f32_e32 v114, v114, v115
	v_add_f32_e32 v115, v193, v198
	v_add_f32_e32 v124, v124, v125
	v_add_f32_e32 v115, v115, v124
	v_add_f32_e32 v124, v114, v115
	ds_bpermute_b32 v125, v192, v124
	v_cvt_pk_bf16_f32 v114, v120, v121
	v_cvt_pk_bf16_f32 v115, v122, v123
	global_store_dwordx4 v[204:205], v[112:115], off
	s_waitcnt lgkmcnt(0)
	s_nop 0
	v_add_f32_e32 v112, v124, v125
	ds_bpermute_b32 v113, v179, v112
	v_cvt_pk_bf16_f32 v114, v116, v117
	v_cvt_pk_bf16_f32 v115, v118, v119
	v_cvt_pk_bf16_f32 v116, v196, v197
	v_cvt_pk_bf16_f32 v117, v194, v195
	global_store_dwordx4 v[204:205], v[114:117], off offset:64
	s_and_saveexec_b64 s[24:25], s[4:5]
	s_cbranch_execz .LBB0_886
	s_add_u32 s28, s51, s27
	s_addc_u32 s29, s52, s26
	s_waitcnt lgkmcnt(0)
	v_add_f32_e32 v114, v112, v113
	v_lshl_add_u64 v[112:113], v[170:171], 2, s[28:29]
	global_store_dword v[112:113], v114, off

.LBB0_972:
	ds_read_b128 v[140:143], v146
	ds_read_b128 v[154:157], v146 offset:1024
	ds_read_b128 v[158:161], v146 offset:2048
	ds_read_b128 v[162:165], v146 offset:3072
	s_add_u32 s28, s26, 0xfffc0080
	s_addc_u32 s29, s27, -1
	s_cmp_eq_u32 s40, 12
	s_cselect_b32 s31, s25, s29
	s_cselect_b32 s30, s34, s28
	s_cselect_b32 s29, s36, s39
	s_cselect_b32 s28, s37, s38
	v_lshl_add_u64 v[198:199], s[26:27], 0, v[134:135]
	s_add_i32 m0, s45, 0xc000
	ds_read_b128 v[166:169], v147
	ds_read_b128 v[170:173], v147 offset:1024
	ds_read_b128 v[174:177], v147 offset:2048
	ds_read_b128 v[178:181], v147 offset:3072
	ds_read_b128 v[182:185], v147 offset:4096
	ds_read_b128 v[186:189], v147 offset:5120
	ds_read_b128 v[190:193], v147 offset:6144
	ds_read_b128 v[194:197], v147 offset:7168
	global_load_lds_dwordx4 v[198:199], off
	v_lshl_add_u64 v[198:199], s[26:27], 0, v[136:137]
	s_add_i32 m0, s45, 0xe000
	s_nop 0
	global_load_lds_dwordx4 v[198:199], off
	ds_read_b128 v[198:201], v148
	ds_read_b128 v[204:207], v148 offset:1024
	ds_read_b128 v[208:211], v148 offset:2048
	ds_read_b128 v[212:215], v148 offset:3072
	s_waitcnt lgkmcnt(0)
	s_waitcnt vmcnt(8)
	s_barrier
	s_setprio 1
	v_mfma_f32_16x16x32_bf16 v[124:127], v[140:143], v[166:169], v[124:127]
	v_mfma_f32_16x16x32_bf16 v[120:123], v[158:161], v[166:169], v[120:123]
	v_mfma_f32_16x16x32_bf16 v[108:111], v[140:143], v[174:177], v[108:111]
	v_mfma_f32_16x16x32_bf16 v[104:107], v[158:161], v[174:177], v[104:107]
	v_mfma_f32_16x16x32_bf16 v[92:95], v[140:143], v[182:185], v[92:95]
	v_mfma_f32_16x16x32_bf16 v[88:91], v[158:161], v[182:185], v[88:91]
	v_mfma_f32_16x16x32_bf16 v[76:79], v[140:143], v[190:193], v[76:79]
	v_mfma_f32_16x16x32_bf16 v[72:75], v[158:161], v[190:193], v[72:75]
	v_mfma_f32_16x16x32_bf16 v[124:127], v[154:157], v[170:173], v[124:127]
	v_mfma_f32_16x16x32_bf16 v[120:123], v[162:165], v[170:173], v[120:123]
	v_mfma_f32_16x16x32_bf16 v[108:111], v[154:157], v[178:181], v[108:111]
	v_mfma_f32_16x16x32_bf16 v[104:107], v[162:165], v[178:181], v[104:107]
	v_mfma_f32_16x16x32_bf16 v[92:95], v[154:157], v[186:189], v[92:95]
	v_mfma_f32_16x16x32_bf16 v[88:91], v[162:165], v[186:189], v[88:91]
	v_mfma_f32_16x16x32_bf16 v[76:79], v[154:157], v[194:197], v[76:79]
	v_mfma_f32_16x16x32_bf16 v[72:75], v[162:165], v[194:197], v[72:75]
	v_mfma_f32_16x16x32_bf16 v[116:119], v[198:201], v[166:169], v[116:119]
	v_mfma_f32_16x16x32_bf16 v[112:115], v[208:211], v[166:169], v[112:115]
	v_mfma_f32_16x16x32_bf16 v[100:103], v[198:201], v[174:177], v[100:103]
	v_mfma_f32_16x16x32_bf16 v[96:99], v[208:211], v[174:177], v[96:99]
	v_mfma_f32_16x16x32_bf16 v[84:87], v[198:201], v[182:185], v[84:87]
	v_mfma_f32_16x16x32_bf16 v[80:83], v[208:211], v[182:185], v[80:83]
	v_mfma_f32_16x16x32_bf16 v[68:71], v[198:201], v[190:193], v[68:71]
	v_mfma_f32_16x16x32_bf16 v[64:67], v[208:211], v[190:193], v[64:67]
	v_mfma_f32_16x16x32_bf16 v[116:119], v[204:207], v[170:173], v[116:119]
	v_mfma_f32_16x16x32_bf16 v[112:115], v[212:215], v[170:173], v[112:115]
	v_mfma_f32_16x16x32_bf16 v[100:103], v[204:207], v[178:181], v[100:103]
	v_mfma_f32_16x16x32_bf16 v[96:99], v[212:215], v[178:181], v[96:99]
	v_mfma_f32_16x16x32_bf16 v[84:87], v[204:207], v[186:189], v[84:87]
	v_mfma_f32_16x16x32_bf16 v[80:83], v[212:215], v[186:189], v[80:83]
	v_mfma_f32_16x16x32_bf16 v[68:71], v[204:207], v[194:197], v[68:71]
	v_mfma_f32_16x16x32_bf16 v[64:67], v[212:215], v[194:197], v[64:67]
	s_setprio 0
	s_barrier
	ds_read_b128 v[166:169], v147 offset:16384
	ds_read_b128 v[170:173], v147 offset:17408
	ds_read_b128 v[174:177], v147 offset:18432
	ds_read_b128 v[178:181], v147 offset:19456
	ds_read_b128 v[182:185], v147 offset:20480
	ds_read_b128 v[186:189], v147 offset:21504
	ds_read_b128 v[190:193], v147 offset:22528
	ds_read_b128 v[194:197], v147 offset:23552
	s_mov_b32 m0, s43
	v_lshl_add_u64 v[216:217], s[28:29], 0, v[128:129]
	global_load_lds_dwordx4 v[216:217], off
	v_lshl_add_u64 v[218:219], s[28:29], 0, v[130:131]
	s_mov_b32 m0, s44
	s_nop 0
	global_load_lds_dwordx4 v[218:219], off
	s_mov_b32 m0, s45
	v_lshl_add_u64 v[220:221], s[30:31], 0, v[128:129]
	global_load_lds_dwordx4 v[220:221], off
	v_lshl_add_u64 v[222:223], s[30:31], 0, v[130:131]
	s_mov_b32 m0, s46
	s_nop 0
	global_load_lds_dwordx4 v[222:223], off
	s_add_u32 s70, s28, 0x40000
	s_addc_u32 s71, s29, 0
	s_mov_b32 m0, s47
	v_lshl_add_u64 v[248:249], s[70:71], 0, v[128:129]
	global_load_lds_dwordx4 v[248:249], off
	v_lshl_add_u64 v[248:249], s[70:71], 0, v[130:131]
	s_mov_b32 m0, s48
	s_nop 0
	global_load_lds_dwordx4 v[248:249], off
	s_waitcnt lgkmcnt(0)
	s_waitcnt vmcnt(8)
	s_barrier
	s_setprio 1
	v_mfma_f32_16x16x32_bf16 v[60:63], v[140:143], v[166:169], v[60:63]
	v_mfma_f32_16x16x32_bf16 v[56:59], v[158:161], v[166:169], v[56:59]
	v_mfma_f32_16x16x32_bf16 v[44:47], v[140:143], v[174:177], v[44:47]
	v_mfma_f32_16x16x32_bf16 v[40:43], v[158:161], v[174:177], v[40:43]
	v_mfma_f32_16x16x32_bf16 v[28:31], v[140:143], v[182:185], v[28:31]
	v_mfma_f32_16x16x32_bf16 v[24:27], v[158:161], v[182:185], v[24:27]
	v_mfma_f32_16x16x32_bf16 v[12:15], v[140:143], v[190:193], v[12:15]
	v_mfma_f32_16x16x32_bf16 v[8:11], v[158:161], v[190:193], v[8:11]
	v_mfma_f32_16x16x32_bf16 v[60:63], v[154:157], v[170:173], v[60:63]
	v_mfma_f32_16x16x32_bf16 v[56:59], v[162:165], v[170:173], v[56:59]
	v_mfma_f32_16x16x32_bf16 v[44:47], v[154:157], v[178:181], v[44:47]
	v_mfma_f32_16x16x32_bf16 v[40:43], v[162:165], v[178:181], v[40:43]
	v_mfma_f32_16x16x32_bf16 v[28:31], v[154:157], v[186:189], v[28:31]
	v_mfma_f32_16x16x32_bf16 v[24:27], v[162:165], v[186:189], v[24:27]
	v_mfma_f32_16x16x32_bf16 v[12:15], v[154:157], v[194:197], v[12:15]
	v_mfma_f32_16x16x32_bf16 v[8:11], v[162:165], v[194:197], v[8:11]
	v_mfma_f32_16x16x32_bf16 v[52:55], v[198:201], v[166:169], v[52:55]
	v_mfma_f32_16x16x32_bf16 v[48:51], v[208:211], v[166:169], v[48:51]
	v_mfma_f32_16x16x32_bf16 v[36:39], v[198:201], v[174:177], v[36:39]
	v_mfma_f32_16x16x32_bf16 v[32:35], v[208:211], v[174:177], v[32:35]
	v_mfma_f32_16x16x32_bf16 v[20:23], v[198:201], v[182:185], v[20:23]
	v_mfma_f32_16x16x32_bf16 v[16:19], v[208:211], v[182:185], v[16:19]
	v_mfma_f32_16x16x32_bf16 v[4:7], v[198:201], v[190:193], v[4:7]
	v_mfma_f32_16x16x32_bf16 v[0:3], v[208:211], v[190:193], v[0:3]
	v_mfma_f32_16x16x32_bf16 v[52:55], v[204:207], v[170:173], v[52:55]
	v_mfma_f32_16x16x32_bf16 v[48:51], v[212:215], v[170:173], v[48:51]
	v_mfma_f32_16x16x32_bf16 v[36:39], v[204:207], v[178:181], v[36:39]
	v_mfma_f32_16x16x32_bf16 v[32:35], v[212:215], v[178:181], v[32:35]
	v_mfma_f32_16x16x32_bf16 v[20:23], v[204:207], v[186:189], v[20:23]
	v_mfma_f32_16x16x32_bf16 v[16:19], v[212:215], v[186:189], v[16:19]
	v_mfma_f32_16x16x32_bf16 v[4:7], v[204:207], v[194:197], v[4:7]
	v_mfma_f32_16x16x32_bf16 v[0:3], v[212:215], v[194:197], v[0:3]
	s_setprio 0
	s_barrier
	ds_read_b128 v[140:143], v149
	ds_read_b128 v[154:157], v149 offset:1024
	ds_read_b128 v[158:161], v149 offset:2048
	ds_read_b128 v[162:165], v149 offset:3072
	s_add_u32 s30, s30, 0x40000
	s_addc_u32 s31, s31, 0
	s_mov_b32 m0, s49
	v_lshl_add_u64 v[198:199], s[30:31], 0, v[128:129]
	ds_read_b128 v[166:169], v147 offset:32768
	ds_read_b128 v[170:173], v147 offset:33792
	ds_read_b128 v[174:177], v147 offset:34816
	ds_read_b128 v[178:181], v147 offset:35840
	ds_read_b128 v[182:185], v147 offset:36864
	ds_read_b128 v[186:189], v147 offset:37888
	ds_read_b128 v[190:193], v147 offset:38912
	ds_read_b128 v[194:197], v147 offset:39936
	global_load_lds_dwordx4 v[198:199], off
	v_lshl_add_u64 v[198:199], s[30:31], 0, v[130:131]
	s_mov_b32 m0, s50
	s_nop 0
	global_load_lds_dwordx4 v[198:199], off
	ds_read_b128 v[198:201], v150
	ds_read_b128 v[204:207], v150 offset:1024
	ds_read_b128 v[208:211], v150 offset:2048
	ds_read_b128 v[212:215], v150 offset:3072
	s_waitcnt lgkmcnt(0)
	s_waitcnt vmcnt(8)
	s_barrier
	s_setprio 1
	v_mfma_f32_16x16x32_bf16 v[124:127], v[140:143], v[166:169], v[124:127]
	v_mfma_f32_16x16x32_bf16 v[120:123], v[158:161], v[166:169], v[120:123]
	v_mfma_f32_16x16x32_bf16 v[108:111], v[140:143], v[174:177], v[108:111]
	v_mfma_f32_16x16x32_bf16 v[104:107], v[158:161], v[174:177], v[104:107]
	v_mfma_f32_16x16x32_bf16 v[92:95], v[140:143], v[182:185], v[92:95]
	v_mfma_f32_16x16x32_bf16 v[88:91], v[158:161], v[182:185], v[88:91]
	v_mfma_f32_16x16x32_bf16 v[76:79], v[140:143], v[190:193], v[76:79]
	v_mfma_f32_16x16x32_bf16 v[72:75], v[158:161], v[190:193], v[72:75]
	v_mfma_f32_16x16x32_bf16 v[124:127], v[154:157], v[170:173], v[124:127]
	v_mfma_f32_16x16x32_bf16 v[120:123], v[162:165], v[170:173], v[120:123]
	v_mfma_f32_16x16x32_bf16 v[108:111], v[154:157], v[178:181], v[108:111]
	v_mfma_f32_16x16x32_bf16 v[104:107], v[162:165], v[178:181], v[104:107]
	v_mfma_f32_16x16x32_bf16 v[92:95], v[154:157], v[186:189], v[92:95]
	v_mfma_f32_16x16x32_bf16 v[88:91], v[162:165], v[186:189], v[88:91]
	v_mfma_f32_16x16x32_bf16 v[76:79], v[154:157], v[194:197], v[76:79]
	v_mfma_f32_16x16x32_bf16 v[72:75], v[162:165], v[194:197], v[72:75]
	v_mfma_f32_16x16x32_bf16 v[116:119], v[198:201], v[166:169], v[116:119]
	v_mfma_f32_16x16x32_bf16 v[112:115], v[208:211], v[166:169], v[112:115]
	v_mfma_f32_16x16x32_bf16 v[100:103], v[198:201], v[174:177], v[100:103]
	v_mfma_f32_16x16x32_bf16 v[96:99], v[208:211], v[174:177], v[96:99]
	v_mfma_f32_16x16x32_bf16 v[84:87], v[198:201], v[182:185], v[84:87]
	v_mfma_f32_16x16x32_bf16 v[80:83], v[208:211], v[182:185], v[80:83]
	v_mfma_f32_16x16x32_bf16 v[68:71], v[198:201], v[190:193], v[68:71]
	v_mfma_f32_16x16x32_bf16 v[64:67], v[208:211], v[190:193], v[64:67]
	v_mfma_f32_16x16x32_bf16 v[116:119], v[204:207], v[170:173], v[116:119]
	v_mfma_f32_16x16x32_bf16 v[112:115], v[212:215], v[170:173], v[112:115]
	v_mfma_f32_16x16x32_bf16 v[100:103], v[204:207], v[178:181], v[100:103]
	v_mfma_f32_16x16x32_bf16 v[96:99], v[212:215], v[178:181], v[96:99]
	v_mfma_f32_16x16x32_bf16 v[84:87], v[204:207], v[186:189], v[84:87]
	v_mfma_f32_16x16x32_bf16 v[80:83], v[212:215], v[186:189], v[80:83]
	v_mfma_f32_16x16x32_bf16 v[68:71], v[204:207], v[194:197], v[68:71]
	v_mfma_f32_16x16x32_bf16 v[64:67], v[212:215], v[194:197], v[64:67]
	s_setprio 0
	s_barrier
	ds_read_b128 v[166:169], v147 offset:49152
	ds_read_b128 v[170:173], v147 offset:50176
	ds_read_b128 v[174:177], v147 offset:51200
	ds_read_b128 v[178:181], v147 offset:52224
	ds_read_b128 v[182:185], v147 offset:53248
	ds_read_b128 v[186:189], v147 offset:54272
	ds_read_b128 v[190:193], v147 offset:55296
	ds_read_b128 v[194:197], v147 offset:56320
	s_mov_b32 m0, s54
	v_lshl_add_u64 v[216:217], v[216:217], 0, s[12:13]
	global_load_lds_dwordx4 v[216:217], off
	v_lshl_add_u64 v[216:217], v[218:219], 0, s[12:13]
	s_mov_b32 m0, s55
	s_nop 0
	global_load_lds_dwordx4 v[216:217], off
	s_mov_b32 m0, s56
	v_lshl_add_u64 v[216:217], v[220:221], 0, s[12:13]
	global_load_lds_dwordx4 v[216:217], off
	v_lshl_add_u64 v[216:217], v[222:223], 0, s[12:13]
	s_mov_b32 m0, s57
	s_nop 0
	global_load_lds_dwordx4 v[216:217], off
	s_add_u32 s28, s28, 0x40080
	s_addc_u32 s29, s29, 0
	s_mov_b32 m0, s58
	v_lshl_add_u64 v[248:249], s[28:29], 0, v[128:129]
	global_load_lds_dwordx4 v[248:249], off
	v_lshl_add_u64 v[248:249], s[28:29], 0, v[130:131]
	s_mov_b32 m0, s59
	s_nop 0
	global_load_lds_dwordx4 v[248:249], off
	s_waitcnt lgkmcnt(0)
	s_waitcnt vmcnt(8)
	s_barrier
	s_setprio 1
	v_mfma_f32_16x16x32_bf16 v[60:63], v[140:143], v[166:169], v[60:63]
	v_mfma_f32_16x16x32_bf16 v[56:59], v[158:161], v[166:169], v[56:59]
	v_mfma_f32_16x16x32_bf16 v[44:47], v[140:143], v[174:177], v[44:47]
	v_mfma_f32_16x16x32_bf16 v[40:43], v[158:161], v[174:177], v[40:43]
	v_mfma_f32_16x16x32_bf16 v[28:31], v[140:143], v[182:185], v[28:31]
	v_mfma_f32_16x16x32_bf16 v[24:27], v[158:161], v[182:185], v[24:27]
	v_mfma_f32_16x16x32_bf16 v[12:15], v[140:143], v[190:193], v[12:15]
	v_mfma_f32_16x16x32_bf16 v[8:11], v[158:161], v[190:193], v[8:11]
	v_mfma_f32_16x16x32_bf16 v[60:63], v[154:157], v[170:173], v[60:63]
	v_mfma_f32_16x16x32_bf16 v[56:59], v[162:165], v[170:173], v[56:59]
	v_mfma_f32_16x16x32_bf16 v[44:47], v[154:157], v[178:181], v[44:47]
	v_mfma_f32_16x16x32_bf16 v[40:43], v[162:165], v[178:181], v[40:43]
	v_mfma_f32_16x16x32_bf16 v[28:31], v[154:157], v[186:189], v[28:31]
	v_mfma_f32_16x16x32_bf16 v[24:27], v[162:165], v[186:189], v[24:27]
	v_mfma_f32_16x16x32_bf16 v[12:15], v[154:157], v[194:197], v[12:15]
	v_mfma_f32_16x16x32_bf16 v[8:11], v[162:165], v[194:197], v[8:11]
	v_mfma_f32_16x16x32_bf16 v[52:55], v[198:201], v[166:169], v[52:55]
	v_mfma_f32_16x16x32_bf16 v[48:51], v[208:211], v[166:169], v[48:51]
	v_mfma_f32_16x16x32_bf16 v[36:39], v[198:201], v[174:177], v[36:39]
	v_mfma_f32_16x16x32_bf16 v[32:35], v[208:211], v[174:177], v[32:35]
	v_mfma_f32_16x16x32_bf16 v[20:23], v[198:201], v[182:185], v[20:23]
	v_mfma_f32_16x16x32_bf16 v[16:19], v[208:211], v[182:185], v[16:19]
	v_mfma_f32_16x16x32_bf16 v[4:7], v[198:201], v[190:193], v[4:7]
	v_mfma_f32_16x16x32_bf16 v[0:3], v[208:211], v[190:193], v[0:3]
	v_mfma_f32_16x16x32_bf16 v[52:55], v[204:207], v[170:173], v[52:55]
	v_mfma_f32_16x16x32_bf16 v[48:51], v[212:215], v[170:173], v[48:51]
	v_mfma_f32_16x16x32_bf16 v[36:39], v[204:207], v[178:181], v[36:39]
	v_mfma_f32_16x16x32_bf16 v[32:35], v[212:215], v[178:181], v[32:35]
	v_mfma_f32_16x16x32_bf16 v[20:23], v[204:207], v[186:189], v[20:23]
	v_mfma_f32_16x16x32_bf16 v[16:19], v[212:215], v[186:189], v[16:19]
	v_mfma_f32_16x16x32_bf16 v[4:7], v[204:207], v[194:197], v[4:7]
	v_mfma_f32_16x16x32_bf16 v[0:3], v[212:215], v[194:197], v[0:3]
	s_setprio 0
	s_add_i32 s40, s40, 2
	s_add_u32 s26, s26, 0x100
	s_addc_u32 s27, s27, 0
	s_add_u32 s38, s38, 0x100
	s_addc_u32 s39, s39, 0
	s_cmp_gt_u32 s40, 13
	s_barrier
	s_cbranch_scc0 .LBB0_972
	v_lshl_add_u32 v140, s24, 8, v144
	v_ashrrev_i32_e32 v141, 31, v140
	v_lshl_add_u64 v[142:143], v[140:141], 2, v[132:133]
	v_add_co_u32_e32 v154, vcc, s60, v142
	v_xor_b32_e32 v153, 16, v151
	s_nop 0
	v_addc_co_u32_e32 v155, vcc, 0, v143, vcc
	v_add_co_u32_e32 v156, vcc, s65, v142
	s_lshl_b32 s24, s68, 2
	s_nop 0
	v_addc_co_u32_e32 v157, vcc, 0, v143, vcc
	v_add_co_u32_e32 v158, vcc, s66, v142
	s_or_b32 s27, s24, s53
	s_nop 0
	v_addc_co_u32_e32 v159, vcc, 0, v143, vcc
	global_load_dword v160, v[142:143], off
	global_load_dword v162, v[142:143], off offset:64
	global_load_dword v163, v[142:143], off offset:128
	global_load_dword v164, v[142:143], off offset:192
	global_load_dword v165, v[142:143], off offset:512
	global_load_dword v166, v[142:143], off offset:576
	global_load_dword v167, v[142:143], off offset:640
	global_load_dword v168, v[142:143], off offset:704
	s_nop 0
	global_load_dword v142, v[154:155], off
	global_load_dword v169, v[154:155], off offset:64
	global_load_dword v170, v[154:155], off offset:128
	global_load_dword v171, v[154:155], off offset:192
	global_load_dword v172, v[154:155], off offset:512
	global_load_dword v173, v[154:155], off offset:576
	global_load_dword v174, v[154:155], off offset:640
	s_nop 0
	global_load_dword v155, v[154:155], off offset:704
	s_nop 0
	global_load_dword v161, v[156:157], off
	global_load_dword v175, v[156:157], off offset:64
	global_load_dword v176, v[156:157], off offset:128
	global_load_dword v177, v[156:157], off offset:192
	global_load_dword v178, v[156:157], off offset:512
	global_load_dword v179, v[156:157], off offset:576
	global_load_dword v180, v[156:157], off offset:640
	s_nop 0
	global_load_dword v156, v[156:157], off offset:704
	s_nop 0
	global_load_dword v143, v[158:159], off
	global_load_dword v157, v[158:159], off offset:64
	global_load_dword v181, v[158:159], off offset:128
	global_load_dword v182, v[158:159], off offset:192
	global_load_dword v183, v[158:159], off offset:512
	global_load_dword v184, v[158:159], off offset:576
	global_load_dword v185, v[158:159], off offset:640
	s_nop 0
	global_load_dword v158, v[158:159], off offset:704
	v_and_b32_e32 v154, 64, v151
	v_add_u32_e32 v154, 64, v154
	v_xor_b32_e32 v159, 32, v151
	v_cmp_lt_i32_e32 vcc, v153, v154
	s_mul_hi_i32 s26, s27, 0x21000
	s_mul_i32 s27, s27, 0x21000
	v_cndmask_b32_e32 v153, v151, v153, vcc
	v_cmp_lt_i32_e32 vcc, v159, v154
	v_lshlrev_b32_e32 v154, 2, v153
	s_waitcnt vmcnt(0)
	v_add_f32_e32 v155, v168, v155
	v_cndmask_b32_e32 v159, v151, v159, vcc
	v_lshlrev_b32_e32 v153, 2, v159
	v_add_f32_e32 v159, v162, v169
	v_add_f32_e32 v162, v163, v170
	v_add_f32_e32 v163, v164, v171
	v_add_f32_e32 v164, v165, v172
	v_add_f32_e32 v165, v166, v173
	v_add_f32_e32 v166, v167, v174
	v_pk_add_f32 v[142:143], v[160:161], v[142:143]
	v_add_f32_e32 v157, v175, v157
	v_add_f32_e32 v142, v142, v143
	v_add_f32_e32 v161, v177, v182
	v_add_f32_e32 v143, v159, v157
	v_add_f32_e32 v167, v178, v183
	v_add_f32_e32 v159, v164, v167
	v_add_f32_e32 v156, v156, v158
	v_add_f32_e32 v155, v155, v156
	ds_bpermute_b32 v156, v154, v142
	v_add_f32_e32 v158, v163, v161
	ds_bpermute_b32 v161, v154, v143
	v_add_f32_e32 v160, v176, v181
	v_add_f32_e32 v168, v179, v184
	s_waitcnt lgkmcnt(0)
	v_add_f32_e32 v142, v142, v156
	v_add_f32_e32 v169, v180, v185
	v_add_f32_e32 v167, v143, v161
	ds_bpermute_b32 v143, v153, v142
	v_add_f32_e32 v157, v162, v160
	v_add_f32_e32 v160, v165, v168
	v_add_f32_e32 v169, v166, v169
	ds_bpermute_b32 v171, v154, v160
	s_waitcnt lgkmcnt(1)
	v_add_f32_e32 v142, v142, v143
	v_fmamk_f32 v142, v142, 0x3a800000, v152
	ds_bpermute_b32 v162, v154, v157
	ds_bpermute_b32 v164, v154, v159
	ds_bpermute_b32 v172, v154, v169
	v_rsq_f32_e32 v170, v142
	ds_bpermute_b32 v142, v154, v155
	s_waitcnt lgkmcnt(3)
	v_add_f32_e32 v165, v157, v162
	s_waitcnt lgkmcnt(2)
	v_add_f32_e32 v161, v159, v164
	v_pk_mul_f32 v[126:127], v[126:127], v[170:171] op_sel_hi:[1,0]
	v_pk_mul_f32 v[124:125], v[124:125], v[170:171] op_sel_hi:[1,0]
	v_add_f32_e32 v159, v160, v171
	s_waitcnt lgkmcnt(1)
	v_add_f32_e32 v157, v169, v172
	s_waitcnt lgkmcnt(0)
	v_add_f32_e32 v155, v155, v142
	v_lshl_or_b32 v142, s68, 8, v145
	v_pk_mul_f32 v[122:123], v[122:123], v[170:171] op_sel_hi:[1,0]
	v_pk_mul_f32 v[120:121], v[120:121], v[170:171] op_sel_hi:[1,0]
	v_pk_mul_f32 v[118:119], v[118:119], v[170:171] op_sel_hi:[1,0]
	v_pk_mul_f32 v[116:117], v[116:117], v[170:171] op_sel_hi:[1,0]
	v_pk_mul_f32 v[172:173], v[114:115], v[170:171] op_sel_hi:[1,0]
	v_pk_mul_f32 v[170:171], v[112:113], v[170:171] op_sel_hi:[1,0]
	v_lshlrev_b64 v[112:113], 10, v[140:141]
	v_mul_f32_e32 v114, v125, v125
	v_mul_f32_e32 v115, v127, v127
	v_ashrrev_i32_e32 v143, 31, v142
	v_lshl_add_u64 v[112:113], s[10:11], 0, v[112:113]
	v_fmac_f32_e32 v114, v124, v124
	v_fmac_f32_e32 v115, v126, v126
	v_lshl_add_u64 v[174:175], v[142:143], 1, v[112:113]
	v_cvt_pk_bf16_f32 v112, v124, v125
	v_add_f32_e32 v114, v114, v115
	v_mul_f32_e32 v115, v121, v121
	v_mul_f32_e32 v124, v123, v123
	v_fmac_f32_e32 v115, v120, v120
	v_fmac_f32_e32 v124, v122, v122
	v_add_f32_e32 v115, v115, v124
	v_add_f32_e32 v114, v114, v115
	v_mul_f32_e32 v115, v117, v117
	v_mul_f32_e32 v124, v119, v119
	v_fmac_f32_e32 v115, v116, v116
	v_fmac_f32_e32 v124, v118, v118
	v_add_f32_e32 v115, v115, v124
	v_mul_f32_e32 v124, v171, v171
	v_mul_f32_e32 v125, v173, v173
	v_fmac_f32_e32 v124, v170, v170
	v_fmac_f32_e32 v125, v172, v172
	v_add_f32_e32 v124, v124, v125
	v_add_f32_e32 v115, v115, v124
	v_add_f32_e32 v124, v114, v115
	ds_bpermute_b32 v163, v154, v158
	ds_bpermute_b32 v125, v154, v124
	v_cvt_pk_bf16_f32 v113, v126, v127
	v_cvt_pk_bf16_f32 v114, v120, v121
	v_cvt_pk_bf16_f32 v115, v122, v123
	s_waitcnt lgkmcnt(1)
	v_add_f32_e32 v163, v158, v163
	global_store_dwordx4 v[174:175], v[112:115], off
	ds_bpermute_b32 v168, v153, v167
	ds_bpermute_b32 v166, v153, v165
	s_waitcnt lgkmcnt(2)
	v_add_f32_e32 v112, v124, v125
	ds_bpermute_b32 v164, v153, v163
	ds_bpermute_b32 v162, v153, v161
	ds_bpermute_b32 v160, v153, v159
	ds_bpermute_b32 v158, v153, v157
	ds_bpermute_b32 v156, v153, v155
	ds_bpermute_b32 v113, v153, v112
	v_cvt_pk_bf16_f32 v114, v116, v117
	v_cvt_pk_bf16_f32 v115, v118, v119
	v_cvt_pk_bf16_f32 v116, v170, v171
	v_cvt_pk_bf16_f32 v117, v172, v173
	global_store_dwordx4 v[174:175], v[114:117], off offset:64
	s_and_saveexec_b64 s[24:25], s[4:5]
	s_cbranch_execz .LBB0_975
	s_add_u32 s28, s51, s27
	s_addc_u32 s29, s52, s26
	v_lshl_add_u64 v[114:115], v[140:141], 2, s[28:29]
	s_waitcnt lgkmcnt(0)
	v_add_f32_e32 v112, v112, v113
	global_store_dword v[114:115], v112, off

.LBB0_1128:
	ds_read_b128 v[128:131], v186
	ds_read_b128 v[132:135], v186 offset:1024
	ds_read_b128 v[136:139], v186 offset:2048
	ds_read_b128 v[140:143], v186 offset:3072
	s_add_u32 s26, s24, 0xfffe0080
	s_addc_u32 s27, s25, -1
	s_cmp_eq_u32 s38, 4
	s_cselect_b32 s29, s19, s27
	s_cselect_b32 s28, s30, s26
	s_cselect_b32 s27, s34, s37
	s_cselect_b32 s26, s35, s36
	v_lshl_add_u64 v[182:183], s[24:25], 0, v[164:165]
	s_add_i32 m0, s42, 0xc000
	ds_read_b128 v[144:147], v187
	ds_read_b128 v[148:151], v187 offset:1024
	ds_read_b128 v[152:155], v187 offset:2048
	ds_read_b128 v[156:159], v187 offset:3072
	ds_read_b128 v[170:173], v187 offset:4096
	ds_read_b128 v[174:177], v187 offset:5120
	ds_read_b128 v[178:181], v187 offset:6144
	ds_read_b128 v[192:195], v187 offset:7168
	global_load_lds_dwordx4 v[182:183], off
	v_lshl_add_u64 v[182:183], s[24:25], 0, v[166:167]
	s_add_i32 m0, s42, 0xe000
	s_nop 0
	global_load_lds_dwordx4 v[182:183], off
	ds_read_b128 v[196:199], v188
	ds_read_b128 v[204:207], v188 offset:1024
	ds_read_b128 v[208:211], v188 offset:2048
	ds_read_b128 v[212:215], v188 offset:3072
	s_waitcnt lgkmcnt(0)
	s_waitcnt vmcnt(8)
	s_barrier
	s_setprio 1
	v_mfma_f32_16x16x32_bf16 v[124:127], v[128:131], v[144:147], v[124:127]
	v_mfma_f32_16x16x32_bf16 v[120:123], v[136:139], v[144:147], v[120:123]
	v_mfma_f32_16x16x32_bf16 v[108:111], v[128:131], v[152:155], v[108:111]
	v_mfma_f32_16x16x32_bf16 v[104:107], v[136:139], v[152:155], v[104:107]
	v_mfma_f32_16x16x32_bf16 v[92:95], v[128:131], v[170:173], v[92:95]
	v_mfma_f32_16x16x32_bf16 v[88:91], v[136:139], v[170:173], v[88:91]
	v_mfma_f32_16x16x32_bf16 v[76:79], v[128:131], v[178:181], v[76:79]
	v_mfma_f32_16x16x32_bf16 v[72:75], v[136:139], v[178:181], v[72:75]
	v_mfma_f32_16x16x32_bf16 v[124:127], v[132:135], v[148:151], v[124:127]
	v_mfma_f32_16x16x32_bf16 v[120:123], v[140:143], v[148:151], v[120:123]
	v_mfma_f32_16x16x32_bf16 v[108:111], v[132:135], v[156:159], v[108:111]
	v_mfma_f32_16x16x32_bf16 v[104:107], v[140:143], v[156:159], v[104:107]
	v_mfma_f32_16x16x32_bf16 v[92:95], v[132:135], v[174:177], v[92:95]
	v_mfma_f32_16x16x32_bf16 v[88:91], v[140:143], v[174:177], v[88:91]
	v_mfma_f32_16x16x32_bf16 v[76:79], v[132:135], v[192:195], v[76:79]
	v_mfma_f32_16x16x32_bf16 v[72:75], v[140:143], v[192:195], v[72:75]
	v_mfma_f32_16x16x32_bf16 v[116:119], v[196:199], v[144:147], v[116:119]
	v_mfma_f32_16x16x32_bf16 v[112:115], v[208:211], v[144:147], v[112:115]
	v_mfma_f32_16x16x32_bf16 v[100:103], v[196:199], v[152:155], v[100:103]
	v_mfma_f32_16x16x32_bf16 v[96:99], v[208:211], v[152:155], v[96:99]
	v_mfma_f32_16x16x32_bf16 v[84:87], v[196:199], v[170:173], v[84:87]
	v_mfma_f32_16x16x32_bf16 v[80:83], v[208:211], v[170:173], v[80:83]
	v_mfma_f32_16x16x32_bf16 v[68:71], v[196:199], v[178:181], v[68:71]
	v_mfma_f32_16x16x32_bf16 v[64:67], v[208:211], v[178:181], v[64:67]
	v_mfma_f32_16x16x32_bf16 v[116:119], v[204:207], v[148:151], v[116:119]
	v_mfma_f32_16x16x32_bf16 v[112:115], v[212:215], v[148:151], v[112:115]
	v_mfma_f32_16x16x32_bf16 v[100:103], v[204:207], v[156:159], v[100:103]
	v_mfma_f32_16x16x32_bf16 v[96:99], v[212:215], v[156:159], v[96:99]
	v_mfma_f32_16x16x32_bf16 v[84:87], v[204:207], v[174:177], v[84:87]
	v_mfma_f32_16x16x32_bf16 v[80:83], v[212:215], v[174:177], v[80:83]
	v_mfma_f32_16x16x32_bf16 v[68:71], v[204:207], v[192:195], v[68:71]
	v_mfma_f32_16x16x32_bf16 v[64:67], v[212:215], v[192:195], v[64:67]
	s_setprio 0
	s_barrier
	ds_read_b128 v[144:147], v187 offset:16384
	ds_read_b128 v[148:151], v187 offset:17408
	ds_read_b128 v[152:155], v187 offset:18432
	ds_read_b128 v[156:159], v187 offset:19456
	ds_read_b128 v[170:173], v187 offset:20480
	ds_read_b128 v[174:177], v187 offset:21504
	ds_read_b128 v[178:181], v187 offset:22528
	ds_read_b128 v[192:195], v187 offset:23552
	s_mov_b32 m0, s40
	v_lshl_add_u64 v[182:183], s[26:27], 0, v[160:161]
	global_load_lds_dwordx4 v[182:183], off
	v_lshl_add_u64 v[200:201], s[26:27], 0, v[162:163]
	s_mov_b32 m0, s41
	s_nop 0
	global_load_lds_dwordx4 v[200:201], off
	s_mov_b32 m0, s42
	v_lshl_add_u64 v[216:217], s[28:29], 0, v[160:161]
	global_load_lds_dwordx4 v[216:217], off
	v_lshl_add_u64 v[218:219], s[28:29], 0, v[162:163]
	s_mov_b32 m0, s43
	s_nop 0
	global_load_lds_dwordx4 v[218:219], off
	s_add_u32 s64, s26, 0x20000
	s_addc_u32 s65, s27, 0
	s_mov_b32 m0, s44
	v_lshl_add_u64 v[248:249], s[64:65], 0, v[160:161]
	global_load_lds_dwordx4 v[248:249], off
	v_lshl_add_u64 v[248:249], s[64:65], 0, v[162:163]
	s_mov_b32 m0, s45
	s_nop 0
	global_load_lds_dwordx4 v[248:249], off
	s_waitcnt lgkmcnt(0)
	s_waitcnt vmcnt(8)
	s_barrier
	s_setprio 1
	v_mfma_f32_16x16x32_bf16 v[60:63], v[128:131], v[144:147], v[60:63]
	v_mfma_f32_16x16x32_bf16 v[56:59], v[136:139], v[144:147], v[56:59]
	v_mfma_f32_16x16x32_bf16 v[44:47], v[128:131], v[152:155], v[44:47]
	v_mfma_f32_16x16x32_bf16 v[40:43], v[136:139], v[152:155], v[40:43]
	v_mfma_f32_16x16x32_bf16 v[28:31], v[128:131], v[170:173], v[28:31]
	v_mfma_f32_16x16x32_bf16 v[24:27], v[136:139], v[170:173], v[24:27]
	v_mfma_f32_16x16x32_bf16 v[12:15], v[128:131], v[178:181], v[12:15]
	v_mfma_f32_16x16x32_bf16 v[8:11], v[136:139], v[178:181], v[8:11]
	v_mfma_f32_16x16x32_bf16 v[60:63], v[132:135], v[148:151], v[60:63]
	v_mfma_f32_16x16x32_bf16 v[56:59], v[140:143], v[148:151], v[56:59]
	v_mfma_f32_16x16x32_bf16 v[44:47], v[132:135], v[156:159], v[44:47]
	v_mfma_f32_16x16x32_bf16 v[40:43], v[140:143], v[156:159], v[40:43]
	v_mfma_f32_16x16x32_bf16 v[28:31], v[132:135], v[174:177], v[28:31]
	v_mfma_f32_16x16x32_bf16 v[24:27], v[140:143], v[174:177], v[24:27]
	v_mfma_f32_16x16x32_bf16 v[12:15], v[132:135], v[192:195], v[12:15]
	v_mfma_f32_16x16x32_bf16 v[8:11], v[140:143], v[192:195], v[8:11]
	v_mfma_f32_16x16x32_bf16 v[52:55], v[196:199], v[144:147], v[52:55]
	v_mfma_f32_16x16x32_bf16 v[48:51], v[208:211], v[144:147], v[48:51]
	v_mfma_f32_16x16x32_bf16 v[36:39], v[196:199], v[152:155], v[36:39]
	v_mfma_f32_16x16x32_bf16 v[32:35], v[208:211], v[152:155], v[32:35]
	v_mfma_f32_16x16x32_bf16 v[20:23], v[196:199], v[170:173], v[20:23]
	v_mfma_f32_16x16x32_bf16 v[16:19], v[208:211], v[170:173], v[16:19]
	v_mfma_f32_16x16x32_bf16 v[4:7], v[196:199], v[178:181], v[4:7]
	v_mfma_f32_16x16x32_bf16 v[0:3], v[208:211], v[178:181], v[0:3]
	v_mfma_f32_16x16x32_bf16 v[52:55], v[204:207], v[148:151], v[52:55]
	v_mfma_f32_16x16x32_bf16 v[48:51], v[212:215], v[148:151], v[48:51]
	v_mfma_f32_16x16x32_bf16 v[36:39], v[204:207], v[156:159], v[36:39]
	v_mfma_f32_16x16x32_bf16 v[32:35], v[212:215], v[156:159], v[32:35]
	v_mfma_f32_16x16x32_bf16 v[20:23], v[204:207], v[174:177], v[20:23]
	v_mfma_f32_16x16x32_bf16 v[16:19], v[212:215], v[174:177], v[16:19]
	v_mfma_f32_16x16x32_bf16 v[4:7], v[204:207], v[192:195], v[4:7]
	v_mfma_f32_16x16x32_bf16 v[0:3], v[212:215], v[192:195], v[0:3]
	s_setprio 0
	s_barrier
	ds_read_b128 v[128:131], v189
	ds_read_b128 v[132:135], v189 offset:1024
	ds_read_b128 v[136:139], v189 offset:2048
	ds_read_b128 v[140:143], v189 offset:3072
	s_add_u32 s28, s28, 0x20000
	s_addc_u32 s29, s29, 0
	s_mov_b32 m0, s46
	v_lshl_add_u64 v[196:197], s[28:29], 0, v[160:161]
	ds_read_b128 v[144:147], v187 offset:32768
	ds_read_b128 v[148:151], v187 offset:33792
	ds_read_b128 v[152:155], v187 offset:34816
	ds_read_b128 v[156:159], v187 offset:35840
	ds_read_b128 v[170:173], v187 offset:36864
	ds_read_b128 v[174:177], v187 offset:37888
	ds_read_b128 v[178:181], v187 offset:38912
	ds_read_b128 v[192:195], v187 offset:39936
	global_load_lds_dwordx4 v[196:197], off
	v_lshl_add_u64 v[196:197], s[28:29], 0, v[162:163]
	s_mov_b32 m0, s47
	s_nop 0
	global_load_lds_dwordx4 v[196:197], off
	ds_read_b128 v[196:199], v190
	ds_read_b128 v[204:207], v190 offset:1024
	ds_read_b128 v[208:211], v190 offset:2048
	ds_read_b128 v[212:215], v190 offset:3072
	s_waitcnt lgkmcnt(0)
	s_waitcnt vmcnt(8)
	s_barrier
	s_setprio 1
	v_mfma_f32_16x16x32_bf16 v[124:127], v[128:131], v[144:147], v[124:127]
	v_mfma_f32_16x16x32_bf16 v[120:123], v[136:139], v[144:147], v[120:123]
	v_mfma_f32_16x16x32_bf16 v[108:111], v[128:131], v[152:155], v[108:111]
	v_mfma_f32_16x16x32_bf16 v[104:107], v[136:139], v[152:155], v[104:107]
	v_mfma_f32_16x16x32_bf16 v[92:95], v[128:131], v[170:173], v[92:95]
	v_mfma_f32_16x16x32_bf16 v[88:91], v[136:139], v[170:173], v[88:91]
	v_mfma_f32_16x16x32_bf16 v[76:79], v[128:131], v[178:181], v[76:79]
	v_mfma_f32_16x16x32_bf16 v[72:75], v[136:139], v[178:181], v[72:75]
	v_mfma_f32_16x16x32_bf16 v[124:127], v[132:135], v[148:151], v[124:127]
	v_mfma_f32_16x16x32_bf16 v[120:123], v[140:143], v[148:151], v[120:123]
	v_mfma_f32_16x16x32_bf16 v[108:111], v[132:135], v[156:159], v[108:111]
	v_mfma_f32_16x16x32_bf16 v[104:107], v[140:143], v[156:159], v[104:107]
	v_mfma_f32_16x16x32_bf16 v[92:95], v[132:135], v[174:177], v[92:95]
	v_mfma_f32_16x16x32_bf16 v[88:91], v[140:143], v[174:177], v[88:91]
	v_mfma_f32_16x16x32_bf16 v[76:79], v[132:135], v[192:195], v[76:79]
	v_mfma_f32_16x16x32_bf16 v[72:75], v[140:143], v[192:195], v[72:75]
	v_mfma_f32_16x16x32_bf16 v[116:119], v[196:199], v[144:147], v[116:119]
	v_mfma_f32_16x16x32_bf16 v[112:115], v[208:211], v[144:147], v[112:115]
	v_mfma_f32_16x16x32_bf16 v[100:103], v[196:199], v[152:155], v[100:103]
	v_mfma_f32_16x16x32_bf16 v[96:99], v[208:211], v[152:155], v[96:99]
	v_mfma_f32_16x16x32_bf16 v[84:87], v[196:199], v[170:173], v[84:87]
	v_mfma_f32_16x16x32_bf16 v[80:83], v[208:211], v[170:173], v[80:83]
	v_mfma_f32_16x16x32_bf16 v[68:71], v[196:199], v[178:181], v[68:71]
	v_mfma_f32_16x16x32_bf16 v[64:67], v[208:211], v[178:181], v[64:67]
	v_mfma_f32_16x16x32_bf16 v[116:119], v[204:207], v[148:151], v[116:119]
	v_mfma_f32_16x16x32_bf16 v[112:115], v[212:215], v[148:151], v[112:115]
	v_mfma_f32_16x16x32_bf16 v[100:103], v[204:207], v[156:159], v[100:103]
	v_mfma_f32_16x16x32_bf16 v[96:99], v[212:215], v[156:159], v[96:99]
	v_mfma_f32_16x16x32_bf16 v[84:87], v[204:207], v[174:177], v[84:87]
	v_mfma_f32_16x16x32_bf16 v[80:83], v[212:215], v[174:177], v[80:83]
	v_mfma_f32_16x16x32_bf16 v[68:71], v[204:207], v[192:195], v[68:71]
	v_mfma_f32_16x16x32_bf16 v[64:67], v[212:215], v[192:195], v[64:67]
	s_setprio 0
	s_barrier
	ds_read_b128 v[144:147], v187 offset:49152
	ds_read_b128 v[148:151], v187 offset:50176
	ds_read_b128 v[152:155], v187 offset:51200
	ds_read_b128 v[156:159], v187 offset:52224
	ds_read_b128 v[170:173], v187 offset:53248
	ds_read_b128 v[174:177], v187 offset:54272
	ds_read_b128 v[178:181], v187 offset:55296
	ds_read_b128 v[192:195], v187 offset:56320
	s_mov_b32 m0, s51
	v_lshl_add_u64 v[182:183], v[182:183], 0, s[10:11]
	global_load_lds_dwordx4 v[182:183], off
	v_lshl_add_u64 v[182:183], v[200:201], 0, s[10:11]
	s_mov_b32 m0, s52
	s_nop 0
	global_load_lds_dwordx4 v[182:183], off
	s_mov_b32 m0, s53
	v_lshl_add_u64 v[182:183], v[216:217], 0, s[10:11]
	global_load_lds_dwordx4 v[182:183], off
	v_lshl_add_u64 v[182:183], v[218:219], 0, s[10:11]
	s_mov_b32 m0, s54
	s_nop 0
	global_load_lds_dwordx4 v[182:183], off
	s_add_u32 s26, s26, 0x20080
	s_addc_u32 s27, s27, 0
	s_mov_b32 m0, s55
	v_lshl_add_u64 v[248:249], s[26:27], 0, v[160:161]
	global_load_lds_dwordx4 v[248:249], off
	v_lshl_add_u64 v[248:249], s[26:27], 0, v[162:163]
	s_mov_b32 m0, s56
	s_nop 0
	global_load_lds_dwordx4 v[248:249], off
	s_waitcnt lgkmcnt(0)
	s_waitcnt vmcnt(8)
	s_barrier
	s_setprio 1
	v_mfma_f32_16x16x32_bf16 v[60:63], v[128:131], v[144:147], v[60:63]
	v_mfma_f32_16x16x32_bf16 v[56:59], v[136:139], v[144:147], v[56:59]
	v_mfma_f32_16x16x32_bf16 v[44:47], v[128:131], v[152:155], v[44:47]
	v_mfma_f32_16x16x32_bf16 v[40:43], v[136:139], v[152:155], v[40:43]
	v_mfma_f32_16x16x32_bf16 v[28:31], v[128:131], v[170:173], v[28:31]
	v_mfma_f32_16x16x32_bf16 v[24:27], v[136:139], v[170:173], v[24:27]
	v_mfma_f32_16x16x32_bf16 v[12:15], v[128:131], v[178:181], v[12:15]
	v_mfma_f32_16x16x32_bf16 v[8:11], v[136:139], v[178:181], v[8:11]
	v_mfma_f32_16x16x32_bf16 v[60:63], v[132:135], v[148:151], v[60:63]
	v_mfma_f32_16x16x32_bf16 v[56:59], v[140:143], v[148:151], v[56:59]
	v_mfma_f32_16x16x32_bf16 v[44:47], v[132:135], v[156:159], v[44:47]
	v_mfma_f32_16x16x32_bf16 v[40:43], v[140:143], v[156:159], v[40:43]
	v_mfma_f32_16x16x32_bf16 v[28:31], v[132:135], v[174:177], v[28:31]
	v_mfma_f32_16x16x32_bf16 v[24:27], v[140:143], v[174:177], v[24:27]
	v_mfma_f32_16x16x32_bf16 v[12:15], v[132:135], v[192:195], v[12:15]
	v_mfma_f32_16x16x32_bf16 v[8:11], v[140:143], v[192:195], v[8:11]
	v_mfma_f32_16x16x32_bf16 v[52:55], v[196:199], v[144:147], v[52:55]
	v_mfma_f32_16x16x32_bf16 v[48:51], v[208:211], v[144:147], v[48:51]
	v_mfma_f32_16x16x32_bf16 v[36:39], v[196:199], v[152:155], v[36:39]
	v_mfma_f32_16x16x32_bf16 v[32:35], v[208:211], v[152:155], v[32:35]
	v_mfma_f32_16x16x32_bf16 v[20:23], v[196:199], v[170:173], v[20:23]
	v_mfma_f32_16x16x32_bf16 v[16:19], v[208:211], v[170:173], v[16:19]
	v_mfma_f32_16x16x32_bf16 v[4:7], v[196:199], v[178:181], v[4:7]
	v_mfma_f32_16x16x32_bf16 v[0:3], v[208:211], v[178:181], v[0:3]
	v_mfma_f32_16x16x32_bf16 v[52:55], v[204:207], v[148:151], v[52:55]
	v_mfma_f32_16x16x32_bf16 v[48:51], v[212:215], v[148:151], v[48:51]
	v_mfma_f32_16x16x32_bf16 v[36:39], v[204:207], v[156:159], v[36:39]
	v_mfma_f32_16x16x32_bf16 v[32:35], v[212:215], v[156:159], v[32:35]
	v_mfma_f32_16x16x32_bf16 v[20:23], v[204:207], v[174:177], v[20:23]
	v_mfma_f32_16x16x32_bf16 v[16:19], v[212:215], v[174:177], v[16:19]
	v_mfma_f32_16x16x32_bf16 v[4:7], v[204:207], v[192:195], v[4:7]
	v_mfma_f32_16x16x32_bf16 v[0:3], v[212:215], v[192:195], v[0:3]
	s_setprio 0
	s_add_i32 s38, s38, 2
	s_add_u32 s24, s24, 0x100
	s_addc_u32 s25, s25, 0
	s_add_u32 s36, s36, 0x100
	s_addc_u32 s37, s37, 0
	s_cmp_gt_u32 s38, 5
	s_barrier
	s_cbranch_scc0 .LBB0_1128
	v_lshl_or_b32 v128, s63, 8, v185
	v_lshl_add_u32 v170, s18, 8, v184
	v_ashrrev_i32_e32 v129, 31, v128
	v_lshlrev_b64 v[174:175], 1, v[128:129]
	v_ashrrev_i32_e32 v171, 31, v170
	v_lshl_add_u64 v[128:129], s[8:9], 0, v[174:175]
	v_lshlrev_b64 v[204:205], 11, v[170:171]
	v_lshl_add_u64 v[130:131], v[128:129], 0, v[204:205]
	global_load_dwordx4 v[194:197], v[130:131], off
	global_load_dwordx4 v[198:201], v[130:131], off offset:64
	v_or_b32_e32 v130, 16, v170
	v_or_b32_e32 v132, 32, v170
	v_or_b32_e32 v134, 48, v170
	v_ashrrev_i32_e32 v131, 31, v130
	v_ashrrev_i32_e32 v133, 31, v132
	v_ashrrev_i32_e32 v135, 31, v134
	v_lshlrev_b64 v[182:183], 11, v[130:131]
	v_add_u32_e32 v178, 0x80, v170
	v_lshlrev_b64 v[180:181], 11, v[132:133]
	v_lshlrev_b64 v[176:177], 11, v[134:135]
	v_lshl_add_u64 v[132:133], v[128:129], 0, v[182:183]
	v_ashrrev_i32_e32 v179, 31, v178
	v_lshl_add_u64 v[134:135], v[128:129], 0, v[180:181]
	v_lshl_add_u64 v[128:129], v[128:129], 0, v[176:177]
	global_load_dwordx4 v[156:159], v[132:133], off
	global_load_dwordx4 v[152:155], v[132:133], off offset:64
	global_load_dwordx4 v[148:151], v[134:135], off
	global_load_dwordx4 v[144:147], v[134:135], off offset:64
	global_load_dwordx4 v[140:143], v[128:129], off
	global_load_dwordx4 v[136:139], v[128:129], off offset:64
	v_lshlrev_b64 v[130:131], 11, v[178:179]
	v_lshl_add_u64 v[130:131], s[8:9], 0, v[130:131]
	v_lshl_add_u64 v[172:173], v[130:131], 0, v[174:175]
	global_load_dwordx4 v[132:135], v[172:173], off
	global_load_dwordx4 v[128:131], v[172:173], off offset:64
	v_and_b32_e32 v192, 64, v191
	v_xor_b32_e32 v179, 16, v191
	v_add_u32_e32 v192, 64, v192
	v_xor_b32_e32 v193, 32, v191
	v_cmp_lt_i32_e32 vcc, v179, v192
	v_lshl_add_u64 v[204:205], s[8:9], 0, v[204:205]
	v_lshl_add_u64 v[204:205], v[204:205], 0, v[174:175]
	v_cndmask_b32_e32 v179, v191, v179, vcc
	v_cmp_lt_i32_e32 vcc, v193, v192
	v_lshlrev_b32_e32 v192, 2, v179
	s_lshl_b32 s18, s63, 2
	v_cndmask_b32_e32 v193, v191, v193, vcc
	v_lshlrev_b32_e32 v179, 2, v193
	s_or_b32 s25, s18, s50
	s_mul_hi_i32 s24, s25, 0x21000
	s_mul_i32 s25, s25, 0x21000
	s_waitcnt vmcnt(0)
	v_lshlrev_b32_e32 v206, 16, v194
	v_and_b32_e32 v207, 0xffff0000, v194
	v_lshlrev_b32_e32 v194, 16, v195
	v_and_b32_e32 v195, 0xffff0000, v195
	v_lshlrev_b32_e32 v208, 16, v196
	v_and_b32_e32 v209, 0xffff0000, v196
	v_lshlrev_b32_e32 v196, 16, v197
	v_and_b32_e32 v197, 0xffff0000, v197
	v_lshlrev_b32_e32 v212, 16, v200
	v_and_b32_e32 v213, 0xffff0000, v200
	v_lshlrev_b32_e32 v200, 16, v201
	v_and_b32_e32 v201, 0xffff0000, v201
	v_pk_add_f32 v[126:127], v[126:127], v[194:195]
	v_pk_add_f32 v[124:125], v[124:125], v[206:207]
	v_pk_add_f32 v[122:123], v[122:123], v[196:197]
	v_pk_add_f32 v[120:121], v[120:121], v[208:209]
	v_lshlrev_b32_e32 v210, 16, v198
	v_and_b32_e32 v211, 0xffff0000, v198
	v_lshlrev_b32_e32 v198, 16, v199
	v_and_b32_e32 v199, 0xffff0000, v199
	v_pk_add_f32 v[194:195], v[114:115], v[200:201]
	v_pk_add_f32 v[196:197], v[112:113], v[212:213]
	v_cvt_pk_bf16_f32 v112, v124, v125
	v_cvt_pk_bf16_f32 v113, v126, v127
	v_mul_f32_e32 v114, v125, v125
	v_mul_f32_e32 v115, v127, v127
	v_mul_f32_e32 v125, v121, v121
	v_mul_f32_e32 v127, v123, v123
	v_pk_add_f32 v[118:119], v[118:119], v[198:199]
	v_pk_add_f32 v[116:117], v[116:117], v[210:211]
	v_fmac_f32_e32 v114, v124, v124
	v_fmac_f32_e32 v115, v126, v126
	v_fmac_f32_e32 v125, v120, v120
	v_fmac_f32_e32 v127, v122, v122
	v_mul_f32_e32 v193, v117, v117
	v_mul_f32_e32 v198, v119, v119
	v_add_f32_e32 v114, v114, v115
	v_add_f32_e32 v115, v125, v127
	v_mul_f32_e32 v124, v197, v197
	v_mul_f32_e32 v125, v195, v195
	v_fmac_f32_e32 v193, v116, v116
	v_fmac_f32_e32 v198, v118, v118
	v_fmac_f32_e32 v124, v196, v196
	v_fmac_f32_e32 v125, v194, v194
	v_add_f32_e32 v114, v114, v115
	v_add_f32_e32 v115, v193, v198
	v_add_f32_e32 v124, v124, v125
	v_add_f32_e32 v115, v115, v124
	v_add_f32_e32 v124, v114, v115
	ds_bpermute_b32 v125, v192, v124
	v_cvt_pk_bf16_f32 v114, v120, v121
	v_cvt_pk_bf16_f32 v115, v122, v123
	global_store_dwordx4 v[204:205], v[112:115], off
	s_waitcnt lgkmcnt(0)
	s_nop 0
	v_add_f32_e32 v112, v124, v125
	ds_bpermute_b32 v113, v179, v112
	v_cvt_pk_bf16_f32 v114, v116, v117
	v_cvt_pk_bf16_f32 v115, v118, v119
	v_cvt_pk_bf16_f32 v116, v196, v197
	v_cvt_pk_bf16_f32 v117, v194, v195
	global_store_dwordx4 v[204:205], v[114:117], off offset:64
	s_and_saveexec_b64 s[18:19], s[4:5]
	s_cbranch_execz .LBB0_1131
	s_add_u32 s26, s48, s25
	s_addc_u32 s27, s49, s24
	s_waitcnt lgkmcnt(0)
	v_add_f32_e32 v114, v112, v113
	v_lshl_add_u64 v[112:113], v[170:171], 2, s[26:27]
	global_store_dword v[112:113], v114, off

.LBB0_1243:
	ds_read_b128 v[170:173], v162
	ds_read_b128 v[174:177], v162 offset:1024
	ds_read_b128 v[178:181], v162 offset:2048
	ds_read_b128 v[182:185], v162 offset:3072
	s_add_u32 s34, s30, 0xfffc0080
	s_addc_u32 s35, s31, -1
	s_cmp_eq_u32 s41, 12
	s_cselect_b32 s37, s11, s35
	s_cselect_b32 s36, s17, s34
	s_cselect_b32 s35, s29, s40
	s_cselect_b32 s34, s38, s39
	v_lshl_add_u64 v[144:145], s[30:31], 0, v[134:135]
	s_add_i32 m0, s48, 0xc000
	ds_read_b128 v[186:189], v163
	ds_read_b128 v[190:193], v163 offset:1024
	ds_read_b128 v[194:197], v163 offset:2048
	ds_read_b128 v[198:201], v163 offset:3072
	ds_read_b128 v[204:207], v163 offset:4096
	ds_read_b128 v[208:211], v163 offset:5120
	ds_read_b128 v[212:215], v163 offset:6144
	ds_read_b128 v[216:219], v163 offset:7168
	global_load_lds_dwordx4 v[144:145], off
	v_lshl_add_u64 v[144:145], s[30:31], 0, v[136:137]
	s_add_i32 m0, s48, 0xe000
	s_nop 0
	global_load_lds_dwordx4 v[144:145], off
	ds_read_b128 v[220:223], v164
	ds_read_b128 v[224:227], v164 offset:1024
	ds_read_b128 v[228:231], v164 offset:2048
	ds_read_b128 v[232:235], v164 offset:3072
	s_waitcnt lgkmcnt(0)
	s_waitcnt vmcnt(8)
	s_barrier
	s_setprio 1
	v_mfma_f32_16x16x32_bf16 v[124:127], v[170:173], v[186:189], v[124:127]
	v_mfma_f32_16x16x32_bf16 v[120:123], v[178:181], v[186:189], v[120:123]
	v_mfma_f32_16x16x32_bf16 v[112:115], v[170:173], v[194:197], v[112:115]
	v_mfma_f32_16x16x32_bf16 v[104:107], v[178:181], v[194:197], v[104:107]
	v_mfma_f32_16x16x32_bf16 v[96:99], v[170:173], v[204:207], v[96:99]
	v_mfma_f32_16x16x32_bf16 v[88:91], v[178:181], v[204:207], v[88:91]
	v_mfma_f32_16x16x32_bf16 v[80:83], v[170:173], v[212:215], v[80:83]
	v_mfma_f32_16x16x32_bf16 v[72:75], v[178:181], v[212:215], v[72:75]
	v_mfma_f32_16x16x32_bf16 v[124:127], v[174:177], v[190:193], v[124:127]
	v_mfma_f32_16x16x32_bf16 v[120:123], v[182:185], v[190:193], v[120:123]
	v_mfma_f32_16x16x32_bf16 v[112:115], v[174:177], v[198:201], v[112:115]
	v_mfma_f32_16x16x32_bf16 v[104:107], v[182:185], v[198:201], v[104:107]
	v_mfma_f32_16x16x32_bf16 v[96:99], v[174:177], v[208:211], v[96:99]
	v_mfma_f32_16x16x32_bf16 v[88:91], v[182:185], v[208:211], v[88:91]
	v_mfma_f32_16x16x32_bf16 v[80:83], v[174:177], v[216:219], v[80:83]
	v_mfma_f32_16x16x32_bf16 v[72:75], v[182:185], v[216:219], v[72:75]
	v_mfma_f32_16x16x32_bf16 v[116:119], v[220:223], v[186:189], v[116:119]
	v_mfma_f32_16x16x32_bf16 v[108:111], v[228:231], v[186:189], v[108:111]
	v_mfma_f32_16x16x32_bf16 v[100:103], v[220:223], v[194:197], v[100:103]
	v_mfma_f32_16x16x32_bf16 v[92:95], v[228:231], v[194:197], v[92:95]
	v_mfma_f32_16x16x32_bf16 v[84:87], v[220:223], v[204:207], v[84:87]
	v_mfma_f32_16x16x32_bf16 v[76:79], v[228:231], v[204:207], v[76:79]
	v_mfma_f32_16x16x32_bf16 v[68:71], v[220:223], v[212:215], v[68:71]
	v_mfma_f32_16x16x32_bf16 v[64:67], v[228:231], v[212:215], v[64:67]
	v_mfma_f32_16x16x32_bf16 v[116:119], v[224:227], v[190:193], v[116:119]
	v_mfma_f32_16x16x32_bf16 v[108:111], v[232:235], v[190:193], v[108:111]
	v_mfma_f32_16x16x32_bf16 v[100:103], v[224:227], v[198:201], v[100:103]
	v_mfma_f32_16x16x32_bf16 v[92:95], v[232:235], v[198:201], v[92:95]
	v_mfma_f32_16x16x32_bf16 v[84:87], v[224:227], v[208:211], v[84:87]
	v_mfma_f32_16x16x32_bf16 v[76:79], v[232:235], v[208:211], v[76:79]
	v_mfma_f32_16x16x32_bf16 v[68:71], v[224:227], v[216:219], v[68:71]
	v_mfma_f32_16x16x32_bf16 v[64:67], v[232:235], v[216:219], v[64:67]
	s_setprio 0
	s_barrier
	ds_read_b128 v[186:189], v163 offset:16384
	ds_read_b128 v[190:193], v163 offset:17408
	ds_read_b128 v[194:197], v163 offset:18432
	ds_read_b128 v[198:201], v163 offset:19456
	ds_read_b128 v[204:207], v163 offset:20480
	ds_read_b128 v[208:211], v163 offset:21504
	ds_read_b128 v[212:215], v163 offset:22528
	ds_read_b128 v[216:219], v163 offset:23552
	s_mov_b32 m0, s46
	v_lshl_add_u64 v[144:145], s[34:35], 0, v[128:129]
	global_load_lds_dwordx4 v[144:145], off
	v_lshl_add_u64 v[236:237], s[34:35], 0, v[130:131]
	s_mov_b32 m0, s47
	s_nop 0
	global_load_lds_dwordx4 v[236:237], off
	s_mov_b32 m0, s48
	v_lshl_add_u64 v[238:239], s[36:37], 0, v[128:129]
	global_load_lds_dwordx4 v[238:239], off
	v_lshl_add_u64 v[240:241], s[36:37], 0, v[130:131]
	s_mov_b32 m0, s49
	s_nop 0
	global_load_lds_dwordx4 v[240:241], off
	s_add_u32 s72, s34, 0x40000
	s_addc_u32 s73, s35, 0
	s_mov_b32 m0, s50
	v_lshl_add_u64 v[248:249], s[72:73], 0, v[128:129]
	global_load_lds_dwordx4 v[248:249], off
	v_lshl_add_u64 v[248:249], s[72:73], 0, v[130:131]
	s_mov_b32 m0, s51
	s_nop 0
	global_load_lds_dwordx4 v[248:249], off
	s_waitcnt lgkmcnt(0)
	s_waitcnt vmcnt(8)
	s_barrier
	s_setprio 1
	v_mfma_f32_16x16x32_bf16 v[60:63], v[170:173], v[186:189], v[60:63]
	v_mfma_f32_16x16x32_bf16 v[56:59], v[178:181], v[186:189], v[56:59]
	v_mfma_f32_16x16x32_bf16 v[48:51], v[170:173], v[194:197], v[48:51]
	v_mfma_f32_16x16x32_bf16 v[40:43], v[178:181], v[194:197], v[40:43]
	v_mfma_f32_16x16x32_bf16 v[32:35], v[170:173], v[204:207], v[32:35]
	v_mfma_f32_16x16x32_bf16 v[24:27], v[178:181], v[204:207], v[24:27]
	v_mfma_f32_16x16x32_bf16 v[16:19], v[170:173], v[212:215], v[16:19]
	v_mfma_f32_16x16x32_bf16 v[8:11], v[178:181], v[212:215], v[8:11]
	v_mfma_f32_16x16x32_bf16 v[60:63], v[174:177], v[190:193], v[60:63]
	v_mfma_f32_16x16x32_bf16 v[56:59], v[182:185], v[190:193], v[56:59]
	v_mfma_f32_16x16x32_bf16 v[48:51], v[174:177], v[198:201], v[48:51]
	v_mfma_f32_16x16x32_bf16 v[40:43], v[182:185], v[198:201], v[40:43]
	v_mfma_f32_16x16x32_bf16 v[32:35], v[174:177], v[208:211], v[32:35]
	v_mfma_f32_16x16x32_bf16 v[24:27], v[182:185], v[208:211], v[24:27]
	v_mfma_f32_16x16x32_bf16 v[16:19], v[174:177], v[216:219], v[16:19]
	v_mfma_f32_16x16x32_bf16 v[8:11], v[182:185], v[216:219], v[8:11]
	v_mfma_f32_16x16x32_bf16 v[52:55], v[220:223], v[186:189], v[52:55]
	v_mfma_f32_16x16x32_bf16 v[44:47], v[228:231], v[186:189], v[44:47]
	v_mfma_f32_16x16x32_bf16 v[36:39], v[220:223], v[194:197], v[36:39]
	v_mfma_f32_16x16x32_bf16 v[28:31], v[228:231], v[194:197], v[28:31]
	v_mfma_f32_16x16x32_bf16 v[20:23], v[220:223], v[204:207], v[20:23]
	v_mfma_f32_16x16x32_bf16 v[12:15], v[228:231], v[204:207], v[12:15]
	v_mfma_f32_16x16x32_bf16 v[4:7], v[220:223], v[212:215], v[4:7]
	v_mfma_f32_16x16x32_bf16 v[0:3], v[228:231], v[212:215], v[0:3]
	v_mfma_f32_16x16x32_bf16 v[52:55], v[224:227], v[190:193], v[52:55]
	v_mfma_f32_16x16x32_bf16 v[44:47], v[232:235], v[190:193], v[44:47]
	v_mfma_f32_16x16x32_bf16 v[36:39], v[224:227], v[198:201], v[36:39]
	v_mfma_f32_16x16x32_bf16 v[28:31], v[232:235], v[198:201], v[28:31]
	v_mfma_f32_16x16x32_bf16 v[20:23], v[224:227], v[208:211], v[20:23]
	v_mfma_f32_16x16x32_bf16 v[12:15], v[232:235], v[208:211], v[12:15]
	v_mfma_f32_16x16x32_bf16 v[4:7], v[224:227], v[216:219], v[4:7]
	v_mfma_f32_16x16x32_bf16 v[0:3], v[232:235], v[216:219], v[0:3]
	s_setprio 0
	s_barrier
	ds_read_b128 v[170:173], v165
	ds_read_b128 v[174:177], v165 offset:1024
	ds_read_b128 v[178:181], v165 offset:2048
	ds_read_b128 v[182:185], v165 offset:3072
	s_add_u32 s36, s36, 0x40000
	s_addc_u32 s37, s37, 0
	s_mov_b32 m0, s52
	v_lshl_add_u64 v[220:221], s[36:37], 0, v[128:129]
	ds_read_b128 v[186:189], v163 offset:32768
	ds_read_b128 v[190:193], v163 offset:33792
	ds_read_b128 v[194:197], v163 offset:34816
	ds_read_b128 v[198:201], v163 offset:35840
	ds_read_b128 v[204:207], v163 offset:36864
	ds_read_b128 v[208:211], v163 offset:37888
	ds_read_b128 v[212:215], v163 offset:38912
	ds_read_b128 v[216:219], v163 offset:39936
	global_load_lds_dwordx4 v[220:221], off
	v_lshl_add_u64 v[220:221], s[36:37], 0, v[130:131]
	s_mov_b32 m0, s53
	s_nop 0
	global_load_lds_dwordx4 v[220:221], off
	ds_read_b128 v[220:223], v166
	ds_read_b128 v[224:227], v166 offset:1024
	ds_read_b128 v[228:231], v166 offset:2048
	ds_read_b128 v[232:235], v166 offset:3072
	s_waitcnt lgkmcnt(0)
	s_waitcnt vmcnt(8)
	s_barrier
	s_setprio 1
	v_mfma_f32_16x16x32_bf16 v[124:127], v[170:173], v[186:189], v[124:127]
	v_mfma_f32_16x16x32_bf16 v[120:123], v[178:181], v[186:189], v[120:123]
	v_mfma_f32_16x16x32_bf16 v[112:115], v[170:173], v[194:197], v[112:115]
	v_mfma_f32_16x16x32_bf16 v[104:107], v[178:181], v[194:197], v[104:107]
	v_mfma_f32_16x16x32_bf16 v[96:99], v[170:173], v[204:207], v[96:99]
	v_mfma_f32_16x16x32_bf16 v[88:91], v[178:181], v[204:207], v[88:91]
	v_mfma_f32_16x16x32_bf16 v[80:83], v[170:173], v[212:215], v[80:83]
	v_mfma_f32_16x16x32_bf16 v[72:75], v[178:181], v[212:215], v[72:75]
	v_mfma_f32_16x16x32_bf16 v[124:127], v[174:177], v[190:193], v[124:127]
	v_mfma_f32_16x16x32_bf16 v[120:123], v[182:185], v[190:193], v[120:123]
	v_mfma_f32_16x16x32_bf16 v[112:115], v[174:177], v[198:201], v[112:115]
	v_mfma_f32_16x16x32_bf16 v[104:107], v[182:185], v[198:201], v[104:107]
	v_mfma_f32_16x16x32_bf16 v[96:99], v[174:177], v[208:211], v[96:99]
	v_mfma_f32_16x16x32_bf16 v[88:91], v[182:185], v[208:211], v[88:91]
	v_mfma_f32_16x16x32_bf16 v[80:83], v[174:177], v[216:219], v[80:83]
	v_mfma_f32_16x16x32_bf16 v[72:75], v[182:185], v[216:219], v[72:75]
	v_mfma_f32_16x16x32_bf16 v[116:119], v[220:223], v[186:189], v[116:119]
	v_mfma_f32_16x16x32_bf16 v[108:111], v[228:231], v[186:189], v[108:111]
	v_mfma_f32_16x16x32_bf16 v[100:103], v[220:223], v[194:197], v[100:103]
	v_mfma_f32_16x16x32_bf16 v[92:95], v[228:231], v[194:197], v[92:95]
	v_mfma_f32_16x16x32_bf16 v[84:87], v[220:223], v[204:207], v[84:87]
	v_mfma_f32_16x16x32_bf16 v[76:79], v[228:231], v[204:207], v[76:79]
	v_mfma_f32_16x16x32_bf16 v[68:71], v[220:223], v[212:215], v[68:71]
	v_mfma_f32_16x16x32_bf16 v[64:67], v[228:231], v[212:215], v[64:67]
	v_mfma_f32_16x16x32_bf16 v[116:119], v[224:227], v[190:193], v[116:119]
	v_mfma_f32_16x16x32_bf16 v[108:111], v[232:235], v[190:193], v[108:111]
	v_mfma_f32_16x16x32_bf16 v[100:103], v[224:227], v[198:201], v[100:103]
	v_mfma_f32_16x16x32_bf16 v[92:95], v[232:235], v[198:201], v[92:95]
	v_mfma_f32_16x16x32_bf16 v[84:87], v[224:227], v[208:211], v[84:87]
	v_mfma_f32_16x16x32_bf16 v[76:79], v[232:235], v[208:211], v[76:79]
	v_mfma_f32_16x16x32_bf16 v[68:71], v[224:227], v[216:219], v[68:71]
	v_mfma_f32_16x16x32_bf16 v[64:67], v[232:235], v[216:219], v[64:67]
	s_setprio 0
	s_barrier
	ds_read_b128 v[186:189], v163 offset:49152
	ds_read_b128 v[190:193], v163 offset:50176
	ds_read_b128 v[194:197], v163 offset:51200
	ds_read_b128 v[198:201], v163 offset:52224
	ds_read_b128 v[204:207], v163 offset:53248
	ds_read_b128 v[208:211], v163 offset:54272
	ds_read_b128 v[212:215], v163 offset:55296
	ds_read_b128 v[216:219], v163 offset:56320
	s_mov_b32 m0, s54
	v_lshl_add_u64 v[144:145], v[144:145], 0, s[12:13]
	global_load_lds_dwordx4 v[144:145], off
	v_lshl_add_u64 v[144:145], v[236:237], 0, s[12:13]
	s_mov_b32 m0, s55
	s_nop 0
	global_load_lds_dwordx4 v[144:145], off
	s_mov_b32 m0, s56
	v_lshl_add_u64 v[144:145], v[238:239], 0, s[12:13]
	global_load_lds_dwordx4 v[144:145], off
	v_lshl_add_u64 v[144:145], v[240:241], 0, s[12:13]
	s_mov_b32 m0, s57
	s_nop 0
	global_load_lds_dwordx4 v[144:145], off
	s_add_u32 s34, s34, 0x40080
	s_addc_u32 s35, s35, 0
	s_mov_b32 m0, s58
	v_lshl_add_u64 v[144:145], s[34:35], 0, v[128:129]
	global_load_lds_dwordx4 v[144:145], off
	v_lshl_add_u64 v[144:145], s[34:35], 0, v[130:131]
	s_mov_b32 m0, s59
	s_nop 0
	global_load_lds_dwordx4 v[144:145], off
	s_waitcnt lgkmcnt(0)
	s_waitcnt vmcnt(8)
	s_barrier
	s_setprio 1
	v_mfma_f32_16x16x32_bf16 v[60:63], v[170:173], v[186:189], v[60:63]
	v_mfma_f32_16x16x32_bf16 v[56:59], v[178:181], v[186:189], v[56:59]
	v_mfma_f32_16x16x32_bf16 v[48:51], v[170:173], v[194:197], v[48:51]
	v_mfma_f32_16x16x32_bf16 v[40:43], v[178:181], v[194:197], v[40:43]
	v_mfma_f32_16x16x32_bf16 v[32:35], v[170:173], v[204:207], v[32:35]
	v_mfma_f32_16x16x32_bf16 v[24:27], v[178:181], v[204:207], v[24:27]
	v_mfma_f32_16x16x32_bf16 v[16:19], v[170:173], v[212:215], v[16:19]
	v_mfma_f32_16x16x32_bf16 v[8:11], v[178:181], v[212:215], v[8:11]
	v_mfma_f32_16x16x32_bf16 v[60:63], v[174:177], v[190:193], v[60:63]
	v_mfma_f32_16x16x32_bf16 v[56:59], v[182:185], v[190:193], v[56:59]
	v_mfma_f32_16x16x32_bf16 v[48:51], v[174:177], v[198:201], v[48:51]
	v_mfma_f32_16x16x32_bf16 v[40:43], v[182:185], v[198:201], v[40:43]
	v_mfma_f32_16x16x32_bf16 v[32:35], v[174:177], v[208:211], v[32:35]
	v_mfma_f32_16x16x32_bf16 v[24:27], v[182:185], v[208:211], v[24:27]
	v_mfma_f32_16x16x32_bf16 v[16:19], v[174:177], v[216:219], v[16:19]
	v_mfma_f32_16x16x32_bf16 v[8:11], v[182:185], v[216:219], v[8:11]
	v_mfma_f32_16x16x32_bf16 v[52:55], v[220:223], v[186:189], v[52:55]
	v_mfma_f32_16x16x32_bf16 v[44:47], v[228:231], v[186:189], v[44:47]
	v_mfma_f32_16x16x32_bf16 v[36:39], v[220:223], v[194:197], v[36:39]
	v_mfma_f32_16x16x32_bf16 v[28:31], v[228:231], v[194:197], v[28:31]
	v_mfma_f32_16x16x32_bf16 v[20:23], v[220:223], v[204:207], v[20:23]
	v_mfma_f32_16x16x32_bf16 v[12:15], v[228:231], v[204:207], v[12:15]
	v_mfma_f32_16x16x32_bf16 v[4:7], v[220:223], v[212:215], v[4:7]
	v_mfma_f32_16x16x32_bf16 v[0:3], v[228:231], v[212:215], v[0:3]
	v_mfma_f32_16x16x32_bf16 v[52:55], v[224:227], v[190:193], v[52:55]
	v_mfma_f32_16x16x32_bf16 v[44:47], v[232:235], v[190:193], v[44:47]
	v_mfma_f32_16x16x32_bf16 v[36:39], v[224:227], v[198:201], v[36:39]
	v_mfma_f32_16x16x32_bf16 v[28:31], v[232:235], v[198:201], v[28:31]
	v_mfma_f32_16x16x32_bf16 v[20:23], v[224:227], v[208:211], v[20:23]
	v_mfma_f32_16x16x32_bf16 v[12:15], v[232:235], v[208:211], v[12:15]
	v_mfma_f32_16x16x32_bf16 v[4:7], v[224:227], v[216:219], v[4:7]
	v_mfma_f32_16x16x32_bf16 v[0:3], v[232:235], v[216:219], v[0:3]
	s_setprio 0
	s_add_i32 s41, s41, 2
	s_add_u32 s30, s30, 0x100
	s_addc_u32 s31, s31, 0
	s_add_u32 s39, s39, 0x100
	s_addc_u32 s40, s40, 0
	s_cmp_gt_u32 s41, 13
	s_barrier
	s_cbranch_scc0 .LBB0_1243
	v_lshl_add_u32 v144, s42, 8, v160
	v_ashrrev_i32_e32 v145, 31, v144
	v_lshl_add_u64 v[170:171], v[144:145], 2, v[132:133]
	v_add_co_u32_e32 v172, vcc, s60, v170
	v_and_b32_e32 v145, 64, v167
	s_nop 0
	v_addc_co_u32_e32 v173, vcc, 0, v171, vcc
	v_add_co_u32_e32 v174, vcc, s66, v170
	v_xor_b32_e32 v146, 16, v167
	s_nop 0
	v_addc_co_u32_e32 v175, vcc, 0, v171, vcc
	v_add_co_u32_e32 v176, vcc, s67, v170
	v_add_u32_e32 v150, 64, v145
	s_nop 0
	v_addc_co_u32_e32 v177, vcc, 0, v171, vcc
	global_load_dword v178, v[172:173], off
	global_load_dword v180, v[172:173], off offset:64
	global_load_dword v182, v[172:173], off offset:128
	global_load_dword v184, v[172:173], off offset:192
	global_load_dword v186, v[172:173], off offset:512
	global_load_dword v188, v[172:173], off offset:576
	global_load_dword v191, v[174:175], off
	global_load_dword v193, v[174:175], off offset:64
	global_load_dword v195, v[174:175], off offset:128
	global_load_dword v197, v[174:175], off offset:192
	global_load_dword v199, v[174:175], off offset:512
	global_load_dword v201, v[174:175], off offset:576
	global_load_dword v179, v[176:177], off
	global_load_dword v181, v[176:177], off offset:64
	global_load_dword v183, v[176:177], off offset:128
	global_load_dword v185, v[176:177], off offset:192
	global_load_dword v187, v[176:177], off offset:512
	global_load_dword v189, v[176:177], off offset:576
	global_load_dword v190, v[170:171], off
	global_load_dword v192, v[170:171], off offset:64
	global_load_dword v194, v[170:171], off offset:128
	global_load_dword v196, v[170:171], off offset:192
	global_load_dword v198, v[170:171], off offset:512
	global_load_dword v200, v[170:171], off offset:576
	global_load_dword v204, v[170:171], off offset:640
	s_nop 0
	global_load_dword v170, v[170:171], off offset:704
	s_nop 0
	global_load_dword v205, v[174:175], off offset:640
	global_load_dword v207, v[176:177], off offset:640
	global_load_dword v206, v[172:173], off offset:640
	s_nop 0
	global_load_dword v172, v[172:173], off offset:704
	s_nop 0
	global_load_dword v171, v[174:175], off offset:704
	global_load_dword v173, v[176:177], off offset:704
	v_cmp_lt_i32_e32 vcc, v146, v150
	v_xor_b32_e32 v148, 32, v167
	v_add_u32_e32 v145, 0x80, v144
	v_cndmask_b32_e32 v146, v167, v146, vcc
	v_cmp_lt_i32_e32 vcc, v148, v150
	v_lshlrev_b32_e32 v146, 2, v146
	s_cmpk_lt_i32 s42, 0x80
	v_cndmask_b32_e32 v148, v167, v148, vcc
	v_lshlrev_b32_e32 v148, 2, v148
	s_waitcnt vmcnt(0)
	v_pk_add_f32 v[174:175], v[190:191], v[178:179]
	v_pk_add_f32 v[176:177], v[192:193], v[180:181]
	v_pk_add_f32 v[178:179], v[194:195], v[182:183]
	v_pk_add_f32 v[180:181], v[196:197], v[184:185]
	v_pk_add_f32 v[182:183], v[198:199], v[186:187]
	v_add_f32_e32 v150, v174, v175
	v_add_f32_e32 v152, v176, v177
	v_add_f32_e32 v154, v178, v179
	v_add_f32_e32 v156, v180, v181
	v_add_f32_e32 v169, v182, v183
	ds_bpermute_b32 v174, v146, v150
	ds_bpermute_b32 v176, v146, v152
	ds_bpermute_b32 v177, v146, v154
	ds_bpermute_b32 v178, v146, v156
	ds_bpermute_b32 v179, v146, v169
	s_waitcnt lgkmcnt(0)
	v_add_f32_e32 v150, v150, v174
	v_pk_add_f32 v[184:185], v[200:201], v[188:189]
	v_add_f32_e32 v152, v152, v176
	v_add_f32_e32 v154, v154, v177
	v_add_f32_e32 v156, v156, v178
	v_add_f32_e32 v169, v169, v179
	ds_bpermute_b32 v174, v148, v150
	v_add_f32_e32 v175, v184, v185
	ds_bpermute_b32 v176, v148, v152
	ds_bpermute_b32 v177, v148, v154
	ds_bpermute_b32 v178, v148, v156
	ds_bpermute_b32 v179, v148, v169
	ds_bpermute_b32 v180, v146, v175
	s_waitcnt lgkmcnt(5)
	v_add_f32_e32 v150, v150, v174
	s_waitcnt lgkmcnt(4)
	v_add_f32_e32 v152, v152, v176
	s_waitcnt lgkmcnt(3)
	v_add_f32_e32 v154, v154, v177
	s_waitcnt lgkmcnt(2)
	v_add_f32_e32 v156, v156, v178
	s_waitcnt lgkmcnt(1)
	v_add_f32_e32 v169, v169, v179
	v_fmamk_f32 v150, v150, 0x3a800000, v168
	v_pk_add_f32 v[178:179], v[204:205], v[206:207]
	v_fmamk_f32 v152, v152, 0x3a800000, v168
	v_fmamk_f32 v154, v154, 0x3a800000, v168
	v_fmamk_f32 v177, v156, 0x3a800000, v168
	v_fmamk_f32 v169, v169, 0x3a800000, v168
	v_rsq_f32_e32 v174, v150
	s_waitcnt lgkmcnt(0)
	v_add_f32_e32 v150, v175, v180
	v_add_f32_e32 v175, v178, v179
	v_rsq_f32_e32 v176, v152
	v_rsq_f32_e32 v156, v154
	v_rsq_f32_e32 v154, v177
	v_rsq_f32_e32 v152, v169
	ds_bpermute_b32 v169, v148, v150
	ds_bpermute_b32 v177, v146, v175
	v_pk_add_f32 v[170:171], v[170:171], v[172:173]
	v_pk_mul_f32 v[124:125], v[124:125], v[174:175] op_sel_hi:[1,0]
	v_add_f32_e32 v170, v170, v171
	ds_bpermute_b32 v146, v146, v170
	s_waitcnt lgkmcnt(2)
	v_add_f32_e32 v150, v150, v169
	s_waitcnt lgkmcnt(1)
	v_add_f32_e32 v169, v175, v177
	ds_bpermute_b32 v171, v148, v169
	v_mul_f32_e32 v172, 0xbfb8aa3b, v125
	s_waitcnt lgkmcnt(1)
	v_add_f32_e32 v146, v170, v146
	ds_bpermute_b32 v170, v148, v146
	v_exp_f32_e32 v173, v172
	s_waitcnt lgkmcnt(1)
	v_add_f32_e32 v148, v169, v171
	v_mul_f32_e32 v169, 0xbfb8aa3b, v124
	v_exp_f32_e32 v169, v169
	v_pk_mul_f32 v[126:127], v[126:127], v[174:175] op_sel_hi:[1,0]
	v_pk_mul_f32 v[118:119], v[118:119], v[174:175] op_sel_hi:[1,0]
	s_waitcnt lgkmcnt(0)
	v_add_f32_e32 v146, v146, v170
	v_add_f32_e32 v169, 1.0, v169
	v_rcp_f32_e32 v172, v169
	v_add_f32_e32 v169, 1.0, v173
	v_mul_f32_e32 v173, 0xbfb8aa3b, v126
	v_exp_f32_e32 v175, v173
	v_mul_f32_e32 v173, 0xbfb8aa3b, v127
	v_exp_f32_e32 v177, v173
	v_rcp_f32_e32 v173, v169
	v_add_f32_e32 v169, 1.0, v175
	v_rcp_f32_e32 v178, v169
	v_add_f32_e32 v169, 1.0, v177
	v_rcp_f32_e32 v179, v169
	v_pk_mul_f32 v[116:117], v[116:117], v[174:175] op_sel_hi:[1,0]
	v_pk_mul_f32 v[124:125], v[124:125], v[172:173]
	v_pk_mul_f32 v[120:121], v[120:121], v[174:175] op_sel_hi:[1,0]
	v_pk_mul_f32 v[116:117], v[116:117], v[124:125]
	v_pk_mul_f32 v[124:125], v[126:127], v[178:179]
	v_pk_mul_f32 v[122:123], v[122:123], v[174:175] op_sel_hi:[1,0]
	v_pk_mul_f32 v[118:119], v[118:119], v[124:125]
	v_mul_f32_e32 v124, 0xbfb8aa3b, v120
	v_mul_f32_e32 v125, 0xbfb8aa3b, v121
	v_exp_f32_e32 v124, v124
	v_exp_f32_e32 v125, v125
	v_mul_f32_e32 v126, 0xbfb8aa3b, v122
	v_mul_f32_e32 v127, 0xbfb8aa3b, v123
	v_exp_f32_e32 v126, v126
	v_exp_f32_e32 v127, v127
	v_add_f32_e32 v124, 1.0, v124
	v_add_f32_e32 v125, 1.0, v125
	v_rcp_f32_e32 v124, v124
	v_rcp_f32_e32 v125, v125
	v_add_f32_e32 v126, 1.0, v126
	v_add_f32_e32 v127, 1.0, v127
	v_rcp_f32_e32 v126, v126
	v_rcp_f32_e32 v127, v127
	v_pk_mul_f32 v[108:109], v[108:109], v[174:175] op_sel_hi:[1,0]
	v_pk_mul_f32 v[120:121], v[120:121], v[124:125]
	v_lshl_or_b32 v170, s28, 7, v161
	v_pk_mul_f32 v[110:111], v[110:111], v[174:175] op_sel_hi:[1,0]
	v_pk_mul_f32 v[108:109], v[108:109], v[120:121]
	v_pk_mul_f32 v[120:121], v[122:123], v[126:127]
	v_ashrrev_i32_e32 v171, 31, v170
	v_pk_mul_f32 v[110:111], v[110:111], v[120:121]
	v_cvt_pk_bf16_f32 v116, v116, v117
	v_cvt_pk_bf16_f32 v117, v118, v119
	v_cvt_pk_bf16_f32 v118, v108, v109
	v_mov_b64_e32 v[108:109], s[6:7]
	v_cvt_pk_bf16_f32 v119, v110, v111
	v_mad_i64_i32 v[120:121], s[28:29], v144, s68, v[108:109]
	v_lshlrev_b64 v[110:111], 1, v[170:171]
	v_lshl_add_u64 v[120:121], v[120:121], 0, v[110:111]
	v_pk_mul_f32 v[112:113], v[112:113], v[176:177] op_sel_hi:[1,0]
	global_store_dwordx4 v[120:121], v[116:119], off
	v_pk_mul_f32 v[114:115], v[114:115], v[176:177] op_sel_hi:[1,0]
	v_pk_mul_f32 v[100:101], v[100:101], v[176:177] op_sel_hi:[1,0]
	v_mul_f32_e32 v116, 0xbfb8aa3b, v112
	v_mul_f32_e32 v117, 0xbfb8aa3b, v113
	v_exp_f32_e32 v116, v116
	v_exp_f32_e32 v117, v117
	v_mul_f32_e32 v118, 0xbfb8aa3b, v114
	v_mul_f32_e32 v119, 0xbfb8aa3b, v115
	v_exp_f32_e32 v118, v118
	v_exp_f32_e32 v119, v119
	v_add_f32_e32 v116, 1.0, v116
	v_add_f32_e32 v117, 1.0, v117
	v_rcp_f32_e32 v116, v116
	v_rcp_f32_e32 v117, v117
	v_add_f32_e32 v118, 1.0, v118
	v_add_f32_e32 v119, 1.0, v119
	v_rcp_f32_e32 v118, v118
	v_rcp_f32_e32 v119, v119
	v_pk_mul_f32 v[112:113], v[112:113], v[116:117]
	v_pk_mul_f32 v[102:103], v[102:103], v[176:177] op_sel_hi:[1,0]
	v_pk_mul_f32 v[100:101], v[100:101], v[112:113]
	v_pk_mul_f32 v[112:113], v[114:115], v[118:119]
	v_pk_mul_f32 v[104:105], v[104:105], v[176:177] op_sel_hi:[1,0]
	v_pk_mul_f32 v[102:103], v[102:103], v[112:113]
	v_pk_mul_f32 v[106:107], v[106:107], v[176:177] op_sel_hi:[1,0]
	v_mul_f32_e32 v112, 0xbfb8aa3b, v104
	v_mul_f32_e32 v113, 0xbfb8aa3b, v105
	v_exp_f32_e32 v112, v112
	v_exp_f32_e32 v113, v113
	v_mul_f32_e32 v114, 0xbfb8aa3b, v106
	v_mul_f32_e32 v115, 0xbfb8aa3b, v107
	v_exp_f32_e32 v114, v114
	v_exp_f32_e32 v115, v115
	v_add_f32_e32 v112, 1.0, v112
	v_add_f32_e32 v113, 1.0, v113
	v_rcp_f32_e32 v112, v112
	v_rcp_f32_e32 v113, v113
	v_add_f32_e32 v114, 1.0, v114
	v_add_f32_e32 v115, 1.0, v115
	v_rcp_f32_e32 v114, v114
	v_rcp_f32_e32 v115, v115
	v_pk_mul_f32 v[92:93], v[92:93], v[176:177] op_sel_hi:[1,0]
	v_pk_mul_f32 v[104:105], v[104:105], v[112:113]
	v_pk_mul_f32 v[94:95], v[94:95], v[176:177] op_sel_hi:[1,0]
	v_pk_mul_f32 v[104:105], v[92:93], v[104:105]
	v_pk_mul_f32 v[92:93], v[106:107], v[114:115]
	v_or_b32_e32 v112, 16, v144
	v_pk_mul_f32 v[106:107], v[94:95], v[92:93]
	v_cvt_pk_bf16_f32 v92, v100, v101
	v_mad_i64_i32 v[100:101], s[28:29], v112, s68, v[108:109]
	v_cvt_pk_bf16_f32 v93, v102, v103
	v_cvt_pk_bf16_f32 v94, v104, v105
	v_cvt_pk_bf16_f32 v95, v106, v107
	v_lshl_add_u64 v[100:101], v[100:101], 0, v[110:111]
	global_store_dwordx4 v[100:101], v[92:95], off
	v_pk_mul_f32 v[86:87], v[86:87], v[156:157] op_sel_hi:[1,0]
	v_pk_mul_f32 v[88:89], v[88:89], v[156:157] op_sel_hi:[1,0]
	v_pk_mul_f32 v[92:93], v[98:99], v[156:157] op_sel_hi:[1,0]
	v_pk_mul_f32 v[94:95], v[96:97], v[156:157] op_sel_hi:[1,0]
	v_mul_f32_e32 v98, 0xbfb8aa3b, v92
	v_mul_f32_e32 v99, 0xbfb8aa3b, v93
	v_mul_f32_e32 v96, 0xbfb8aa3b, v94
	v_mul_f32_e32 v97, 0xbfb8aa3b, v95
	v_exp_f32_e32 v98, v98
	v_exp_f32_e32 v99, v99
	v_exp_f32_e32 v96, v96
	v_exp_f32_e32 v97, v97
	v_add_f32_e32 v98, 1.0, v98
	v_add_f32_e32 v99, 1.0, v99
	v_add_f32_e32 v96, 1.0, v96
	v_add_f32_e32 v97, 1.0, v97
	v_rcp_f32_e32 v98, v98
	v_rcp_f32_e32 v99, v99
	v_rcp_f32_e32 v96, v96
	v_rcp_f32_e32 v97, v97
	v_pk_mul_f32 v[84:85], v[84:85], v[156:157] op_sel_hi:[1,0]
	v_pk_mul_f32 v[92:93], v[92:93], v[98:99]
	v_pk_mul_f32 v[90:91], v[90:91], v[156:157] op_sel_hi:[1,0]
	v_pk_mul_f32 v[94:95], v[94:95], v[96:97]
	v_pk_mul_f32 v[86:87], v[86:87], v[92:93]
	v_mul_f32_e32 v92, 0xbfb8aa3b, v88
	v_mul_f32_e32 v93, 0xbfb8aa3b, v89
	v_pk_mul_f32 v[84:85], v[84:85], v[94:95]
	v_exp_f32_e32 v92, v92
	v_exp_f32_e32 v93, v93
	v_mul_f32_e32 v94, 0xbfb8aa3b, v90
	v_mul_f32_e32 v95, 0xbfb8aa3b, v91
	v_exp_f32_e32 v94, v94
	v_exp_f32_e32 v95, v95
	v_add_f32_e32 v92, 1.0, v92
	v_add_f32_e32 v93, 1.0, v93
	v_rcp_f32_e32 v92, v92
	v_rcp_f32_e32 v93, v93
	v_add_f32_e32 v94, 1.0, v94
	v_add_f32_e32 v95, 1.0, v95
	v_rcp_f32_e32 v94, v94
	v_rcp_f32_e32 v95, v95
	v_pk_mul_f32 v[76:77], v[76:77], v[156:157] op_sel_hi:[1,0]
	v_pk_mul_f32 v[88:89], v[88:89], v[92:93]
	v_pk_mul_f32 v[78:79], v[78:79], v[156:157] op_sel_hi:[1,0]
	v_pk_mul_f32 v[88:89], v[76:77], v[88:89]
	v_pk_mul_f32 v[76:77], v[90:91], v[94:95]
	v_or_b32_e32 v92, 32, v144
	v_pk_mul_f32 v[90:91], v[78:79], v[76:77]
	v_cvt_pk_bf16_f32 v76, v84, v85
	v_mad_i64_i32 v[84:85], s[28:29], v92, s68, v[108:109]
	v_cvt_pk_bf16_f32 v77, v86, v87
	v_cvt_pk_bf16_f32 v78, v88, v89
	v_cvt_pk_bf16_f32 v79, v90, v91
	v_lshl_add_u64 v[84:85], v[84:85], 0, v[110:111]
	global_store_dwordx4 v[84:85], v[76:79], off
	v_pk_mul_f32 v[70:71], v[70:71], v[154:155] op_sel_hi:[1,0]
	v_pk_mul_f32 v[72:73], v[72:73], v[154:155] op_sel_hi:[1,0]
	v_pk_mul_f32 v[76:77], v[82:83], v[154:155] op_sel_hi:[1,0]
	v_pk_mul_f32 v[78:79], v[80:81], v[154:155] op_sel_hi:[1,0]
	v_mul_f32_e32 v82, 0xbfb8aa3b, v76
	v_mul_f32_e32 v83, 0xbfb8aa3b, v77
	v_mul_f32_e32 v80, 0xbfb8aa3b, v78
	v_mul_f32_e32 v81, 0xbfb8aa3b, v79
	v_exp_f32_e32 v82, v82
	v_exp_f32_e32 v83, v83
	v_exp_f32_e32 v80, v80
	v_exp_f32_e32 v81, v81
	v_add_f32_e32 v82, 1.0, v82
	v_add_f32_e32 v83, 1.0, v83
	v_add_f32_e32 v80, 1.0, v80
	v_add_f32_e32 v81, 1.0, v81
	v_rcp_f32_e32 v82, v82
	v_rcp_f32_e32 v83, v83
	v_rcp_f32_e32 v80, v80
	v_rcp_f32_e32 v81, v81
	v_pk_mul_f32 v[68:69], v[68:69], v[154:155] op_sel_hi:[1,0]
	v_pk_mul_f32 v[76:77], v[76:77], v[82:83]
	v_pk_mul_f32 v[74:75], v[74:75], v[154:155] op_sel_hi:[1,0]
	v_pk_mul_f32 v[78:79], v[78:79], v[80:81]
	v_pk_mul_f32 v[70:71], v[70:71], v[76:77]
	v_mul_f32_e32 v76, 0xbfb8aa3b, v72
	v_mul_f32_e32 v77, 0xbfb8aa3b, v73
	v_pk_mul_f32 v[68:69], v[68:69], v[78:79]
	v_exp_f32_e32 v76, v76
	v_exp_f32_e32 v77, v77
	v_mul_f32_e32 v78, 0xbfb8aa3b, v74
	v_mul_f32_e32 v79, 0xbfb8aa3b, v75
	v_exp_f32_e32 v78, v78
	v_exp_f32_e32 v79, v79
	v_add_f32_e32 v76, 1.0, v76
	v_add_f32_e32 v77, 1.0, v77
	v_rcp_f32_e32 v76, v76
	v_rcp_f32_e32 v77, v77
	v_add_f32_e32 v78, 1.0, v78
	v_add_f32_e32 v79, 1.0, v79
	v_rcp_f32_e32 v78, v78
	v_rcp_f32_e32 v79, v79
	v_pk_mul_f32 v[64:65], v[64:65], v[154:155] op_sel_hi:[1,0]
	v_pk_mul_f32 v[72:73], v[72:73], v[76:77]
	v_pk_mul_f32 v[66:67], v[66:67], v[154:155] op_sel_hi:[1,0]
	v_pk_mul_f32 v[72:73], v[64:65], v[72:73]
	v_pk_mul_f32 v[64:65], v[74:75], v[78:79]
	v_or_b32_e32 v76, 48, v144
	v_pk_mul_f32 v[74:75], v[66:67], v[64:65]
	v_cvt_pk_bf16_f32 v64, v68, v69
	v_mad_i64_i32 v[68:69], s[28:29], v76, s68, v[108:109]
	v_cvt_pk_bf16_f32 v65, v70, v71
	v_cvt_pk_bf16_f32 v66, v72, v73
	v_cvt_pk_bf16_f32 v67, v74, v75
	v_lshl_add_u64 v[68:69], v[68:69], 0, v[110:111]
	v_pk_mul_f32 v[60:61], v[60:61], v[152:153] op_sel_hi:[1,0]
	global_store_dwordx4 v[68:69], v[64:67], off
	v_pk_mul_f32 v[62:63], v[62:63], v[152:153] op_sel_hi:[1,0]
	v_pk_mul_f32 v[52:53], v[52:53], v[152:153] op_sel_hi:[1,0]
	v_mul_f32_e32 v64, 0xbfb8aa3b, v60
	v_mul_f32_e32 v65, 0xbfb8aa3b, v61
	v_exp_f32_e32 v64, v64
	v_exp_f32_e32 v65, v65
	v_mul_f32_e32 v66, 0xbfb8aa3b, v62
	v_mul_f32_e32 v67, 0xbfb8aa3b, v63
	v_exp_f32_e32 v66, v66
	v_exp_f32_e32 v67, v67
	v_add_f32_e32 v64, 1.0, v64
	v_add_f32_e32 v65, 1.0, v65
	v_rcp_f32_e32 v64, v64
	v_rcp_f32_e32 v65, v65
	v_add_f32_e32 v66, 1.0, v66
	v_add_f32_e32 v67, 1.0, v67
	v_rcp_f32_e32 v66, v66
	v_rcp_f32_e32 v67, v67
	v_pk_mul_f32 v[60:61], v[60:61], v[64:65]
	v_pk_mul_f32 v[54:55], v[54:55], v[152:153] op_sel_hi:[1,0]
	v_pk_mul_f32 v[52:53], v[52:53], v[60:61]
	v_pk_mul_f32 v[60:61], v[62:63], v[66:67]
	v_pk_mul_f32 v[56:57], v[56:57], v[152:153] op_sel_hi:[1,0]
	v_pk_mul_f32 v[54:55], v[54:55], v[60:61]
	v_pk_mul_f32 v[58:59], v[58:59], v[152:153] op_sel_hi:[1,0]
	v_mul_f32_e32 v60, 0xbfb8aa3b, v56
	v_mul_f32_e32 v61, 0xbfb8aa3b, v57
	v_exp_f32_e32 v60, v60
	v_exp_f32_e32 v61, v61
	v_mul_f32_e32 v62, 0xbfb8aa3b, v58
	v_mul_f32_e32 v63, 0xbfb8aa3b, v59
	v_exp_f32_e32 v62, v62
	v_exp_f32_e32 v63, v63
	v_add_f32_e32 v60, 1.0, v60
	v_add_f32_e32 v61, 1.0, v61
	v_rcp_f32_e32 v60, v60
	v_rcp_f32_e32 v61, v61
	v_add_f32_e32 v62, 1.0, v62
	v_add_f32_e32 v63, 1.0, v63
	v_rcp_f32_e32 v62, v62
	v_rcp_f32_e32 v63, v63
	v_fmamk_f32 v150, v150, 0x3a800000, v168
	v_rsq_f32_e32 v150, v150
	v_pk_mul_f32 v[44:45], v[44:45], v[152:153] op_sel_hi:[1,0]
	v_pk_mul_f32 v[56:57], v[56:57], v[60:61]
	v_pk_mul_f32 v[46:47], v[46:47], v[152:153] op_sel_hi:[1,0]
	v_pk_mul_f32 v[56:57], v[44:45], v[56:57]
	v_pk_mul_f32 v[44:45], v[58:59], v[62:63]
	v_pk_mul_f32 v[38:39], v[38:39], v[150:151] op_sel_hi:[1,0]
	v_pk_mul_f32 v[58:59], v[46:47], v[44:45]
	v_cvt_pk_bf16_f32 v44, v52, v53
	v_mad_i64_i32 v[52:53], s[28:29], v145, s68, v[108:109]
	v_cvt_pk_bf16_f32 v45, v54, v55
	v_cvt_pk_bf16_f32 v46, v56, v57
	v_cvt_pk_bf16_f32 v47, v58, v59
	v_lshl_add_u64 v[52:53], v[52:53], 0, v[110:111]
	global_store_dwordx4 v[52:53], v[44:47], off
	v_pk_mul_f32 v[40:41], v[40:41], v[150:151] op_sel_hi:[1,0]
	v_pk_mul_f32 v[36:37], v[36:37], v[150:151] op_sel_hi:[1,0]
	v_pk_mul_f32 v[44:45], v[50:51], v[150:151] op_sel_hi:[1,0]
	v_pk_mul_f32 v[46:47], v[48:49], v[150:151] op_sel_hi:[1,0]
	v_mul_f32_e32 v50, 0xbfb8aa3b, v44
	v_mul_f32_e32 v51, 0xbfb8aa3b, v45
	v_mul_f32_e32 v48, 0xbfb8aa3b, v46
	v_mul_f32_e32 v49, 0xbfb8aa3b, v47
	v_exp_f32_e32 v50, v50
	v_exp_f32_e32 v51, v51
	v_exp_f32_e32 v48, v48
	v_exp_f32_e32 v49, v49
	v_add_f32_e32 v50, 1.0, v50
	v_add_f32_e32 v51, 1.0, v51
	v_add_f32_e32 v48, 1.0, v48
	v_add_f32_e32 v49, 1.0, v49
	v_rcp_f32_e32 v50, v50
	v_rcp_f32_e32 v51, v51
	v_rcp_f32_e32 v48, v48
	v_rcp_f32_e32 v49, v49
	v_pk_mul_f32 v[42:43], v[42:43], v[150:151] op_sel_hi:[1,0]
	v_pk_mul_f32 v[44:45], v[44:45], v[50:51]
	v_fmamk_f32 v148, v148, 0x3a800000, v168
	v_pk_mul_f32 v[46:47], v[46:47], v[48:49]
	v_pk_mul_f32 v[38:39], v[38:39], v[44:45]
	v_mul_f32_e32 v44, 0xbfb8aa3b, v40
	v_mul_f32_e32 v45, 0xbfb8aa3b, v41
	v_pk_mul_f32 v[36:37], v[36:37], v[46:47]
	v_exp_f32_e32 v44, v44
	v_exp_f32_e32 v45, v45
	v_mul_f32_e32 v46, 0xbfb8aa3b, v42
	v_mul_f32_e32 v47, 0xbfb8aa3b, v43
	v_exp_f32_e32 v46, v46
	v_exp_f32_e32 v47, v47
	v_add_f32_e32 v44, 1.0, v44
	v_add_f32_e32 v45, 1.0, v45
	v_rcp_f32_e32 v44, v44
	v_rcp_f32_e32 v45, v45
	v_add_f32_e32 v46, 1.0, v46
	v_add_f32_e32 v47, 1.0, v47
	v_rcp_f32_e32 v46, v46
	v_rcp_f32_e32 v47, v47
	v_rsq_f32_e32 v148, v148
	v_pk_mul_f32 v[28:29], v[28:29], v[150:151] op_sel_hi:[1,0]
	v_pk_mul_f32 v[40:41], v[40:41], v[44:45]
	v_pk_mul_f32 v[30:31], v[30:31], v[150:151] op_sel_hi:[1,0]
	v_pk_mul_f32 v[40:41], v[28:29], v[40:41]
	v_pk_mul_f32 v[28:29], v[42:43], v[46:47]
	v_add_u32_e32 v44, 0x90, v144
	v_pk_mul_f32 v[42:43], v[30:31], v[28:29]
	v_cvt_pk_bf16_f32 v28, v36, v37
	v_mad_i64_i32 v[36:37], s[28:29], v44, s68, v[108:109]
	v_cvt_pk_bf16_f32 v29, v38, v39
	v_cvt_pk_bf16_f32 v30, v40, v41
	v_cvt_pk_bf16_f32 v31, v42, v43
	v_lshl_add_u64 v[36:37], v[36:37], 0, v[110:111]
	global_store_dwordx4 v[36:37], v[28:31], off
	v_pk_mul_f32 v[22:23], v[22:23], v[148:149] op_sel_hi:[1,0]
	v_pk_mul_f32 v[24:25], v[24:25], v[148:149] op_sel_hi:[1,0]
	v_pk_mul_f32 v[28:29], v[34:35], v[148:149] op_sel_hi:[1,0]
	v_pk_mul_f32 v[30:31], v[32:33], v[148:149] op_sel_hi:[1,0]
	v_mul_f32_e32 v34, 0xbfb8aa3b, v28
	v_mul_f32_e32 v35, 0xbfb8aa3b, v29
	v_mul_f32_e32 v32, 0xbfb8aa3b, v30
	v_mul_f32_e32 v33, 0xbfb8aa3b, v31
	v_exp_f32_e32 v34, v34
	v_exp_f32_e32 v35, v35
	v_exp_f32_e32 v32, v32
	v_exp_f32_e32 v33, v33
	v_add_f32_e32 v34, 1.0, v34
	v_add_f32_e32 v35, 1.0, v35
	v_add_f32_e32 v32, 1.0, v32
	v_add_f32_e32 v33, 1.0, v33
	v_rcp_f32_e32 v34, v34
	v_rcp_f32_e32 v35, v35
	v_rcp_f32_e32 v32, v32
	v_rcp_f32_e32 v33, v33
	v_pk_mul_f32 v[20:21], v[20:21], v[148:149] op_sel_hi:[1,0]
	v_pk_mul_f32 v[28:29], v[28:29], v[34:35]
	v_pk_mul_f32 v[26:27], v[26:27], v[148:149] op_sel_hi:[1,0]
	v_pk_mul_f32 v[30:31], v[30:31], v[32:33]
	v_pk_mul_f32 v[22:23], v[22:23], v[28:29]
	v_mul_f32_e32 v28, 0xbfb8aa3b, v24
	v_mul_f32_e32 v29, 0xbfb8aa3b, v25
	v_pk_mul_f32 v[20:21], v[20:21], v[30:31]
	v_exp_f32_e32 v28, v28
	v_exp_f32_e32 v29, v29
	v_mul_f32_e32 v30, 0xbfb8aa3b, v26
	v_mul_f32_e32 v31, 0xbfb8aa3b, v27
	v_exp_f32_e32 v30, v30
	v_exp_f32_e32 v31, v31
	v_add_f32_e32 v28, 1.0, v28
	v_add_f32_e32 v29, 1.0, v29
	v_rcp_f32_e32 v28, v28
	v_rcp_f32_e32 v29, v29
	v_add_f32_e32 v30, 1.0, v30
	v_add_f32_e32 v31, 1.0, v31
	v_rcp_f32_e32 v30, v30
	v_rcp_f32_e32 v31, v31
	v_fmamk_f32 v146, v146, 0x3a800000, v168
	v_rsq_f32_e32 v146, v146
	v_pk_mul_f32 v[12:13], v[12:13], v[148:149] op_sel_hi:[1,0]
	v_pk_mul_f32 v[24:25], v[24:25], v[28:29]
	v_pk_mul_f32 v[14:15], v[14:15], v[148:149] op_sel_hi:[1,0]
	v_pk_mul_f32 v[24:25], v[12:13], v[24:25]
	v_pk_mul_f32 v[12:13], v[26:27], v[30:31]
	v_add_u32_e32 v28, 0xa0, v144
	v_pk_mul_f32 v[26:27], v[14:15], v[12:13]
	v_cvt_pk_bf16_f32 v12, v20, v21
	v_mad_i64_i32 v[20:21], s[28:29], v28, s68, v[108:109]
	v_cvt_pk_bf16_f32 v13, v22, v23
	v_cvt_pk_bf16_f32 v14, v24, v25
	v_cvt_pk_bf16_f32 v15, v26, v27
	v_lshl_add_u64 v[20:21], v[20:21], 0, v[110:111]
	global_store_dwordx4 v[20:21], v[12:15], off
	v_pk_mul_f32 v[6:7], v[6:7], v[146:147] op_sel_hi:[1,0]
	v_pk_mul_f32 v[8:9], v[8:9], v[146:147] op_sel_hi:[1,0]
	v_pk_mul_f32 v[12:13], v[18:19], v[146:147] op_sel_hi:[1,0]
	v_pk_mul_f32 v[14:15], v[16:17], v[146:147] op_sel_hi:[1,0]
	v_mul_f32_e32 v18, 0xbfb8aa3b, v12
	v_mul_f32_e32 v19, 0xbfb8aa3b, v13
	v_mul_f32_e32 v16, 0xbfb8aa3b, v14
	v_mul_f32_e32 v17, 0xbfb8aa3b, v15
	v_exp_f32_e32 v18, v18
	v_exp_f32_e32 v19, v19
	v_exp_f32_e32 v16, v16
	v_exp_f32_e32 v17, v17
	v_add_f32_e32 v18, 1.0, v18
	v_add_f32_e32 v19, 1.0, v19
	v_add_f32_e32 v16, 1.0, v16
	v_add_f32_e32 v17, 1.0, v17
	v_rcp_f32_e32 v18, v18
	v_rcp_f32_e32 v19, v19
	v_rcp_f32_e32 v16, v16
	v_rcp_f32_e32 v17, v17
	v_pk_mul_f32 v[4:5], v[4:5], v[146:147] op_sel_hi:[1,0]
	v_pk_mul_f32 v[12:13], v[12:13], v[18:19]
	v_pk_mul_f32 v[10:11], v[10:11], v[146:147] op_sel_hi:[1,0]
	v_pk_mul_f32 v[14:15], v[14:15], v[16:17]
	v_pk_mul_f32 v[6:7], v[6:7], v[12:13]
	v_mul_f32_e32 v12, 0xbfb8aa3b, v8
	v_mul_f32_e32 v13, 0xbfb8aa3b, v9
	v_pk_mul_f32 v[4:5], v[4:5], v[14:15]
	v_exp_f32_e32 v12, v12
	v_exp_f32_e32 v13, v13
	v_mul_f32_e32 v14, 0xbfb8aa3b, v10
	v_mul_f32_e32 v15, 0xbfb8aa3b, v11
	v_exp_f32_e32 v14, v14
	v_exp_f32_e32 v15, v15
	v_add_f32_e32 v12, 1.0, v12
	v_add_f32_e32 v13, 1.0, v13
	v_rcp_f32_e32 v12, v12
	v_rcp_f32_e32 v13, v13
	v_add_f32_e32 v14, 1.0, v14
	v_add_f32_e32 v15, 1.0, v15
	v_rcp_f32_e32 v14, v14
	v_rcp_f32_e32 v15, v15
	v_pk_mul_f32 v[0:1], v[0:1], v[146:147] op_sel_hi:[1,0]
	v_pk_mul_f32 v[8:9], v[8:9], v[12:13]
	v_pk_mul_f32 v[2:3], v[2:3], v[146:147] op_sel_hi:[1,0]
	v_pk_mul_f32 v[8:9], v[0:1], v[8:9]
	v_pk_mul_f32 v[0:1], v[10:11], v[14:15]
	v_add_u32_e32 v12, 0xb0, v144
	v_pk_mul_f32 v[10:11], v[2:3], v[0:1]
	v_cvt_pk_bf16_f32 v0, v4, v5
	v_mad_i64_i32 v[4:5], s[28:29], v12, s68, v[108:109]
	v_cvt_pk_bf16_f32 v1, v6, v7
	v_cvt_pk_bf16_f32 v2, v8, v9
	v_cvt_pk_bf16_f32 v3, v10, v11
	v_lshl_add_u64 v[4:5], v[4:5], 0, v[110:111]
	global_store_dwordx4 v[4:5], v[0:3], off
	s_cbranch_scc1 .LBB0_1226
	s_waitcnt vmcnt(0)
	buffer_wbl2 sc1
	s_waitcnt vmcnt(0)
	s_waitcnt vmcnt(0)
	s_and_saveexec_b64 s[28:29], s[4:5]
	s_cbranch_execz .LBB0_1225
	s_mov_b64 s[30:31], exec
	v_mbcnt_lo_u32_b32 v0, s30, 0
	v_mbcnt_hi_u32_b32 v0, s31, v0
	v_cmp_eq_u32_e32 vcc, 0, v0
	s_and_b64 s[34:35], exec, vcc
	s_mov_b64 exec, s[34:35]
	s_cbranch_execz .LBB0_1225
	s_bcnt1_i32_b64 s11, s[30:31]
	v_mov_b32_e32 v0, s11
	global_atomic_add v129, v0, s[8:9]
	s_branch .LBB0_1225

.LBB0_1268:
	s_add_u32 s14, s10, s12
	ds_read_b128 v[144:147], v138
	ds_read_b128 v[148:151], v138 offset:1024
	ds_read_b128 v[152:155], v138 offset:2048
	ds_read_b128 v[156:159], v138 offset:3072
	s_addc_u32 s15, s11, s13
	s_add_u32 s14, s14, 0x11424100
	s_addc_u32 s15, s15, 0
	s_add_u32 s46, s41, s12
	s_addc_u32 s47, s42, s13
	s_cmpk_eq_i32 s12, 0x1500
	s_cselect_b32 s17, s5, s15
	s_cselect_b32 s16, s4, s14
	s_cselect_b32 s15, s7, s47
	s_cselect_b32 s14, s6, s46
	s_mov_b32 m0, s44
	v_lshl_add_u64 v[192:193], v[132:133], 0, s[12:13]
	ds_read_b128 v[160:163], v139
	ds_read_b128 v[164:167], v139 offset:1024
	ds_read_b128 v[168:171], v139 offset:2048
	ds_read_b128 v[172:175], v139 offset:3072
	ds_read_b128 v[176:179], v139 offset:4096
	ds_read_b128 v[180:183], v139 offset:5120
	ds_read_b128 v[184:187], v139 offset:6144
	ds_read_b128 v[188:191], v139 offset:7168
	global_load_lds_dwordx4 v[192:193], off
	v_lshl_add_u64 v[192:193], v[134:135], 0, s[12:13]
	s_mov_b32 m0, s45
	s_nop 0
	global_load_lds_dwordx4 v[192:193], off
	ds_read_b128 v[192:195], v140
	ds_read_b128 v[196:199], v140 offset:1024
	ds_read_b128 v[204:207], v140 offset:2048
	ds_read_b128 v[208:211], v140 offset:3072
	s_waitcnt lgkmcnt(0)
	s_waitcnt vmcnt(8)
	s_barrier
	s_setprio 1
	v_mfma_f32_16x16x32_bf16 v[124:127], v[144:147], v[160:163], v[124:127]
	v_mfma_f32_16x16x32_bf16 v[120:123], v[152:155], v[160:163], v[120:123]
	v_mfma_f32_16x16x32_bf16 v[116:119], v[144:147], v[168:171], v[116:119]
	v_mfma_f32_16x16x32_bf16 v[112:115], v[152:155], v[168:171], v[112:115]
	v_mfma_f32_16x16x32_bf16 v[92:95], v[144:147], v[176:179], v[92:95]
	v_mfma_f32_16x16x32_bf16 v[88:91], v[152:155], v[176:179], v[88:91]
	v_mfma_f32_16x16x32_bf16 v[76:79], v[144:147], v[184:187], v[76:79]
	v_mfma_f32_16x16x32_bf16 v[72:75], v[152:155], v[184:187], v[72:75]
	v_mfma_f32_16x16x32_bf16 v[124:127], v[148:151], v[164:167], v[124:127]
	v_mfma_f32_16x16x32_bf16 v[120:123], v[156:159], v[164:167], v[120:123]
	v_mfma_f32_16x16x32_bf16 v[116:119], v[148:151], v[172:175], v[116:119]
	v_mfma_f32_16x16x32_bf16 v[112:115], v[156:159], v[172:175], v[112:115]
	v_mfma_f32_16x16x32_bf16 v[92:95], v[148:151], v[180:183], v[92:95]
	v_mfma_f32_16x16x32_bf16 v[88:91], v[156:159], v[180:183], v[88:91]
	v_mfma_f32_16x16x32_bf16 v[76:79], v[148:151], v[188:191], v[76:79]
	v_mfma_f32_16x16x32_bf16 v[72:75], v[156:159], v[188:191], v[72:75]
	v_mfma_f32_16x16x32_bf16 v[108:111], v[192:195], v[160:163], v[108:111]
	v_mfma_f32_16x16x32_bf16 v[104:107], v[204:207], v[160:163], v[104:107]
	v_mfma_f32_16x16x32_bf16 v[100:103], v[192:195], v[168:171], v[100:103]
	v_mfma_f32_16x16x32_bf16 v[96:99], v[204:207], v[168:171], v[96:99]
	v_mfma_f32_16x16x32_bf16 v[84:87], v[192:195], v[176:179], v[84:87]
	v_mfma_f32_16x16x32_bf16 v[80:83], v[204:207], v[176:179], v[80:83]
	v_mfma_f32_16x16x32_bf16 v[68:71], v[192:195], v[184:187], v[68:71]
	v_mfma_f32_16x16x32_bf16 v[64:67], v[204:207], v[184:187], v[64:67]
	v_mfma_f32_16x16x32_bf16 v[108:111], v[196:199], v[164:167], v[108:111]
	v_mfma_f32_16x16x32_bf16 v[104:107], v[208:211], v[164:167], v[104:107]
	v_mfma_f32_16x16x32_bf16 v[100:103], v[196:199], v[172:175], v[100:103]
	v_mfma_f32_16x16x32_bf16 v[96:99], v[208:211], v[172:175], v[96:99]
	v_mfma_f32_16x16x32_bf16 v[84:87], v[196:199], v[180:183], v[84:87]
	v_mfma_f32_16x16x32_bf16 v[80:83], v[208:211], v[180:183], v[80:83]
	v_mfma_f32_16x16x32_bf16 v[68:71], v[196:199], v[188:191], v[68:71]
	v_mfma_f32_16x16x32_bf16 v[64:67], v[208:211], v[188:191], v[64:67]
	s_setprio 0
	s_barrier
	ds_read_b128 v[160:163], v139 offset:16384
	ds_read_b128 v[164:167], v139 offset:17408
	ds_read_b128 v[168:171], v139 offset:18432
	ds_read_b128 v[172:175], v139 offset:19456
	ds_read_b128 v[176:179], v139 offset:20480
	ds_read_b128 v[180:183], v139 offset:21504
	ds_read_b128 v[184:187], v139 offset:22528
	ds_read_b128 v[188:191], v139 offset:23552
	s_mov_b32 m0, s25
	v_lshl_add_u64 v[200:201], s[14:15], 0, v[130:131]
	global_load_lds_dwordx4 v[200:201], off
	v_lshl_add_u64 v[212:213], s[14:15], 0, v[128:129]
	s_mov_b32 m0, s26
	s_nop 0
	global_load_lds_dwordx4 v[212:213], off
	s_mov_b32 m0, s27
	v_lshl_add_u64 v[214:215], s[16:17], 0, v[130:131]
	global_load_lds_dwordx4 v[214:215], off
	v_lshl_add_u64 v[216:217], s[16:17], 0, v[128:129]
	s_mov_b32 m0, s28
	s_nop 0
	global_load_lds_dwordx4 v[216:217], off
	s_add_u32 s46, s14, 0xb0000
	s_addc_u32 s47, s15, 0
	s_mov_b32 m0, s29
	v_lshl_add_u64 v[248:249], s[46:47], 0, v[130:131]
	global_load_lds_dwordx4 v[248:249], off
	v_lshl_add_u64 v[248:249], s[46:47], 0, v[128:129]
	s_mov_b32 m0, s30
	s_nop 0
	global_load_lds_dwordx4 v[248:249], off
	s_waitcnt lgkmcnt(0)
	s_waitcnt vmcnt(8)
	s_barrier
	s_setprio 1
	v_mfma_f32_16x16x32_bf16 v[60:63], v[144:147], v[160:163], v[60:63]
	v_mfma_f32_16x16x32_bf16 v[56:59], v[152:155], v[160:163], v[56:59]
	v_mfma_f32_16x16x32_bf16 v[44:47], v[144:147], v[168:171], v[44:47]
	v_mfma_f32_16x16x32_bf16 v[40:43], v[152:155], v[168:171], v[40:43]
	v_mfma_f32_16x16x32_bf16 v[28:31], v[144:147], v[176:179], v[28:31]
	v_mfma_f32_16x16x32_bf16 v[24:27], v[152:155], v[176:179], v[24:27]
	v_mfma_f32_16x16x32_bf16 v[12:15], v[144:147], v[184:187], v[12:15]
	v_mfma_f32_16x16x32_bf16 v[8:11], v[152:155], v[184:187], v[8:11]
	v_mfma_f32_16x16x32_bf16 v[60:63], v[148:151], v[164:167], v[60:63]
	v_mfma_f32_16x16x32_bf16 v[56:59], v[156:159], v[164:167], v[56:59]
	v_mfma_f32_16x16x32_bf16 v[44:47], v[148:151], v[172:175], v[44:47]
	v_mfma_f32_16x16x32_bf16 v[40:43], v[156:159], v[172:175], v[40:43]
	v_mfma_f32_16x16x32_bf16 v[28:31], v[148:151], v[180:183], v[28:31]
	v_mfma_f32_16x16x32_bf16 v[24:27], v[156:159], v[180:183], v[24:27]
	v_mfma_f32_16x16x32_bf16 v[12:15], v[148:151], v[188:191], v[12:15]
	v_mfma_f32_16x16x32_bf16 v[8:11], v[156:159], v[188:191], v[8:11]
	v_mfma_f32_16x16x32_bf16 v[52:55], v[192:195], v[160:163], v[52:55]
	v_mfma_f32_16x16x32_bf16 v[48:51], v[204:207], v[160:163], v[48:51]
	v_mfma_f32_16x16x32_bf16 v[36:39], v[192:195], v[168:171], v[36:39]
	v_mfma_f32_16x16x32_bf16 v[32:35], v[204:207], v[168:171], v[32:35]
	v_mfma_f32_16x16x32_bf16 v[20:23], v[192:195], v[176:179], v[20:23]
	v_mfma_f32_16x16x32_bf16 v[16:19], v[204:207], v[176:179], v[16:19]
	v_mfma_f32_16x16x32_bf16 v[4:7], v[192:195], v[184:187], v[4:7]
	v_mfma_f32_16x16x32_bf16 v[0:3], v[204:207], v[184:187], v[0:3]
	v_mfma_f32_16x16x32_bf16 v[52:55], v[196:199], v[164:167], v[52:55]
	v_mfma_f32_16x16x32_bf16 v[48:51], v[208:211], v[164:167], v[48:51]
	v_mfma_f32_16x16x32_bf16 v[36:39], v[196:199], v[172:175], v[36:39]
	v_mfma_f32_16x16x32_bf16 v[32:35], v[208:211], v[172:175], v[32:35]
	v_mfma_f32_16x16x32_bf16 v[20:23], v[196:199], v[180:183], v[20:23]
	v_mfma_f32_16x16x32_bf16 v[16:19], v[208:211], v[180:183], v[16:19]
	v_mfma_f32_16x16x32_bf16 v[4:7], v[196:199], v[188:191], v[4:7]
	v_mfma_f32_16x16x32_bf16 v[0:3], v[208:211], v[188:191], v[0:3]
	s_setprio 0
	s_barrier
	ds_read_b128 v[144:147], v141
	ds_read_b128 v[148:151], v141 offset:1024
	ds_read_b128 v[152:155], v141 offset:2048
	ds_read_b128 v[156:159], v141 offset:3072
	s_add_u32 s16, s16, 0xb0000
	s_addc_u32 s17, s17, 0
	s_mov_b32 m0, s31
	v_lshl_add_u64 v[192:193], s[16:17], 0, v[130:131]
	ds_read_b128 v[160:163], v139 offset:32768
	ds_read_b128 v[164:167], v139 offset:33792
	ds_read_b128 v[168:171], v139 offset:34816
	ds_read_b128 v[172:175], v139 offset:35840
	ds_read_b128 v[176:179], v139 offset:36864
	ds_read_b128 v[180:183], v139 offset:37888
	ds_read_b128 v[184:187], v139 offset:38912
	ds_read_b128 v[188:191], v139 offset:39936
	global_load_lds_dwordx4 v[192:193], off
	v_lshl_add_u64 v[192:193], s[16:17], 0, v[128:129]
	s_mov_b32 m0, s33
	s_nop 0
	global_load_lds_dwordx4 v[192:193], off
	ds_read_b128 v[192:195], v142
	ds_read_b128 v[196:199], v142 offset:1024
	ds_read_b128 v[204:207], v142 offset:2048
	ds_read_b128 v[208:211], v142 offset:3072
	s_waitcnt lgkmcnt(0)
	s_waitcnt vmcnt(8)
	s_barrier
	s_setprio 1
	v_mfma_f32_16x16x32_bf16 v[124:127], v[144:147], v[160:163], v[124:127]
	v_mfma_f32_16x16x32_bf16 v[120:123], v[152:155], v[160:163], v[120:123]
	v_mfma_f32_16x16x32_bf16 v[116:119], v[144:147], v[168:171], v[116:119]
	v_mfma_f32_16x16x32_bf16 v[112:115], v[152:155], v[168:171], v[112:115]
	v_mfma_f32_16x16x32_bf16 v[92:95], v[144:147], v[176:179], v[92:95]
	v_mfma_f32_16x16x32_bf16 v[88:91], v[152:155], v[176:179], v[88:91]
	v_mfma_f32_16x16x32_bf16 v[76:79], v[144:147], v[184:187], v[76:79]
	v_mfma_f32_16x16x32_bf16 v[72:75], v[152:155], v[184:187], v[72:75]
	v_mfma_f32_16x16x32_bf16 v[124:127], v[148:151], v[164:167], v[124:127]
	v_mfma_f32_16x16x32_bf16 v[120:123], v[156:159], v[164:167], v[120:123]
	v_mfma_f32_16x16x32_bf16 v[116:119], v[148:151], v[172:175], v[116:119]
	v_mfma_f32_16x16x32_bf16 v[112:115], v[156:159], v[172:175], v[112:115]
	v_mfma_f32_16x16x32_bf16 v[92:95], v[148:151], v[180:183], v[92:95]
	v_mfma_f32_16x16x32_bf16 v[88:91], v[156:159], v[180:183], v[88:91]
	v_mfma_f32_16x16x32_bf16 v[76:79], v[148:151], v[188:191], v[76:79]
	v_mfma_f32_16x16x32_bf16 v[72:75], v[156:159], v[188:191], v[72:75]
	v_mfma_f32_16x16x32_bf16 v[108:111], v[192:195], v[160:163], v[108:111]
	v_mfma_f32_16x16x32_bf16 v[104:107], v[204:207], v[160:163], v[104:107]
	v_mfma_f32_16x16x32_bf16 v[100:103], v[192:195], v[168:171], v[100:103]
	v_mfma_f32_16x16x32_bf16 v[96:99], v[204:207], v[168:171], v[96:99]
	v_mfma_f32_16x16x32_bf16 v[84:87], v[192:195], v[176:179], v[84:87]
	v_mfma_f32_16x16x32_bf16 v[80:83], v[204:207], v[176:179], v[80:83]
	v_mfma_f32_16x16x32_bf16 v[68:71], v[192:195], v[184:187], v[68:71]
	v_mfma_f32_16x16x32_bf16 v[64:67], v[204:207], v[184:187], v[64:67]
	v_mfma_f32_16x16x32_bf16 v[108:111], v[196:199], v[164:167], v[108:111]
	v_mfma_f32_16x16x32_bf16 v[104:107], v[208:211], v[164:167], v[104:107]
	v_mfma_f32_16x16x32_bf16 v[100:103], v[196:199], v[172:175], v[100:103]
	v_mfma_f32_16x16x32_bf16 v[96:99], v[208:211], v[172:175], v[96:99]
	v_mfma_f32_16x16x32_bf16 v[84:87], v[196:199], v[180:183], v[84:87]
	v_mfma_f32_16x16x32_bf16 v[80:83], v[208:211], v[180:183], v[80:83]
	v_mfma_f32_16x16x32_bf16 v[68:71], v[196:199], v[188:191], v[68:71]
	v_mfma_f32_16x16x32_bf16 v[64:67], v[208:211], v[188:191], v[64:67]
	s_setprio 0
	s_barrier
	ds_read_b128 v[160:163], v139 offset:49152
	ds_read_b128 v[164:167], v139 offset:50176
	ds_read_b128 v[168:171], v139 offset:51200
	ds_read_b128 v[172:175], v139 offset:52224
	ds_read_b128 v[176:179], v139 offset:53248
	ds_read_b128 v[180:183], v139 offset:54272
	ds_read_b128 v[184:187], v139 offset:55296
	ds_read_b128 v[188:191], v139 offset:56320
	s_mov_b32 m0, s35
	v_lshl_add_u64 v[200:201], v[200:201], 0, s[8:9]
	global_load_lds_dwordx4 v[200:201], off
	v_lshl_add_u64 v[200:201], v[212:213], 0, s[8:9]
	s_mov_b32 m0, s36
	s_nop 0
	global_load_lds_dwordx4 v[200:201], off
	s_mov_b32 m0, s37
	v_lshl_add_u64 v[200:201], v[214:215], 0, s[8:9]
	global_load_lds_dwordx4 v[200:201], off
	v_lshl_add_u64 v[200:201], v[216:217], 0, s[8:9]
	s_mov_b32 m0, s38
	s_nop 0
	global_load_lds_dwordx4 v[200:201], off
	s_add_u32 s14, s14, 0xb0080
	s_addc_u32 s15, s15, 0
	s_mov_b32 m0, s39
	v_lshl_add_u64 v[248:249], s[14:15], 0, v[130:131]
	global_load_lds_dwordx4 v[248:249], off
	v_lshl_add_u64 v[248:249], s[14:15], 0, v[128:129]
	s_mov_b32 m0, s40
	s_nop 0
	global_load_lds_dwordx4 v[248:249], off
	s_waitcnt lgkmcnt(0)
	s_waitcnt vmcnt(8)
	s_barrier
	s_setprio 1
	v_mfma_f32_16x16x32_bf16 v[60:63], v[144:147], v[160:163], v[60:63]
	v_mfma_f32_16x16x32_bf16 v[56:59], v[152:155], v[160:163], v[56:59]
	v_mfma_f32_16x16x32_bf16 v[44:47], v[144:147], v[168:171], v[44:47]
	v_mfma_f32_16x16x32_bf16 v[40:43], v[152:155], v[168:171], v[40:43]
	v_mfma_f32_16x16x32_bf16 v[28:31], v[144:147], v[176:179], v[28:31]
	v_mfma_f32_16x16x32_bf16 v[24:27], v[152:155], v[176:179], v[24:27]
	v_mfma_f32_16x16x32_bf16 v[12:15], v[144:147], v[184:187], v[12:15]
	v_mfma_f32_16x16x32_bf16 v[8:11], v[152:155], v[184:187], v[8:11]
	v_mfma_f32_16x16x32_bf16 v[60:63], v[148:151], v[164:167], v[60:63]
	v_mfma_f32_16x16x32_bf16 v[56:59], v[156:159], v[164:167], v[56:59]
	v_mfma_f32_16x16x32_bf16 v[44:47], v[148:151], v[172:175], v[44:47]
	v_mfma_f32_16x16x32_bf16 v[40:43], v[156:159], v[172:175], v[40:43]
	v_mfma_f32_16x16x32_bf16 v[28:31], v[148:151], v[180:183], v[28:31]
	v_mfma_f32_16x16x32_bf16 v[24:27], v[156:159], v[180:183], v[24:27]
	v_mfma_f32_16x16x32_bf16 v[12:15], v[148:151], v[188:191], v[12:15]
	v_mfma_f32_16x16x32_bf16 v[8:11], v[156:159], v[188:191], v[8:11]
	v_mfma_f32_16x16x32_bf16 v[52:55], v[192:195], v[160:163], v[52:55]
	v_mfma_f32_16x16x32_bf16 v[48:51], v[204:207], v[160:163], v[48:51]
	v_mfma_f32_16x16x32_bf16 v[36:39], v[192:195], v[168:171], v[36:39]
	v_mfma_f32_16x16x32_bf16 v[32:35], v[204:207], v[168:171], v[32:35]
	v_mfma_f32_16x16x32_bf16 v[20:23], v[192:195], v[176:179], v[20:23]
	v_mfma_f32_16x16x32_bf16 v[16:19], v[204:207], v[176:179], v[16:19]
	v_mfma_f32_16x16x32_bf16 v[4:7], v[192:195], v[184:187], v[4:7]
	v_mfma_f32_16x16x32_bf16 v[0:3], v[204:207], v[184:187], v[0:3]
	v_mfma_f32_16x16x32_bf16 v[52:55], v[196:199], v[164:167], v[52:55]
	v_mfma_f32_16x16x32_bf16 v[48:51], v[208:211], v[164:167], v[48:51]
	v_mfma_f32_16x16x32_bf16 v[36:39], v[196:199], v[172:175], v[36:39]
	v_mfma_f32_16x16x32_bf16 v[32:35], v[208:211], v[172:175], v[32:35]
	v_mfma_f32_16x16x32_bf16 v[20:23], v[196:199], v[180:183], v[20:23]
	v_mfma_f32_16x16x32_bf16 v[16:19], v[208:211], v[180:183], v[16:19]
	v_mfma_f32_16x16x32_bf16 v[4:7], v[196:199], v[188:191], v[4:7]
	v_mfma_f32_16x16x32_bf16 v[0:3], v[208:211], v[188:191], v[0:3]
	s_setprio 0
	s_add_i32 s43, s43, 2
	s_add_u32 s12, s12, 0x100
	s_addc_u32 s13, s13, 0
	s_cmp_gt_u32 s43, 41
	s_barrier
	s_cbranch_scc0 .LBB0_1268
	s_lshl_b32 s4, s24, 8
	s_lshl_b32 s5, s34, 6
	s_or_b32 s4, s5, s4
	v_or_b32_e32 v138, s4, v137
	v_mov_b32_e32 v139, 0
	v_lshl_add_u32 v146, s19, 8, v136
	v_lshlrev_b32_e32 v144, 1, v138
	v_mov_b32_e32 v145, v139
	v_mov_b32_e32 v147, v139
	v_lshl_add_u64 v[128:129], s[2:3], 0, v[144:145]
	v_lshlrev_b64 v[130:131], 11, v[146:147]
	v_lshl_add_u64 v[130:131], v[128:129], 0, v[130:131]
	v_or_b32_e32 v182, 16, v146
	v_mov_b32_e32 v183, v139
	global_load_dwordx4 v[150:153], v[130:131], off
	global_load_dwordx4 v[154:157], v[130:131], off offset:64
	v_lshlrev_b64 v[130:131], 11, v[182:183]
	v_lshl_add_u64 v[130:131], v[128:129], 0, v[130:131]
	global_load_dwordx4 v[158:161], v[130:131], off
	global_load_dwordx4 v[162:165], v[130:131], off offset:64
	v_or_b32_e32 v148, 32, v146
	v_mov_b32_e32 v149, v139
	v_lshlrev_b64 v[130:131], 11, v[148:149]
	v_lshl_add_u64 v[172:173], v[128:129], 0, v[130:131]
	v_add_u32_e32 v140, 0x80, v146
	v_mov_b32_e32 v141, v139
	global_load_dwordx4 v[166:169], v[172:173], off
	v_or_b32_e32 v142, 48, v146
	v_mov_b32_e32 v143, v139
	v_lshlrev_b64 v[134:135], 11, v[140:141]
	v_lshlrev_b64 v[136:137], 12, v[146:147]
	v_lshlrev_b64 v[132:133], 11, v[142:143]
	v_lshl_add_u64 v[134:135], s[2:3], 0, v[134:135]
	v_lshl_add_u64 v[170:171], s[20:21], 0, v[136:137]
	v_lshlrev_b64 v[136:137], 2, v[138:139]
	v_add_u32_e32 v138, 0x90, v146
	v_lshl_add_u64 v[130:131], v[134:135], 0, v[144:145]
	v_lshl_add_u64 v[184:185], v[170:171], 0, v[136:137]
	v_lshlrev_b64 v[170:171], 11, v[138:139]
	v_lshl_add_u64 v[178:179], v[128:129], 0, v[132:133]
	global_load_dwordx4 v[132:135], v[130:131], off
	s_nop 0
	global_load_dwordx4 v[128:131], v[130:131], off offset:64
	v_lshl_add_u64 v[186:187], s[2:3], 0, v[170:171]
	global_load_dwordx4 v[170:173], v[172:173], off offset:64
	s_nop 0
	global_load_dwordx4 v[174:177], v[178:179], off
	s_nop 0
	global_load_dwordx4 v[178:181], v[178:179], off offset:64
	v_lshl_add_u64 v[186:187], v[186:187], 0, v[144:145]
	s_cmpk_lt_u32 s18, 0x100
	s_waitcnt vmcnt(0)
	v_lshlrev_b32_e32 v188, 16, v150
	v_and_b32_e32 v189, 0xffff0000, v150
	v_lshlrev_b32_e32 v150, 16, v151
	v_and_b32_e32 v151, 0xffff0000, v151
	v_lshlrev_b32_e32 v190, 16, v152
	v_and_b32_e32 v191, 0xffff0000, v152
	v_lshlrev_b32_e32 v152, 16, v153
	v_and_b32_e32 v153, 0xffff0000, v153
	v_lshlrev_b32_e32 v192, 16, v154
	v_and_b32_e32 v193, 0xffff0000, v154
	v_lshlrev_b32_e32 v154, 16, v155
	v_and_b32_e32 v155, 0xffff0000, v155
	v_lshlrev_b32_e32 v194, 16, v156
	v_and_b32_e32 v195, 0xffff0000, v156
	v_lshlrev_b32_e32 v156, 16, v157
	v_and_b32_e32 v157, 0xffff0000, v157
	v_pk_add_f32 v[126:127], v[126:127], v[150:151]
	v_pk_add_f32 v[124:125], v[124:125], v[188:189]
	v_pk_add_f32 v[120:121], v[120:121], v[190:191]
	v_pk_add_f32 v[122:123], v[122:123], v[152:153]
	v_pk_add_f32 v[110:111], v[110:111], v[154:155]
	v_pk_add_f32 v[108:109], v[108:109], v[192:193]
	v_pk_add_f32 v[106:107], v[106:107], v[156:157]
	v_pk_add_f32 v[104:105], v[104:105], v[194:195]
	global_store_dwordx4 v[184:185], v[124:127], off nt
	global_store_dwordx4 v[184:185], v[120:123], off offset:16 nt
	global_store_dwordx4 v[184:185], v[108:111], off offset:128 nt
	global_store_dwordx4 v[184:185], v[104:107], off offset:144 nt
	v_lshlrev_b32_e32 v120, 16, v163
	v_and_b32_e32 v121, 0xffff0000, v163
	v_pk_add_f32 v[102:103], v[102:103], v[120:121]
	v_lshlrev_b32_e32 v120, 16, v164
	v_and_b32_e32 v121, 0xffff0000, v164
	global_load_dwordx4 v[108:111], v[186:187], off
	global_load_dwordx4 v[104:107], v[186:187], off offset:64
	v_pk_add_f32 v[96:97], v[96:97], v[120:121]
	v_lshlrev_b64 v[120:121], 12, v[182:183]
	v_lshlrev_b32_e32 v196, 16, v158
	v_and_b32_e32 v197, 0xffff0000, v158
	v_lshlrev_b32_e32 v158, 16, v159
	v_and_b32_e32 v159, 0xffff0000, v159
	v_lshlrev_b32_e32 v198, 16, v160
	v_and_b32_e32 v199, 0xffff0000, v160
	v_lshlrev_b32_e32 v160, 16, v161
	v_and_b32_e32 v161, 0xffff0000, v161
	v_lshl_add_u64 v[120:121], s[20:21], 0, v[120:121]
	v_lshlrev_b32_e32 v200, 16, v162
	v_pk_add_f32 v[118:119], v[118:119], v[158:159]
	v_pk_add_f32 v[116:117], v[116:117], v[196:197]
	v_pk_add_f32 v[114:115], v[114:115], v[160:161]
	v_pk_add_f32 v[112:113], v[112:113], v[198:199]
	v_and_b32_e32 v201, 0xffff0000, v162
	v_lshlrev_b32_e32 v122, 16, v165
	v_and_b32_e32 v123, 0xffff0000, v165
	v_lshl_add_u64 v[120:121], v[120:121], 0, v[136:137]
	v_pk_add_f32 v[100:101], v[100:101], v[200:201]
	v_pk_add_f32 v[98:99], v[98:99], v[122:123]
	global_store_dwordx4 v[120:121], v[116:119], off nt
	global_store_dwordx4 v[120:121], v[112:115], off offset:16 nt
	global_store_dwordx4 v[120:121], v[100:103], off offset:128 nt
	global_store_dwordx4 v[120:121], v[96:99], off offset:144 nt
	v_add_u32_e32 v112, 0xa0, v146
	v_mov_b32_e32 v113, v139
	v_lshlrev_b32_e32 v114, 16, v166
	v_and_b32_e32 v115, 0xffff0000, v166
	v_lshlrev_b64 v[96:97], 11, v[112:113]
	v_pk_add_f32 v[92:93], v[92:93], v[114:115]
	v_lshlrev_b32_e32 v114, 16, v168
	v_and_b32_e32 v115, 0xffff0000, v168
	v_lshl_add_u64 v[96:97], s[2:3], 0, v[96:97]
	v_pk_add_f32 v[88:89], v[88:89], v[114:115]
	v_lshlrev_b32_e32 v114, 16, v170
	v_and_b32_e32 v115, 0xffff0000, v170
	v_lshl_add_u64 v[96:97], v[96:97], 0, v[144:145]
	v_lshlrev_b32_e32 v116, 16, v167
	v_and_b32_e32 v117, 0xffff0000, v167
	v_pk_add_f32 v[84:85], v[84:85], v[114:115]
	v_lshlrev_b32_e32 v114, 16, v172
	v_and_b32_e32 v115, 0xffff0000, v172
	global_load_dwordx4 v[100:103], v[96:97], off
	s_nop 0
	global_load_dwordx4 v[96:99], v[96:97], off offset:64
	v_pk_add_f32 v[94:95], v[94:95], v[116:117]
	v_lshlrev_b32_e32 v116, 16, v169
	v_and_b32_e32 v117, 0xffff0000, v169
	v_pk_add_f32 v[80:81], v[80:81], v[114:115]
	v_lshlrev_b64 v[114:115], 12, v[148:149]
	v_pk_add_f32 v[90:91], v[90:91], v[116:117]
	v_lshlrev_b32_e32 v116, 16, v171
	v_and_b32_e32 v117, 0xffff0000, v171
	v_lshl_add_u64 v[114:115], s[20:21], 0, v[114:115]
	v_pk_add_f32 v[86:87], v[86:87], v[116:117]
	v_lshlrev_b32_e32 v116, 16, v173
	v_and_b32_e32 v117, 0xffff0000, v173
	v_lshl_add_u64 v[114:115], v[114:115], 0, v[136:137]
	v_pk_add_f32 v[82:83], v[82:83], v[116:117]
	global_store_dwordx4 v[114:115], v[92:95], off nt
	global_store_dwordx4 v[114:115], v[88:91], off offset:16 nt
	global_store_dwordx4 v[114:115], v[84:87], off offset:128 nt
	global_store_dwordx4 v[114:115], v[80:83], off offset:144 nt
	v_add_u32_e32 v88, 0xb0, v146
	v_mov_b32_e32 v89, v139
	v_lshlrev_b64 v[80:81], 11, v[88:89]
	v_lshl_add_u64 v[80:81], s[2:3], 0, v[80:81]
	v_lshl_add_u64 v[80:81], v[80:81], 0, v[144:145]
	global_load_dwordx4 v[84:87], v[80:81], off
	s_nop 0
	global_load_dwordx4 v[80:83], v[80:81], off offset:64
	v_lshlrev_b32_e32 v90, 16, v174
	v_and_b32_e32 v91, 0xffff0000, v174
	v_pk_add_f32 v[76:77], v[76:77], v[90:91]
	v_lshlrev_b32_e32 v90, 16, v176
	v_and_b32_e32 v91, 0xffff0000, v176
	v_pk_add_f32 v[72:73], v[72:73], v[90:91]
	v_lshlrev_b32_e32 v90, 16, v178
	v_and_b32_e32 v91, 0xffff0000, v178
	v_lshlrev_b32_e32 v92, 16, v175
	v_and_b32_e32 v93, 0xffff0000, v175
	v_pk_add_f32 v[68:69], v[68:69], v[90:91]
	v_lshlrev_b32_e32 v90, 16, v180
	v_and_b32_e32 v91, 0xffff0000, v180
	v_pk_add_f32 v[78:79], v[78:79], v[92:93]
	v_lshlrev_b32_e32 v92, 16, v177
	v_and_b32_e32 v93, 0xffff0000, v177
	v_pk_add_f32 v[64:65], v[64:65], v[90:91]
	v_lshlrev_b64 v[90:91], 12, v[142:143]
	v_pk_add_f32 v[74:75], v[74:75], v[92:93]
	v_lshlrev_b32_e32 v92, 16, v179
	v_and_b32_e32 v93, 0xffff0000, v179
	v_lshl_add_u64 v[90:91], s[20:21], 0, v[90:91]
	v_pk_add_f32 v[70:71], v[70:71], v[92:93]
	v_lshlrev_b32_e32 v92, 16, v181
	v_and_b32_e32 v93, 0xffff0000, v181
	v_lshl_add_u64 v[90:91], v[90:91], 0, v[136:137]
	v_pk_add_f32 v[66:67], v[66:67], v[92:93]
	global_store_dwordx4 v[90:91], v[76:79], off nt
	global_store_dwordx4 v[90:91], v[72:75], off offset:16 nt
	global_store_dwordx4 v[90:91], v[68:71], off offset:128 nt
	global_store_dwordx4 v[90:91], v[64:67], off offset:144 nt
	s_nop 1
	v_lshlrev_b32_e32 v64, 16, v132
	v_and_b32_e32 v65, 0xffff0000, v132
	v_pk_add_f32 v[60:61], v[60:61], v[64:65]
	v_lshlrev_b32_e32 v64, 16, v134
	v_and_b32_e32 v65, 0xffff0000, v134
	v_pk_add_f32 v[56:57], v[56:57], v[64:65]
	v_lshlrev_b32_e32 v64, 16, v128
	v_and_b32_e32 v65, 0xffff0000, v128
	v_lshlrev_b32_e32 v66, 16, v133
	v_and_b32_e32 v67, 0xffff0000, v133
	v_pk_add_f32 v[52:53], v[52:53], v[64:65]
	v_lshlrev_b32_e32 v64, 16, v130
	v_and_b32_e32 v65, 0xffff0000, v130
	v_pk_add_f32 v[62:63], v[62:63], v[66:67]
	v_lshlrev_b32_e32 v66, 16, v135
	v_and_b32_e32 v67, 0xffff0000, v135
	v_pk_add_f32 v[48:49], v[48:49], v[64:65]
	v_lshlrev_b64 v[64:65], 12, v[140:141]
	v_pk_add_f32 v[58:59], v[58:59], v[66:67]
	v_lshlrev_b32_e32 v66, 16, v129
	v_and_b32_e32 v67, 0xffff0000, v129
	v_lshl_add_u64 v[64:65], s[20:21], 0, v[64:65]
	v_pk_add_f32 v[54:55], v[54:55], v[66:67]
	v_lshlrev_b32_e32 v66, 16, v131
	v_and_b32_e32 v67, 0xffff0000, v131
	v_lshl_add_u64 v[64:65], v[64:65], 0, v[136:137]
	v_pk_add_f32 v[50:51], v[50:51], v[66:67]
	global_store_dwordx4 v[64:65], v[60:63], off nt
	global_store_dwordx4 v[64:65], v[56:59], off offset:16 nt
	global_store_dwordx4 v[64:65], v[52:55], off offset:128 nt
	global_store_dwordx4 v[64:65], v[48:51], off offset:144 nt
	s_waitcnt vmcnt(0)
	s_nop 0
	v_lshlrev_b32_e32 v48, 16, v108
	v_and_b32_e32 v49, 0xffff0000, v108
	v_pk_add_f32 v[44:45], v[44:45], v[48:49]
	v_lshlrev_b32_e32 v48, 16, v110
	v_and_b32_e32 v49, 0xffff0000, v110
	v_pk_add_f32 v[40:41], v[40:41], v[48:49]
	v_lshlrev_b32_e32 v48, 16, v104
	v_and_b32_e32 v49, 0xffff0000, v104
	v_lshlrev_b32_e32 v50, 16, v109
	v_and_b32_e32 v51, 0xffff0000, v109
	v_pk_add_f32 v[36:37], v[36:37], v[48:49]
	v_lshlrev_b32_e32 v48, 16, v106
	v_and_b32_e32 v49, 0xffff0000, v106
	v_pk_add_f32 v[46:47], v[46:47], v[50:51]
	v_lshlrev_b32_e32 v50, 16, v111
	v_and_b32_e32 v51, 0xffff0000, v111
	v_pk_add_f32 v[32:33], v[32:33], v[48:49]
	v_lshlrev_b64 v[48:49], 12, v[138:139]
	v_pk_add_f32 v[42:43], v[42:43], v[50:51]
	v_lshlrev_b32_e32 v50, 16, v105
	v_and_b32_e32 v51, 0xffff0000, v105
	v_lshl_add_u64 v[48:49], s[20:21], 0, v[48:49]
	v_pk_add_f32 v[38:39], v[38:39], v[50:51]
	v_lshlrev_b32_e32 v50, 16, v107
	v_and_b32_e32 v51, 0xffff0000, v107
	v_lshl_add_u64 v[48:49], v[48:49], 0, v[136:137]
	v_pk_add_f32 v[34:35], v[34:35], v[50:51]
	global_store_dwordx4 v[48:49], v[44:47], off nt
	global_store_dwordx4 v[48:49], v[40:43], off offset:16 nt
	global_store_dwordx4 v[48:49], v[36:39], off offset:128 nt
	global_store_dwordx4 v[48:49], v[32:35], off offset:144 nt
	s_nop 1
	v_lshlrev_b32_e32 v32, 16, v100
	v_and_b32_e32 v33, 0xffff0000, v100
	v_pk_add_f32 v[28:29], v[28:29], v[32:33]
	v_lshlrev_b32_e32 v32, 16, v102
	v_and_b32_e32 v33, 0xffff0000, v102
	v_pk_add_f32 v[24:25], v[24:25], v[32:33]
	v_lshlrev_b32_e32 v32, 16, v96
	v_and_b32_e32 v33, 0xffff0000, v96
	v_lshlrev_b32_e32 v34, 16, v101
	v_and_b32_e32 v35, 0xffff0000, v101
	v_pk_add_f32 v[20:21], v[20:21], v[32:33]
	v_lshlrev_b32_e32 v32, 16, v98
	v_and_b32_e32 v33, 0xffff0000, v98
	v_pk_add_f32 v[30:31], v[30:31], v[34:35]
	v_lshlrev_b32_e32 v34, 16, v103
	v_and_b32_e32 v35, 0xffff0000, v103
	v_pk_add_f32 v[16:17], v[16:17], v[32:33]
	v_lshlrev_b64 v[32:33], 12, v[112:113]
	v_pk_add_f32 v[26:27], v[26:27], v[34:35]
	v_lshlrev_b32_e32 v34, 16, v97
	v_and_b32_e32 v35, 0xffff0000, v97
	v_lshl_add_u64 v[32:33], s[20:21], 0, v[32:33]
	v_pk_add_f32 v[22:23], v[22:23], v[34:35]
	v_lshlrev_b32_e32 v34, 16, v99
	v_and_b32_e32 v35, 0xffff0000, v99
	v_lshl_add_u64 v[32:33], v[32:33], 0, v[136:137]
	v_pk_add_f32 v[18:19], v[18:19], v[34:35]
	global_store_dwordx4 v[32:33], v[28:31], off nt
	global_store_dwordx4 v[32:33], v[24:27], off offset:16 nt
	global_store_dwordx4 v[32:33], v[20:23], off offset:128 nt
	global_store_dwordx4 v[32:33], v[16:19], off offset:144 nt
	s_nop 1
	v_lshlrev_b32_e32 v16, 16, v84
	v_and_b32_e32 v17, 0xffff0000, v84
	v_pk_add_f32 v[12:13], v[12:13], v[16:17]
	v_lshlrev_b32_e32 v16, 16, v86
	v_and_b32_e32 v17, 0xffff0000, v86
	v_pk_add_f32 v[8:9], v[8:9], v[16:17]
	v_lshlrev_b32_e32 v16, 16, v80
	v_and_b32_e32 v17, 0xffff0000, v80
	v_lshlrev_b32_e32 v18, 16, v85
	v_and_b32_e32 v19, 0xffff0000, v85
	v_pk_add_f32 v[4:5], v[4:5], v[16:17]
	v_lshlrev_b32_e32 v16, 16, v82
	v_and_b32_e32 v17, 0xffff0000, v82
	v_pk_add_f32 v[14:15], v[14:15], v[18:19]
	v_lshlrev_b32_e32 v18, 16, v87
	v_and_b32_e32 v19, 0xffff0000, v87
	v_pk_add_f32 v[0:1], v[0:1], v[16:17]
	v_lshlrev_b64 v[16:17], 12, v[88:89]
	v_pk_add_f32 v[10:11], v[10:11], v[18:19]
	v_lshlrev_b32_e32 v18, 16, v81
	v_and_b32_e32 v19, 0xffff0000, v81
	v_lshl_add_u64 v[16:17], s[20:21], 0, v[16:17]
	v_pk_add_f32 v[6:7], v[6:7], v[18:19]
	v_lshlrev_b32_e32 v18, 16, v83
	v_and_b32_e32 v19, 0xffff0000, v83
	v_lshl_add_u64 v[16:17], v[16:17], 0, v[136:137]
	v_pk_add_f32 v[2:3], v[2:3], v[18:19]
	global_store_dwordx4 v[16:17], v[12:15], off nt
	global_store_dwordx4 v[16:17], v[8:11], off offset:16 nt
	global_store_dwordx4 v[16:17], v[4:7], off offset:128 nt
	global_store_dwordx4 v[16:17], v[0:3], off offset:144 nt
	s_waitcnt vmcnt(0)
	s_cbranch_scc0 .LBB0_1271
	s_barrier

.LBB0_1336:
	ds_read_b128 v[128:131], v162
	ds_read_b128 v[132:135], v162 offset:1024
	ds_read_b128 v[146:149], v162 offset:2048
	ds_read_b128 v[150:153], v162 offset:3072
	s_add_u32 s18, s16, 0xfff50080
	s_addc_u32 s19, s17, -1
	s_cmp_eq_u32 s54, 40
	s_cselect_b32 s23, s24, s19
	s_cselect_b32 s22, s25, s18
	s_cselect_b32 s19, s26, s53
	s_cselect_b32 s18, s27, s52
	v_lshl_add_u64 v[158:159], s[16:17], 0, v[140:141]
	s_add_i32 m0, s35, 0xc000
	ds_read_b128 v[154:157], v163
	ds_read_b128 v[168:171], v163 offset:1024
	ds_read_b128 v[172:175], v163 offset:2048
	ds_read_b128 v[176:179], v163 offset:3072
	ds_read_b128 v[180:183], v163 offset:4096
	ds_read_b128 v[184:187], v163 offset:5120
	ds_read_b128 v[188:191], v163 offset:6144
	ds_read_b128 v[192:195], v163 offset:7168
	global_load_lds_dwordx4 v[158:159], off
	v_lshl_add_u64 v[158:159], s[16:17], 0, v[142:143]
	s_add_i32 m0, s35, 0xe000
	s_nop 0
	global_load_lds_dwordx4 v[158:159], off
	ds_read_b128 v[196:199], v164
	ds_read_b128 v[200:203], v164 offset:1024
	ds_read_b128 v[204:207], v164 offset:2048
	ds_read_b128 v[208:211], v164 offset:3072
	s_waitcnt lgkmcnt(0)
	s_waitcnt vmcnt(8)
	s_barrier
	s_setprio 1
	v_mfma_f32_16x16x32_bf16 v[124:127], v[128:131], v[154:157], v[124:127]
	v_mfma_f32_16x16x32_bf16 v[120:123], v[146:149], v[154:157], v[120:123]
	v_mfma_f32_16x16x32_bf16 v[116:119], v[128:131], v[172:175], v[116:119]
	v_mfma_f32_16x16x32_bf16 v[112:115], v[146:149], v[172:175], v[112:115]
	v_mfma_f32_16x16x32_bf16 v[92:95], v[128:131], v[180:183], v[92:95]
	v_mfma_f32_16x16x32_bf16 v[88:91], v[146:149], v[180:183], v[88:91]
	v_mfma_f32_16x16x32_bf16 v[76:79], v[128:131], v[188:191], v[76:79]
	v_mfma_f32_16x16x32_bf16 v[72:75], v[146:149], v[188:191], v[72:75]
	v_mfma_f32_16x16x32_bf16 v[124:127], v[132:135], v[168:171], v[124:127]
	v_mfma_f32_16x16x32_bf16 v[120:123], v[150:153], v[168:171], v[120:123]
	v_mfma_f32_16x16x32_bf16 v[116:119], v[132:135], v[176:179], v[116:119]
	v_mfma_f32_16x16x32_bf16 v[112:115], v[150:153], v[176:179], v[112:115]
	v_mfma_f32_16x16x32_bf16 v[92:95], v[132:135], v[184:187], v[92:95]
	v_mfma_f32_16x16x32_bf16 v[88:91], v[150:153], v[184:187], v[88:91]
	v_mfma_f32_16x16x32_bf16 v[76:79], v[132:135], v[192:195], v[76:79]
	v_mfma_f32_16x16x32_bf16 v[72:75], v[150:153], v[192:195], v[72:75]
	v_mfma_f32_16x16x32_bf16 v[108:111], v[196:199], v[154:157], v[108:111]
	v_mfma_f32_16x16x32_bf16 v[104:107], v[204:207], v[154:157], v[104:107]
	v_mfma_f32_16x16x32_bf16 v[100:103], v[196:199], v[172:175], v[100:103]
	v_mfma_f32_16x16x32_bf16 v[96:99], v[204:207], v[172:175], v[96:99]
	v_mfma_f32_16x16x32_bf16 v[84:87], v[196:199], v[180:183], v[84:87]
	v_mfma_f32_16x16x32_bf16 v[80:83], v[204:207], v[180:183], v[80:83]
	v_mfma_f32_16x16x32_bf16 v[68:71], v[196:199], v[188:191], v[68:71]
	v_mfma_f32_16x16x32_bf16 v[64:67], v[204:207], v[188:191], v[64:67]
	v_mfma_f32_16x16x32_bf16 v[108:111], v[200:203], v[168:171], v[108:111]
	v_mfma_f32_16x16x32_bf16 v[104:107], v[208:211], v[168:171], v[104:107]
	v_mfma_f32_16x16x32_bf16 v[100:103], v[200:203], v[176:179], v[100:103]
	v_mfma_f32_16x16x32_bf16 v[96:99], v[208:211], v[176:179], v[96:99]
	v_mfma_f32_16x16x32_bf16 v[84:87], v[200:203], v[184:187], v[84:87]
	v_mfma_f32_16x16x32_bf16 v[80:83], v[208:211], v[184:187], v[80:83]
	v_mfma_f32_16x16x32_bf16 v[68:71], v[200:203], v[192:195], v[68:71]
	v_mfma_f32_16x16x32_bf16 v[64:67], v[208:211], v[192:195], v[64:67]
	s_setprio 0
	s_barrier
	ds_read_b128 v[154:157], v163 offset:16384
	ds_read_b128 v[168:171], v163 offset:17408
	ds_read_b128 v[172:175], v163 offset:18432
	ds_read_b128 v[176:179], v163 offset:19456
	ds_read_b128 v[180:183], v163 offset:20480
	ds_read_b128 v[184:187], v163 offset:21504
	ds_read_b128 v[188:191], v163 offset:22528
	ds_read_b128 v[192:195], v163 offset:23552
	s_mov_b32 m0, s33
	v_lshl_add_u64 v[158:159], s[18:19], 0, v[138:139]
	global_load_lds_dwordx4 v[158:159], off
	v_lshl_add_u64 v[212:213], s[18:19], 0, v[136:137]
	s_mov_b32 m0, s34
	s_nop 0
	global_load_lds_dwordx4 v[212:213], off
	s_mov_b32 m0, s35
	v_lshl_add_u64 v[214:215], s[22:23], 0, v[138:139]
	global_load_lds_dwordx4 v[214:215], off
	v_lshl_add_u64 v[216:217], s[22:23], 0, v[136:137]
	s_mov_b32 m0, s36
	s_nop 0
	global_load_lds_dwordx4 v[216:217], off
	s_add_u32 s56, s18, 0xb0000
	s_addc_u32 s57, s19, 0
	s_mov_b32 m0, s37
	v_lshl_add_u64 v[248:249], s[56:57], 0, v[138:139]
	global_load_lds_dwordx4 v[248:249], off
	v_lshl_add_u64 v[248:249], s[56:57], 0, v[136:137]
	s_mov_b32 m0, s38
	s_nop 0
	global_load_lds_dwordx4 v[248:249], off
	s_waitcnt lgkmcnt(0)
	s_waitcnt vmcnt(8)
	s_barrier
	s_setprio 1
	v_mfma_f32_16x16x32_bf16 v[60:63], v[128:131], v[154:157], v[60:63]
	v_mfma_f32_16x16x32_bf16 v[56:59], v[146:149], v[154:157], v[56:59]
	v_mfma_f32_16x16x32_bf16 v[44:47], v[128:131], v[172:175], v[44:47]
	v_mfma_f32_16x16x32_bf16 v[40:43], v[146:149], v[172:175], v[40:43]
	v_mfma_f32_16x16x32_bf16 v[28:31], v[128:131], v[180:183], v[28:31]
	v_mfma_f32_16x16x32_bf16 v[24:27], v[146:149], v[180:183], v[24:27]
	v_mfma_f32_16x16x32_bf16 v[12:15], v[128:131], v[188:191], v[12:15]
	v_mfma_f32_16x16x32_bf16 v[8:11], v[146:149], v[188:191], v[8:11]
	v_mfma_f32_16x16x32_bf16 v[60:63], v[132:135], v[168:171], v[60:63]
	v_mfma_f32_16x16x32_bf16 v[56:59], v[150:153], v[168:171], v[56:59]
	v_mfma_f32_16x16x32_bf16 v[44:47], v[132:135], v[176:179], v[44:47]
	v_mfma_f32_16x16x32_bf16 v[40:43], v[150:153], v[176:179], v[40:43]
	v_mfma_f32_16x16x32_bf16 v[28:31], v[132:135], v[184:187], v[28:31]
	v_mfma_f32_16x16x32_bf16 v[24:27], v[150:153], v[184:187], v[24:27]
	v_mfma_f32_16x16x32_bf16 v[12:15], v[132:135], v[192:195], v[12:15]
	v_mfma_f32_16x16x32_bf16 v[8:11], v[150:153], v[192:195], v[8:11]
	v_mfma_f32_16x16x32_bf16 v[52:55], v[196:199], v[154:157], v[52:55]
	v_mfma_f32_16x16x32_bf16 v[48:51], v[204:207], v[154:157], v[48:51]
	v_mfma_f32_16x16x32_bf16 v[36:39], v[196:199], v[172:175], v[36:39]
	v_mfma_f32_16x16x32_bf16 v[32:35], v[204:207], v[172:175], v[32:35]
	v_mfma_f32_16x16x32_bf16 v[20:23], v[196:199], v[180:183], v[20:23]
	v_mfma_f32_16x16x32_bf16 v[16:19], v[204:207], v[180:183], v[16:19]
	v_mfma_f32_16x16x32_bf16 v[4:7], v[196:199], v[188:191], v[4:7]
	v_mfma_f32_16x16x32_bf16 v[0:3], v[204:207], v[188:191], v[0:3]
	v_mfma_f32_16x16x32_bf16 v[52:55], v[200:203], v[168:171], v[52:55]
	v_mfma_f32_16x16x32_bf16 v[48:51], v[208:211], v[168:171], v[48:51]
	v_mfma_f32_16x16x32_bf16 v[36:39], v[200:203], v[176:179], v[36:39]
	v_mfma_f32_16x16x32_bf16 v[32:35], v[208:211], v[176:179], v[32:35]
	v_mfma_f32_16x16x32_bf16 v[20:23], v[200:203], v[184:187], v[20:23]
	v_mfma_f32_16x16x32_bf16 v[16:19], v[208:211], v[184:187], v[16:19]
	v_mfma_f32_16x16x32_bf16 v[4:7], v[200:203], v[192:195], v[4:7]
	v_mfma_f32_16x16x32_bf16 v[0:3], v[208:211], v[192:195], v[0:3]
	s_setprio 0
	s_barrier
	ds_read_b128 v[128:131], v165
	ds_read_b128 v[132:135], v165 offset:1024
	ds_read_b128 v[146:149], v165 offset:2048
	ds_read_b128 v[150:153], v165 offset:3072
	s_add_u32 s22, s22, 0xb0000
	s_addc_u32 s23, s23, 0
	s_mov_b32 m0, s39
	v_lshl_add_u64 v[196:197], s[22:23], 0, v[138:139]
	ds_read_b128 v[154:157], v163 offset:32768
	ds_read_b128 v[168:171], v163 offset:33792
	ds_read_b128 v[172:175], v163 offset:34816
	ds_read_b128 v[176:179], v163 offset:35840
	ds_read_b128 v[180:183], v163 offset:36864
	ds_read_b128 v[184:187], v163 offset:37888
	ds_read_b128 v[188:191], v163 offset:38912
	ds_read_b128 v[192:195], v163 offset:39936
	global_load_lds_dwordx4 v[196:197], off
	v_lshl_add_u64 v[196:197], s[22:23], 0, v[136:137]
	s_mov_b32 m0, s40
	s_nop 0
	global_load_lds_dwordx4 v[196:197], off
	ds_read_b128 v[196:199], v166
	ds_read_b128 v[200:203], v166 offset:1024
	ds_read_b128 v[204:207], v166 offset:2048
	ds_read_b128 v[208:211], v166 offset:3072
	s_waitcnt lgkmcnt(0)
	s_waitcnt vmcnt(8)
	s_barrier
	s_setprio 1
	v_mfma_f32_16x16x32_bf16 v[124:127], v[128:131], v[154:157], v[124:127]
	v_mfma_f32_16x16x32_bf16 v[120:123], v[146:149], v[154:157], v[120:123]
	v_mfma_f32_16x16x32_bf16 v[116:119], v[128:131], v[172:175], v[116:119]
	v_mfma_f32_16x16x32_bf16 v[112:115], v[146:149], v[172:175], v[112:115]
	v_mfma_f32_16x16x32_bf16 v[92:95], v[128:131], v[180:183], v[92:95]
	v_mfma_f32_16x16x32_bf16 v[88:91], v[146:149], v[180:183], v[88:91]
	v_mfma_f32_16x16x32_bf16 v[76:79], v[128:131], v[188:191], v[76:79]
	v_mfma_f32_16x16x32_bf16 v[72:75], v[146:149], v[188:191], v[72:75]
	v_mfma_f32_16x16x32_bf16 v[124:127], v[132:135], v[168:171], v[124:127]
	v_mfma_f32_16x16x32_bf16 v[120:123], v[150:153], v[168:171], v[120:123]
	v_mfma_f32_16x16x32_bf16 v[116:119], v[132:135], v[176:179], v[116:119]
	v_mfma_f32_16x16x32_bf16 v[112:115], v[150:153], v[176:179], v[112:115]
	v_mfma_f32_16x16x32_bf16 v[92:95], v[132:135], v[184:187], v[92:95]
	v_mfma_f32_16x16x32_bf16 v[88:91], v[150:153], v[184:187], v[88:91]
	v_mfma_f32_16x16x32_bf16 v[76:79], v[132:135], v[192:195], v[76:79]
	v_mfma_f32_16x16x32_bf16 v[72:75], v[150:153], v[192:195], v[72:75]
	v_mfma_f32_16x16x32_bf16 v[108:111], v[196:199], v[154:157], v[108:111]
	v_mfma_f32_16x16x32_bf16 v[104:107], v[204:207], v[154:157], v[104:107]
	v_mfma_f32_16x16x32_bf16 v[100:103], v[196:199], v[172:175], v[100:103]
	v_mfma_f32_16x16x32_bf16 v[96:99], v[204:207], v[172:175], v[96:99]
	v_mfma_f32_16x16x32_bf16 v[84:87], v[196:199], v[180:183], v[84:87]
	v_mfma_f32_16x16x32_bf16 v[80:83], v[204:207], v[180:183], v[80:83]
	v_mfma_f32_16x16x32_bf16 v[68:71], v[196:199], v[188:191], v[68:71]
	v_mfma_f32_16x16x32_bf16 v[64:67], v[204:207], v[188:191], v[64:67]
	v_mfma_f32_16x16x32_bf16 v[108:111], v[200:203], v[168:171], v[108:111]
	v_mfma_f32_16x16x32_bf16 v[104:107], v[208:211], v[168:171], v[104:107]
	v_mfma_f32_16x16x32_bf16 v[100:103], v[200:203], v[176:179], v[100:103]
	v_mfma_f32_16x16x32_bf16 v[96:99], v[208:211], v[176:179], v[96:99]
	v_mfma_f32_16x16x32_bf16 v[84:87], v[200:203], v[184:187], v[84:87]
	v_mfma_f32_16x16x32_bf16 v[80:83], v[208:211], v[184:187], v[80:83]
	v_mfma_f32_16x16x32_bf16 v[68:71], v[200:203], v[192:195], v[68:71]
	v_mfma_f32_16x16x32_bf16 v[64:67], v[208:211], v[192:195], v[64:67]
	s_setprio 0
	s_barrier
	ds_read_b128 v[154:157], v163 offset:49152
	ds_read_b128 v[168:171], v163 offset:50176
	ds_read_b128 v[172:175], v163 offset:51200
	ds_read_b128 v[176:179], v163 offset:52224
	ds_read_b128 v[180:183], v163 offset:53248
	ds_read_b128 v[184:187], v163 offset:54272
	ds_read_b128 v[188:191], v163 offset:55296
	ds_read_b128 v[192:195], v163 offset:56320
	s_mov_b32 m0, s41
	v_lshl_add_u64 v[158:159], v[158:159], 0, s[8:9]
	global_load_lds_dwordx4 v[158:159], off
	v_lshl_add_u64 v[158:159], v[212:213], 0, s[8:9]
	s_mov_b32 m0, s42
	s_nop 0
	global_load_lds_dwordx4 v[158:159], off
	s_mov_b32 m0, s43
	v_lshl_add_u64 v[158:159], v[214:215], 0, s[8:9]
	global_load_lds_dwordx4 v[158:159], off
	v_lshl_add_u64 v[158:159], v[216:217], 0, s[8:9]
	s_mov_b32 m0, s44
	s_nop 0
	global_load_lds_dwordx4 v[158:159], off
	s_add_u32 s18, s18, 0xb0080
	s_addc_u32 s19, s19, 0
	s_mov_b32 m0, s45
	v_lshl_add_u64 v[248:249], s[18:19], 0, v[138:139]
	global_load_lds_dwordx4 v[248:249], off
	v_lshl_add_u64 v[248:249], s[18:19], 0, v[136:137]
	s_mov_b32 m0, s46
	s_nop 0
	global_load_lds_dwordx4 v[248:249], off
	s_waitcnt lgkmcnt(0)
	s_waitcnt vmcnt(8)
	s_barrier
	s_setprio 1
	v_mfma_f32_16x16x32_bf16 v[60:63], v[128:131], v[154:157], v[60:63]
	v_mfma_f32_16x16x32_bf16 v[56:59], v[146:149], v[154:157], v[56:59]
	v_mfma_f32_16x16x32_bf16 v[44:47], v[128:131], v[172:175], v[44:47]
	v_mfma_f32_16x16x32_bf16 v[40:43], v[146:149], v[172:175], v[40:43]
	v_mfma_f32_16x16x32_bf16 v[28:31], v[128:131], v[180:183], v[28:31]
	v_mfma_f32_16x16x32_bf16 v[24:27], v[146:149], v[180:183], v[24:27]
	v_mfma_f32_16x16x32_bf16 v[12:15], v[128:131], v[188:191], v[12:15]
	v_mfma_f32_16x16x32_bf16 v[8:11], v[146:149], v[188:191], v[8:11]
	v_mfma_f32_16x16x32_bf16 v[60:63], v[132:135], v[168:171], v[60:63]
	v_mfma_f32_16x16x32_bf16 v[56:59], v[150:153], v[168:171], v[56:59]
	v_mfma_f32_16x16x32_bf16 v[44:47], v[132:135], v[176:179], v[44:47]
	v_mfma_f32_16x16x32_bf16 v[40:43], v[150:153], v[176:179], v[40:43]
	v_mfma_f32_16x16x32_bf16 v[28:31], v[132:135], v[184:187], v[28:31]
	v_mfma_f32_16x16x32_bf16 v[24:27], v[150:153], v[184:187], v[24:27]
	v_mfma_f32_16x16x32_bf16 v[12:15], v[132:135], v[192:195], v[12:15]
	v_mfma_f32_16x16x32_bf16 v[8:11], v[150:153], v[192:195], v[8:11]
	v_mfma_f32_16x16x32_bf16 v[52:55], v[196:199], v[154:157], v[52:55]
	v_mfma_f32_16x16x32_bf16 v[48:51], v[204:207], v[154:157], v[48:51]
	v_mfma_f32_16x16x32_bf16 v[36:39], v[196:199], v[172:175], v[36:39]
	v_mfma_f32_16x16x32_bf16 v[32:35], v[204:207], v[172:175], v[32:35]
	v_mfma_f32_16x16x32_bf16 v[20:23], v[196:199], v[180:183], v[20:23]
	v_mfma_f32_16x16x32_bf16 v[16:19], v[204:207], v[180:183], v[16:19]
	v_mfma_f32_16x16x32_bf16 v[4:7], v[196:199], v[188:191], v[4:7]
	v_mfma_f32_16x16x32_bf16 v[0:3], v[204:207], v[188:191], v[0:3]
	v_mfma_f32_16x16x32_bf16 v[52:55], v[200:203], v[168:171], v[52:55]
	v_mfma_f32_16x16x32_bf16 v[48:51], v[208:211], v[168:171], v[48:51]
	v_mfma_f32_16x16x32_bf16 v[36:39], v[200:203], v[176:179], v[36:39]
	v_mfma_f32_16x16x32_bf16 v[32:35], v[208:211], v[176:179], v[32:35]
	v_mfma_f32_16x16x32_bf16 v[20:23], v[200:203], v[184:187], v[20:23]
	v_mfma_f32_16x16x32_bf16 v[16:19], v[208:211], v[184:187], v[16:19]
	v_mfma_f32_16x16x32_bf16 v[4:7], v[200:203], v[192:195], v[4:7]
	v_mfma_f32_16x16x32_bf16 v[0:3], v[208:211], v[192:195], v[0:3]
	s_setprio 0
	s_add_i32 s54, s54, 2
	s_add_u32 s16, s16, 0x100
	s_addc_u32 s17, s17, 0
	s_add_u32 s52, s52, 0x100
	s_addc_u32 s53, s53, 0
	s_cmp_gt_u32 s54, 41
	s_barrier
	s_cbranch_scc0 .LBB0_1336
	v_lshl_or_b32 v128, s51, 8, v161
	v_lshl_add_u32 v156, s50, 8, v160
	v_ashrrev_i32_e32 v129, 31, v128
	v_lshlrev_b64 v[154:155], 1, v[128:129]
	v_ashrrev_i32_e32 v157, 31, v156
	v_lshl_add_u64 v[130:131], s[6:7], 0, v[154:155]
	v_lshlrev_b64 v[132:133], 11, v[156:157]
	v_or_b32_e32 v200, 16, v156
	v_lshl_add_u64 v[132:133], v[130:131], 0, v[132:133]
	v_ashrrev_i32_e32 v201, 31, v200
	global_load_dwordx4 v[168:171], v[132:133], off
	global_load_dwordx4 v[172:175], v[132:133], off offset:64
	v_lshlrev_b64 v[132:133], 11, v[200:201]
	v_lshl_add_u64 v[132:133], v[130:131], 0, v[132:133]
	global_load_dwordx4 v[176:179], v[132:133], off
	global_load_dwordx4 v[180:183], v[132:133], off offset:64
	v_or_b32_e32 v158, 32, v156
	v_ashrrev_i32_e32 v159, 31, v158
	v_lshlrev_b64 v[146:147], 2, v[128:129]
	v_lshlrev_b64 v[128:129], 11, v[158:159]
	v_lshl_add_u64 v[128:129], v[130:131], 0, v[128:129]
	global_load_dwordx4 v[184:187], v[128:129], off
	v_or_b32_e32 v152, 48, v156
	v_add_u32_e32 v148, 0x80, v156
	v_add_u32_e32 v150, 0x90, v156
	v_readlane_b32 s16, v246, 62
	v_ashrrev_i32_e32 v153, 31, v152
	v_ashrrev_i32_e32 v149, 31, v148
	v_lshlrev_b64 v[132:133], 12, v[156:157]
	v_ashrrev_i32_e32 v151, 31, v150
	v_readlane_b32 s17, v246, 63
	v_lshlrev_b64 v[134:135], 11, v[152:153]
	v_lshlrev_b64 v[188:189], 11, v[148:149]
	v_lshl_add_u64 v[132:133], s[16:17], 0, v[132:133]
	v_lshlrev_b64 v[190:191], 11, v[150:151]
	v_lshl_add_u64 v[130:131], v[130:131], 0, v[134:135]
	v_lshl_add_u64 v[134:135], s[6:7], 0, v[188:189]
	v_lshl_add_u64 v[202:203], v[132:133], 0, v[146:147]
	v_lshl_add_u64 v[132:133], s[6:7], 0, v[190:191]
	global_load_dwordx4 v[188:191], v[128:129], off offset:64
	global_load_dwordx4 v[192:195], v[130:131], off
	global_load_dwordx4 v[196:199], v[130:131], off offset:64
	v_lshl_add_u64 v[128:129], v[134:135], 0, v[154:155]
	v_lshl_add_u64 v[204:205], v[132:133], 0, v[154:155]
	global_load_dwordx4 v[132:135], v[128:129], off
	s_nop 0
	global_load_dwordx4 v[128:131], v[128:129], off offset:64
	v_readlane_b32 s18, v245, 0
	v_readlane_b32 s19, v245, 1
	s_and_b64 vcc, exec, s[14:15]
	s_mov_b32 s51, s48
	s_mov_b32 s50, s49
	s_mov_b64 s[18:19], s[12:13]
	s_waitcnt vmcnt(0)
	v_lshlrev_b32_e32 v206, 16, v168
	v_and_b32_e32 v207, 0xffff0000, v168
	v_lshlrev_b32_e32 v168, 16, v169
	v_and_b32_e32 v169, 0xffff0000, v169
	v_lshlrev_b32_e32 v208, 16, v170
	v_and_b32_e32 v209, 0xffff0000, v170
	v_lshlrev_b32_e32 v170, 16, v171
	v_and_b32_e32 v171, 0xffff0000, v171
	v_lshlrev_b32_e32 v210, 16, v172
	v_and_b32_e32 v211, 0xffff0000, v172
	v_lshlrev_b32_e32 v172, 16, v173
	v_and_b32_e32 v173, 0xffff0000, v173
	v_lshlrev_b32_e32 v212, 16, v174
	v_and_b32_e32 v213, 0xffff0000, v174
	v_lshlrev_b32_e32 v174, 16, v175
	v_and_b32_e32 v175, 0xffff0000, v175
	v_pk_add_f32 v[126:127], v[126:127], v[168:169]
	v_pk_add_f32 v[124:125], v[124:125], v[206:207]
	v_pk_add_f32 v[120:121], v[120:121], v[208:209]
	v_pk_add_f32 v[122:123], v[122:123], v[170:171]
	v_pk_add_f32 v[110:111], v[110:111], v[172:173]
	v_pk_add_f32 v[108:109], v[108:109], v[210:211]
	v_pk_add_f32 v[106:107], v[106:107], v[174:175]
	v_pk_add_f32 v[104:105], v[104:105], v[212:213]
	global_store_dwordx4 v[202:203], v[124:127], off nt
	global_store_dwordx4 v[202:203], v[120:123], off offset:16 nt
	global_store_dwordx4 v[202:203], v[108:111], off offset:128 nt
	global_store_dwordx4 v[202:203], v[104:107], off offset:144 nt
	v_lshlrev_b32_e32 v120, 16, v182
	v_and_b32_e32 v121, 0xffff0000, v182
	v_pk_add_f32 v[96:97], v[96:97], v[120:121]
	v_lshlrev_b64 v[120:121], 12, v[200:201]
	v_lshlrev_b32_e32 v214, 16, v176
	v_and_b32_e32 v215, 0xffff0000, v176
	v_lshlrev_b32_e32 v176, 16, v177
	v_and_b32_e32 v177, 0xffff0000, v177
	v_lshlrev_b32_e32 v216, 16, v178
	v_and_b32_e32 v217, 0xffff0000, v178
	v_lshlrev_b32_e32 v178, 16, v179
	v_and_b32_e32 v179, 0xffff0000, v179
	global_load_dwordx4 v[108:111], v[204:205], off
	global_load_dwordx4 v[104:107], v[204:205], off offset:64
	v_lshl_add_u64 v[120:121], s[16:17], 0, v[120:121]
	v_lshlrev_b32_e32 v218, 16, v180
	v_and_b32_e32 v219, 0xffff0000, v180
	v_lshlrev_b32_e32 v180, 16, v181
	v_pk_add_f32 v[118:119], v[118:119], v[176:177]
	v_pk_add_f32 v[116:117], v[116:117], v[214:215]
	v_pk_add_f32 v[114:115], v[114:115], v[178:179]
	v_pk_add_f32 v[112:113], v[112:113], v[216:217]
	v_and_b32_e32 v181, 0xffff0000, v181
	v_lshlrev_b32_e32 v122, 16, v183
	v_and_b32_e32 v123, 0xffff0000, v183
	v_lshl_add_u64 v[120:121], v[120:121], 0, v[146:147]
	v_pk_add_f32 v[102:103], v[102:103], v[180:181]
	v_pk_add_f32 v[100:101], v[100:101], v[218:219]
	v_pk_add_f32 v[98:99], v[98:99], v[122:123]
	global_store_dwordx4 v[120:121], v[116:119], off nt
	global_store_dwordx4 v[120:121], v[112:115], off offset:16 nt
	global_store_dwordx4 v[120:121], v[100:103], off offset:128 nt
	global_store_dwordx4 v[120:121], v[96:99], off offset:144 nt
	v_add_u32_e32 v112, 0xa0, v156
	v_lshlrev_b32_e32 v114, 16, v184
	v_and_b32_e32 v115, 0xffff0000, v184
	v_ashrrev_i32_e32 v113, 31, v112
	v_pk_add_f32 v[92:93], v[92:93], v[114:115]
	v_lshlrev_b32_e32 v114, 16, v186
	v_and_b32_e32 v115, 0xffff0000, v186
	v_lshlrev_b64 v[96:97], 11, v[112:113]
	v_pk_add_f32 v[88:89], v[88:89], v[114:115]
	v_lshlrev_b32_e32 v114, 16, v188
	v_and_b32_e32 v115, 0xffff0000, v188
	v_lshl_add_u64 v[96:97], s[6:7], 0, v[96:97]
	v_lshlrev_b32_e32 v116, 16, v185
	v_and_b32_e32 v117, 0xffff0000, v185
	v_pk_add_f32 v[84:85], v[84:85], v[114:115]
	v_lshlrev_b32_e32 v114, 16, v190
	v_and_b32_e32 v115, 0xffff0000, v190
	v_lshl_add_u64 v[96:97], v[96:97], 0, v[154:155]
	v_pk_add_f32 v[94:95], v[94:95], v[116:117]
	v_lshlrev_b32_e32 v116, 16, v187
	v_and_b32_e32 v117, 0xffff0000, v187
	v_pk_add_f32 v[80:81], v[80:81], v[114:115]
	v_lshlrev_b64 v[114:115], 12, v[158:159]
	global_load_dwordx4 v[100:103], v[96:97], off
	s_nop 0
	global_load_dwordx4 v[96:99], v[96:97], off offset:64
	v_pk_add_f32 v[90:91], v[90:91], v[116:117]
	v_lshlrev_b32_e32 v116, 16, v189
	v_and_b32_e32 v117, 0xffff0000, v189
	v_lshl_add_u64 v[114:115], s[16:17], 0, v[114:115]
	v_pk_add_f32 v[86:87], v[86:87], v[116:117]
	v_lshlrev_b32_e32 v116, 16, v191
	v_and_b32_e32 v117, 0xffff0000, v191
	v_lshl_add_u64 v[114:115], v[114:115], 0, v[146:147]
	v_pk_add_f32 v[82:83], v[82:83], v[116:117]
	global_store_dwordx4 v[114:115], v[92:95], off nt
	global_store_dwordx4 v[114:115], v[88:91], off offset:16 nt
	global_store_dwordx4 v[114:115], v[84:87], off offset:128 nt
	global_store_dwordx4 v[114:115], v[80:83], off offset:144 nt
	v_add_u32_e32 v88, 0xb0, v156
	v_ashrrev_i32_e32 v89, 31, v88
	v_lshlrev_b64 v[80:81], 11, v[88:89]
	v_lshl_add_u64 v[80:81], s[6:7], 0, v[80:81]
	v_lshl_add_u64 v[80:81], v[80:81], 0, v[154:155]
	global_load_dwordx4 v[84:87], v[80:81], off
	s_nop 0
	global_load_dwordx4 v[80:83], v[80:81], off offset:64
	v_lshlrev_b32_e32 v90, 16, v192
	v_and_b32_e32 v91, 0xffff0000, v192
	v_pk_add_f32 v[76:77], v[76:77], v[90:91]
	v_lshlrev_b32_e32 v90, 16, v194
	v_and_b32_e32 v91, 0xffff0000, v194
	v_pk_add_f32 v[72:73], v[72:73], v[90:91]
	v_lshlrev_b32_e32 v90, 16, v196
	v_and_b32_e32 v91, 0xffff0000, v196
	v_lshlrev_b32_e32 v92, 16, v193
	v_and_b32_e32 v93, 0xffff0000, v193
	v_pk_add_f32 v[68:69], v[68:69], v[90:91]
	v_lshlrev_b32_e32 v90, 16, v198
	v_and_b32_e32 v91, 0xffff0000, v198
	v_pk_add_f32 v[78:79], v[78:79], v[92:93]
	v_lshlrev_b32_e32 v92, 16, v195
	v_and_b32_e32 v93, 0xffff0000, v195
	v_pk_add_f32 v[64:65], v[64:65], v[90:91]
	v_lshlrev_b64 v[90:91], 12, v[152:153]
	v_pk_add_f32 v[74:75], v[74:75], v[92:93]
	v_lshlrev_b32_e32 v92, 16, v197
	v_and_b32_e32 v93, 0xffff0000, v197
	v_lshl_add_u64 v[90:91], s[16:17], 0, v[90:91]
	v_pk_add_f32 v[70:71], v[70:71], v[92:93]
	v_lshlrev_b32_e32 v92, 16, v199
	v_and_b32_e32 v93, 0xffff0000, v199
	v_lshl_add_u64 v[90:91], v[90:91], 0, v[146:147]
	v_pk_add_f32 v[66:67], v[66:67], v[92:93]
	global_store_dwordx4 v[90:91], v[76:79], off nt
	global_store_dwordx4 v[90:91], v[72:75], off offset:16 nt
	global_store_dwordx4 v[90:91], v[68:71], off offset:128 nt
	global_store_dwordx4 v[90:91], v[64:67], off offset:144 nt
	s_nop 1
	v_lshlrev_b32_e32 v64, 16, v132
	v_and_b32_e32 v65, 0xffff0000, v132
	v_pk_add_f32 v[60:61], v[60:61], v[64:65]
	v_lshlrev_b32_e32 v64, 16, v134
	v_and_b32_e32 v65, 0xffff0000, v134
	v_pk_add_f32 v[56:57], v[56:57], v[64:65]
	v_lshlrev_b32_e32 v64, 16, v128
	v_and_b32_e32 v65, 0xffff0000, v128
	v_lshlrev_b32_e32 v66, 16, v133
	v_and_b32_e32 v67, 0xffff0000, v133
	v_pk_add_f32 v[52:53], v[52:53], v[64:65]
	v_lshlrev_b32_e32 v64, 16, v130
	v_and_b32_e32 v65, 0xffff0000, v130
	v_pk_add_f32 v[62:63], v[62:63], v[66:67]
	v_lshlrev_b32_e32 v66, 16, v135
	v_and_b32_e32 v67, 0xffff0000, v135
	v_pk_add_f32 v[48:49], v[48:49], v[64:65]
	v_lshlrev_b64 v[64:65], 12, v[148:149]
	v_pk_add_f32 v[58:59], v[58:59], v[66:67]
	v_lshlrev_b32_e32 v66, 16, v129
	v_and_b32_e32 v67, 0xffff0000, v129
	v_lshl_add_u64 v[64:65], s[16:17], 0, v[64:65]
	v_pk_add_f32 v[54:55], v[54:55], v[66:67]
	v_lshlrev_b32_e32 v66, 16, v131
	v_and_b32_e32 v67, 0xffff0000, v131
	v_lshl_add_u64 v[64:65], v[64:65], 0, v[146:147]
	v_pk_add_f32 v[50:51], v[50:51], v[66:67]
	global_store_dwordx4 v[64:65], v[60:63], off nt
	global_store_dwordx4 v[64:65], v[56:59], off offset:16 nt
	global_store_dwordx4 v[64:65], v[52:55], off offset:128 nt
	global_store_dwordx4 v[64:65], v[48:51], off offset:144 nt
	s_waitcnt vmcnt(0)
	s_nop 0
	v_lshlrev_b32_e32 v48, 16, v108
	v_and_b32_e32 v49, 0xffff0000, v108
	v_pk_add_f32 v[44:45], v[44:45], v[48:49]
	v_lshlrev_b32_e32 v48, 16, v110
	v_and_b32_e32 v49, 0xffff0000, v110
	v_pk_add_f32 v[40:41], v[40:41], v[48:49]
	v_lshlrev_b32_e32 v48, 16, v104
	v_and_b32_e32 v49, 0xffff0000, v104
	v_lshlrev_b32_e32 v50, 16, v109
	v_and_b32_e32 v51, 0xffff0000, v109
	v_pk_add_f32 v[36:37], v[36:37], v[48:49]
	v_lshlrev_b32_e32 v48, 16, v106
	v_and_b32_e32 v49, 0xffff0000, v106
	v_pk_add_f32 v[46:47], v[46:47], v[50:51]
	v_lshlrev_b32_e32 v50, 16, v111
	v_and_b32_e32 v51, 0xffff0000, v111
	v_pk_add_f32 v[32:33], v[32:33], v[48:49]
	v_lshlrev_b64 v[48:49], 12, v[150:151]
	v_pk_add_f32 v[42:43], v[42:43], v[50:51]
	v_lshlrev_b32_e32 v50, 16, v105
	v_and_b32_e32 v51, 0xffff0000, v105
	v_lshl_add_u64 v[48:49], s[16:17], 0, v[48:49]
	v_pk_add_f32 v[38:39], v[38:39], v[50:51]
	v_lshlrev_b32_e32 v50, 16, v107
	v_and_b32_e32 v51, 0xffff0000, v107
	v_lshl_add_u64 v[48:49], v[48:49], 0, v[146:147]
	v_pk_add_f32 v[34:35], v[34:35], v[50:51]
	global_store_dwordx4 v[48:49], v[44:47], off nt
	global_store_dwordx4 v[48:49], v[40:43], off offset:16 nt
	global_store_dwordx4 v[48:49], v[36:39], off offset:128 nt
	global_store_dwordx4 v[48:49], v[32:35], off offset:144 nt
	s_nop 1
	v_lshlrev_b32_e32 v32, 16, v100
	v_and_b32_e32 v33, 0xffff0000, v100
	v_pk_add_f32 v[28:29], v[28:29], v[32:33]
	v_lshlrev_b32_e32 v32, 16, v102
	v_and_b32_e32 v33, 0xffff0000, v102
	v_pk_add_f32 v[24:25], v[24:25], v[32:33]
	v_lshlrev_b32_e32 v32, 16, v96
	v_and_b32_e32 v33, 0xffff0000, v96
	v_lshlrev_b32_e32 v34, 16, v101
	v_and_b32_e32 v35, 0xffff0000, v101
	v_pk_add_f32 v[20:21], v[20:21], v[32:33]
	v_lshlrev_b32_e32 v32, 16, v98
	v_and_b32_e32 v33, 0xffff0000, v98
	v_pk_add_f32 v[30:31], v[30:31], v[34:35]
	v_lshlrev_b32_e32 v34, 16, v103
	v_and_b32_e32 v35, 0xffff0000, v103
	v_pk_add_f32 v[16:17], v[16:17], v[32:33]
	v_lshlrev_b64 v[32:33], 12, v[112:113]
	v_pk_add_f32 v[26:27], v[26:27], v[34:35]
	v_lshlrev_b32_e32 v34, 16, v97
	v_and_b32_e32 v35, 0xffff0000, v97
	v_lshl_add_u64 v[32:33], s[16:17], 0, v[32:33]
	v_pk_add_f32 v[22:23], v[22:23], v[34:35]
	v_lshlrev_b32_e32 v34, 16, v99
	v_and_b32_e32 v35, 0xffff0000, v99
	v_lshl_add_u64 v[32:33], v[32:33], 0, v[146:147]
	v_pk_add_f32 v[18:19], v[18:19], v[34:35]
	global_store_dwordx4 v[32:33], v[28:31], off nt
	global_store_dwordx4 v[32:33], v[24:27], off offset:16 nt
	global_store_dwordx4 v[32:33], v[20:23], off offset:128 nt
	global_store_dwordx4 v[32:33], v[16:19], off offset:144 nt
	s_nop 1
	v_lshlrev_b32_e32 v16, 16, v84
	v_and_b32_e32 v17, 0xffff0000, v84
	v_pk_add_f32 v[12:13], v[12:13], v[16:17]
	v_lshlrev_b32_e32 v16, 16, v86
	v_and_b32_e32 v17, 0xffff0000, v86
	v_pk_add_f32 v[8:9], v[8:9], v[16:17]
	v_lshlrev_b32_e32 v16, 16, v80
	v_and_b32_e32 v17, 0xffff0000, v80
	v_lshlrev_b32_e32 v18, 16, v85
	v_and_b32_e32 v19, 0xffff0000, v85
	v_pk_add_f32 v[4:5], v[4:5], v[16:17]
	v_lshlrev_b32_e32 v16, 16, v82
	v_and_b32_e32 v17, 0xffff0000, v82
	v_pk_add_f32 v[14:15], v[14:15], v[18:19]
	v_lshlrev_b32_e32 v18, 16, v87
	v_and_b32_e32 v19, 0xffff0000, v87
	v_pk_add_f32 v[0:1], v[0:1], v[16:17]
	v_lshlrev_b64 v[16:17], 12, v[88:89]
	v_pk_add_f32 v[10:11], v[10:11], v[18:19]
	v_lshlrev_b32_e32 v18, 16, v81
	v_and_b32_e32 v19, 0xffff0000, v81
	v_lshl_add_u64 v[16:17], s[16:17], 0, v[16:17]
	v_pk_add_f32 v[6:7], v[6:7], v[18:19]
	v_lshlrev_b32_e32 v18, 16, v83
	v_and_b32_e32 v19, 0xffff0000, v83
	v_lshl_add_u64 v[16:17], v[16:17], 0, v[146:147]
	s_mov_b64 s[16:17], s[10:11]
	v_pk_add_f32 v[2:3], v[2:3], v[18:19]
	global_store_dwordx4 v[16:17], v[12:15], off nt
	global_store_dwordx4 v[16:17], v[8:11], off offset:16 nt
	global_store_dwordx4 v[16:17], v[4:7], off offset:128 nt
	global_store_dwordx4 v[16:17], v[0:3], off offset:144 nt
	s_cbranch_vccz .LBB0_1331
	s_branch .LBB0_1340

	.amdhsa_kernel _Z10fwd_kernel6Params
		.amdhsa_group_segment_fixed_size 147456
		.amdhsa_private_segment_fixed_size 0
		.amdhsa_kernarg_size 472
		.amdhsa_user_sgpr_count 2
		.amdhsa_user_sgpr_dispatch_ptr 0
		.amdhsa_user_sgpr_queue_ptr 0
		.amdhsa_user_sgpr_kernarg_segment_ptr 1
		.amdhsa_user_sgpr_dispatch_id 0
		.amdhsa_user_sgpr_kernarg_preload_length 0
		.amdhsa_user_sgpr_kernarg_preload_offset 0
		.amdhsa_user_sgpr_private_segment_size 0
		.amdhsa_uses_dynamic_stack 0
		.amdhsa_enable_private_segment 0
		.amdhsa_system_sgpr_workgroup_id_x 1
		.amdhsa_system_sgpr_workgroup_id_y 0
		.amdhsa_system_sgpr_workgroup_id_z 0
		.amdhsa_system_sgpr_workgroup_info 0
		.amdhsa_system_vgpr_workitem_id 2
		.amdhsa_next_free_vgpr 256
		.amdhsa_next_free_sgpr 98
		.amdhsa_accum_offset 256
		.amdhsa_reserve_vcc 1
		.amdhsa_float_round_mode_32 0
		.amdhsa_float_round_mode_16_64 0
		.amdhsa_float_denorm_mode_32 3
		.amdhsa_float_denorm_mode_16_64 3
		.amdhsa_dx10_clamp 1
		.amdhsa_ieee_mode 1
		.amdhsa_fp16_overflow 0
		.amdhsa_tg_split 0
		.amdhsa_exception_fp_ieee_invalid_op 0
		.amdhsa_exception_fp_denorm_src 0
		.amdhsa_exception_fp_ieee_div_zero 0
		.amdhsa_exception_fp_ieee_overflow 0
		.amdhsa_exception_fp_ieee_underflow 0
		.amdhsa_exception_fp_ieee_inexact 0
		.amdhsa_exception_int_div_zero 0
	.end_amdhsa_kernel

amdhsa.kernels:
  - .agpr_count:     0
    .args:
      - .offset:         0
        .size:           216
        .value_kind:     by_value
      - .offset:         216
        .size:           4
        .value_kind:     hidden_block_count_x
      - .offset:         220
        .size:           4
        .value_kind:     hidden_block_count_y
      - .offset:         224
        .size:           4
        .value_kind:     hidden_block_count_z
      - .offset:         228
        .size:           2
        .value_kind:     hidden_group_size_x
      - .offset:         230
        .size:           2
        .value_kind:     hidden_group_size_y
      - .offset:         232
        .size:           2
        .value_kind:     hidden_group_size_z
      - .offset:         234
        .size:           2
        .value_kind:     hidden_remainder_x
      - .offset:         236
        .size:           2
        .value_kind:     hidden_remainder_y
      - .offset:         238
        .size:           2
        .value_kind:     hidden_remainder_z
      - .offset:         256
        .size:           8
        .value_kind:     hidden_global_offset_x
      - .offset:         264
        .size:           8
        .value_kind:     hidden_global_offset_y
      - .offset:         272
        .size:           8
        .value_kind:     hidden_global_offset_z
      - .offset:         280
        .size:           2
        .value_kind:     hidden_grid_dims
      - .offset:         304
        .size:           8
        .value_kind:     hidden_multigrid_sync_arg
    .group_segment_fixed_size: 147456
    .kernarg_segment_align: 8
    .kernarg_segment_size: 472
    .language:       OpenCL C
    .language_version:
      - 2
      - 0
    .max_flat_workgroup_size: 512
    .name:           _Z10fwd_kernel6Params
    .private_segment_fixed_size: 0
    .sgpr_count:     104
    .sgpr_spill_count: 199
    .symbol:         _Z10fwd_kernel6Params.kd
    .uniform_work_group_size: 1
    .uses_dynamic_stack: false
    .vgpr_count:     256
    .vgpr_spill_count: 0
    .wavefront_size: 64
